# RWKV scan passes rewritten: f32 MFMA rank-2 state update on decay-scaled state, LDS-broadcast dot products; plus carry rewrite and qkv epilogue batching
# speedup vs baseline: 1.1107x; 1.1107x over previous
; DI bf16_t f2bf(float x) { unsigned u = __float_as_uint(x); u += 0x7fffu + ((u >> 16) & 1u); return (bf16_t)(u >> 16); }
; #define XT4_LOOP(NTN, BASE) \
;   for (int pos_ = first_item((BASE), (int)(blockIdx.x >> 3), (int)(gridDim.x >> 3)); pos_ < 16 * (NTN); pos_ += (int)(gridDim.x >> 3))
; DI void phase_gemm_qkv(const Params& p, bf16_t* sm) {
;     ...
;   XT4_LOOP(12, 0) {
;     int mt_, nt_; xt4_decode(pos_, 12, mt_, nt_);
;     const int row0 = mt_ * 256, n0 = nt_ * 128;
;     f32x16 acc[4][2]; zero_acc4(acc);
;     gemm_acc4(acc, p.h, 1024, row0, p.Wqkv, 1024, n0, 1024, sm);
; #pragma unroll
;     for (int mi = 0; mi < 4; mi++)
; #pragma unroll
;       for (int i = 0; i < 16; i++) {
;         const int row = EPI_ROW4(mi, i);
;         const int col = n0 + ewn * 64 + er;
;         float x1 = acc[mi][0][i], x2 = acc[mi][1][i];
;         if (n0 < 1024) {
;           int pos = row & (SEQ - 1);
;           float c = p.ropeC[pos * 32 + er], s = p.ropeS[pos * 32 + er];
;           float o1 = x1 * c - x2 * s, o2 = x2 * c + x1 * s;
;           if (n0 < 512) { o1 *= 0.125f; o2 *= 0.125f; }
;           x1 = o1; x2 = o2;
;         }
;         qkv[(size_t)row * 1536 + col] = f2bf(x1);
;         qkv[(size_t)row * 1536 + col + 32] = f2bf(x2);
;       }
;   }
.LBB0_193:
	s_add_i32 s14, s14, s12
	s_add_i32 s10, s10, s12
	s_cmpk_lt_u32 s14, 0xc0
	s_cbranch_scc0 .LBB0_330

; DI void phase_gemm_qkv(const Params& p, bf16_t* sm) {
;     ...
;         const int row = EPI_ROW4(mi, i);
;         const int col = n0 + ewn * 64 + er;
;         float x1 = acc[mi][0][i], x2 = acc[mi][1][i];
;         if (n0 < 1024) {
;           int pos = row & (SEQ - 1);
;           float c = p.ropeC[pos * 32 + er], s = p.ropeS[pos * 32 + er];
;           float o1 = x1 * c - x2 * s, o2 = x2 * c + x1 * s;
;           if (n0 < 512) { o1 *= 0.125f; o2 *= 0.125f; }
;           x1 = o1; x2 = o2;
.LBB0_202:
	v_or_b32_e32 v245, s2, v203
	v_or_b32_e32 v246, s15, v204
	v_readlane_b32 s8, v254, 44
	v_readlane_b32 s9, v254, 45
	v_mul_u32_u24_e32 v247, 0xc00, v246
	v_lshl_add_u32 v247, v245, 1, v247
	s_cmp_gt_i32 s3, 7
	s_cbranch_scc1 .Lqkv0_store
	s_cmp_lt_i32 s3, 4
	s_cselect_b32 s2, 0x3e000000, 1.0
	v_readlane_b32 s0, v254, 38
	v_readlane_b32 s1, v254, 39
	v_readlane_b32 s4, v254, 40
	v_readlane_b32 s5, v254, 41
	v_and_b32_e32 v244, 0x3fff, v246
	v_lshlrev_b32_e32 v244, 7, v244
	v_lshl_add_u32 v244, v202, 2, v244
	s_nop 4
	global_load_dword v128, v244, s[0:1] offset:0
	global_load_dword v144, v244, s[4:5] offset:0
	global_load_dword v129, v244, s[0:1] offset:128
	global_load_dword v145, v244, s[4:5] offset:128
	global_load_dword v130, v244, s[0:1] offset:256
	global_load_dword v146, v244, s[4:5] offset:256
	global_load_dword v131, v244, s[0:1] offset:384
	global_load_dword v147, v244, s[4:5] offset:384
	global_load_dword v132, v244, s[0:1] offset:1024
	global_load_dword v148, v244, s[4:5] offset:1024
	global_load_dword v133, v244, s[0:1] offset:1152
	global_load_dword v149, v244, s[4:5] offset:1152
	global_load_dword v134, v244, s[0:1] offset:1280
	global_load_dword v150, v244, s[4:5] offset:1280
	global_load_dword v135, v244, s[0:1] offset:1408
	global_load_dword v151, v244, s[4:5] offset:1408
	global_load_dword v136, v244, s[0:1] offset:2048
	global_load_dword v152, v244, s[4:5] offset:2048
	global_load_dword v137, v244, s[0:1] offset:2176
	global_load_dword v153, v244, s[4:5] offset:2176
	global_load_dword v138, v244, s[0:1] offset:2304
	global_load_dword v154, v244, s[4:5] offset:2304
	global_load_dword v139, v244, s[0:1] offset:2432
	global_load_dword v155, v244, s[4:5] offset:2432
	global_load_dword v140, v244, s[0:1] offset:3072
	global_load_dword v156, v244, s[4:5] offset:3072
	global_load_dword v141, v244, s[0:1] offset:3200
	global_load_dword v157, v244, s[4:5] offset:3200
	global_load_dword v142, v244, s[0:1] offset:3328
	global_load_dword v158, v244, s[4:5] offset:3328
	global_load_dword v143, v244, s[0:1] offset:3456
	global_load_dword v159, v244, s[4:5] offset:3456
	s_add_u32 s0, s0, 0x1000
	s_addc_u32 s1, s1, 0
	s_add_u32 s4, s4, 0x1000
	s_addc_u32 s5, s5, 0
	global_load_dword v160, v244, s[0:1] offset:0
	global_load_dword v190, v244, s[4:5] offset:0
	global_load_dword v161, v244, s[0:1] offset:128
	global_load_dword v191, v244, s[4:5] offset:128
	global_load_dword v162, v244, s[0:1] offset:256
	global_load_dword v192, v244, s[4:5] offset:256
	global_load_dword v163, v244, s[0:1] offset:384
	global_load_dword v193, v244, s[4:5] offset:384
	global_load_dword v164, v244, s[0:1] offset:1024
	global_load_dword v194, v244, s[4:5] offset:1024
	global_load_dword v165, v244, s[0:1] offset:1152
	global_load_dword v195, v244, s[4:5] offset:1152
	global_load_dword v166, v244, s[0:1] offset:1280
	global_load_dword v196, v244, s[4:5] offset:1280
	global_load_dword v167, v244, s[0:1] offset:1408
	global_load_dword v197, v244, s[4:5] offset:1408
	global_load_dword v168, v244, s[0:1] offset:2048
	global_load_dword v198, v244, s[4:5] offset:2048
	global_load_dword v169, v244, s[0:1] offset:2176
	global_load_dword v199, v244, s[4:5] offset:2176
	global_load_dword v170, v244, s[0:1] offset:2304
	global_load_dword v200, v244, s[4:5] offset:2304
	global_load_dword v171, v244, s[0:1] offset:2432
	global_load_dword v201, v244, s[4:5] offset:2432
	global_load_dword v172, v244, s[0:1] offset:3072
	global_load_dword v206, v244, s[4:5] offset:3072
	global_load_dword v173, v244, s[0:1] offset:3200
	global_load_dword v207, v244, s[4:5] offset:3200
	global_load_dword v174, v244, s[0:1] offset:3328
	global_load_dword v208, v244, s[4:5] offset:3328
	global_load_dword v175, v244, s[0:1] offset:3456
	global_load_dword v209, v244, s[4:5] offset:3456
	s_add_u32 s0, s0, 0x1000
	s_addc_u32 s1, s1, 0
	s_add_u32 s4, s4, 0x1000
	s_addc_u32 s5, s5, 0
	s_waitcnt vmcnt(32)
	v_mul_f32_e32 v128, s2, v128
	v_mul_f32_e32 v144, s2, v144
	v_mul_f32_e32 v248, v96, v144
	v_mul_f32_e32 v249, v112, v144
	v_fma_f32 v112, v112, v128, -v248
	v_fma_f32 v96, v96, v128, v249
	v_mul_f32_e32 v129, s2, v129
	v_mul_f32_e32 v145, s2, v145
	v_mul_f32_e32 v250, v97, v145
	v_mul_f32_e32 v251, v113, v145
	v_fma_f32 v113, v113, v129, -v250
	v_fma_f32 v97, v97, v129, v251
	v_mul_f32_e32 v130, s2, v130
	v_mul_f32_e32 v146, s2, v146
	v_mul_f32_e32 v248, v98, v146
	v_mul_f32_e32 v249, v114, v146
	v_fma_f32 v114, v114, v130, -v248
	v_fma_f32 v98, v98, v130, v249
	v_mul_f32_e32 v131, s2, v131
	v_mul_f32_e32 v147, s2, v147
	v_mul_f32_e32 v250, v99, v147
	v_mul_f32_e32 v251, v115, v147
	v_fma_f32 v115, v115, v131, -v250
	v_fma_f32 v99, v99, v131, v251
	v_mul_f32_e32 v132, s2, v132
	v_mul_f32_e32 v148, s2, v148
	v_mul_f32_e32 v248, v100, v148
	v_mul_f32_e32 v249, v116, v148
	v_fma_f32 v116, v116, v132, -v248
	v_fma_f32 v100, v100, v132, v249
	v_mul_f32_e32 v133, s2, v133
	v_mul_f32_e32 v149, s2, v149
	v_mul_f32_e32 v250, v101, v149
	v_mul_f32_e32 v251, v117, v149
	v_fma_f32 v117, v117, v133, -v250
	v_fma_f32 v101, v101, v133, v251
	v_mul_f32_e32 v134, s2, v134
	v_mul_f32_e32 v150, s2, v150
	v_mul_f32_e32 v248, v102, v150
	v_mul_f32_e32 v249, v118, v150
	v_fma_f32 v118, v118, v134, -v248
	v_fma_f32 v102, v102, v134, v249
	v_mul_f32_e32 v135, s2, v135
	v_mul_f32_e32 v151, s2, v151
	v_mul_f32_e32 v250, v103, v151
	v_mul_f32_e32 v251, v119, v151
	v_fma_f32 v119, v119, v135, -v250
	v_fma_f32 v103, v103, v135, v251
	v_mul_f32_e32 v136, s2, v136
	v_mul_f32_e32 v152, s2, v152
	v_mul_f32_e32 v248, v104, v152
	v_mul_f32_e32 v249, v120, v152
	v_fma_f32 v120, v120, v136, -v248
	v_fma_f32 v104, v104, v136, v249
; DI void phase_gemm_qkv(const Params& p, bf16_t* sm) {
;     ...
;         const int row = EPI_ROW4(mi, i);
;         const int col = n0 + ewn * 64 + er;
;         float x1 = acc[mi][0][i], x2 = acc[mi][1][i];
;         if (n0 < 1024) {
;           int pos = row & (SEQ - 1);
;           float c = p.ropeC[pos * 32 + er], s = p.ropeS[pos * 32 + er];
;           float o1 = x1 * c - x2 * s, o2 = x2 * c + x1 * s;
;           if (n0 < 512) { o1 *= 0.125f; o2 *= 0.125f; }
;           x1 = o1; x2 = o2;
	v_mul_f32_e32 v137, s2, v137
	v_mul_f32_e32 v153, s2, v153
	v_mul_f32_e32 v250, v105, v153
	v_mul_f32_e32 v251, v121, v153
	v_fma_f32 v121, v121, v137, -v250
	v_fma_f32 v105, v105, v137, v251
	v_mul_f32_e32 v138, s2, v138
	v_mul_f32_e32 v154, s2, v154
	v_mul_f32_e32 v248, v106, v154
	v_mul_f32_e32 v249, v122, v154
	v_fma_f32 v122, v122, v138, -v248
	v_fma_f32 v106, v106, v138, v249
	v_mul_f32_e32 v139, s2, v139
	v_mul_f32_e32 v155, s2, v155
	v_mul_f32_e32 v250, v107, v155
	v_mul_f32_e32 v251, v123, v155
	v_fma_f32 v123, v123, v139, -v250
	v_fma_f32 v107, v107, v139, v251
	v_mul_f32_e32 v140, s2, v140
	v_mul_f32_e32 v156, s2, v156
	v_mul_f32_e32 v248, v108, v156
	v_mul_f32_e32 v249, v124, v156
	v_fma_f32 v124, v124, v140, -v248
	v_fma_f32 v108, v108, v140, v249
	v_mul_f32_e32 v141, s2, v141
	v_mul_f32_e32 v157, s2, v157
	v_mul_f32_e32 v250, v109, v157
	v_mul_f32_e32 v251, v125, v157
	v_fma_f32 v125, v125, v141, -v250
	v_fma_f32 v109, v109, v141, v251
	v_mul_f32_e32 v142, s2, v142
	v_mul_f32_e32 v158, s2, v158
	v_mul_f32_e32 v248, v110, v158
	v_mul_f32_e32 v249, v126, v158
	v_fma_f32 v126, v126, v142, -v248
	v_fma_f32 v110, v110, v142, v249
	v_mul_f32_e32 v143, s2, v143
	v_mul_f32_e32 v159, s2, v159
	v_mul_f32_e32 v250, v111, v159
	v_mul_f32_e32 v251, v127, v159
	v_fma_f32 v127, v127, v143, -v250
	v_fma_f32 v111, v111, v143, v251
	global_load_dword v128, v244, s[0:1] offset:0
	global_load_dword v144, v244, s[4:5] offset:0
	global_load_dword v129, v244, s[0:1] offset:128
	global_load_dword v145, v244, s[4:5] offset:128
	global_load_dword v130, v244, s[0:1] offset:256
	global_load_dword v146, v244, s[4:5] offset:256
	global_load_dword v131, v244, s[0:1] offset:384
	global_load_dword v147, v244, s[4:5] offset:384
	global_load_dword v132, v244, s[0:1] offset:1024
	global_load_dword v148, v244, s[4:5] offset:1024
	global_load_dword v133, v244, s[0:1] offset:1152
	global_load_dword v149, v244, s[4:5] offset:1152
	global_load_dword v134, v244, s[0:1] offset:1280
	global_load_dword v150, v244, s[4:5] offset:1280
	global_load_dword v135, v244, s[0:1] offset:1408
	global_load_dword v151, v244, s[4:5] offset:1408
	global_load_dword v136, v244, s[0:1] offset:2048
	global_load_dword v152, v244, s[4:5] offset:2048
	global_load_dword v137, v244, s[0:1] offset:2176
	global_load_dword v153, v244, s[4:5] offset:2176
	global_load_dword v138, v244, s[0:1] offset:2304
	global_load_dword v154, v244, s[4:5] offset:2304
	global_load_dword v139, v244, s[0:1] offset:2432
	global_load_dword v155, v244, s[4:5] offset:2432
	global_load_dword v140, v244, s[0:1] offset:3072
	global_load_dword v156, v244, s[4:5] offset:3072
	global_load_dword v141, v244, s[0:1] offset:3200
	global_load_dword v157, v244, s[4:5] offset:3200
	global_load_dword v142, v244, s[0:1] offset:3328
	global_load_dword v158, v244, s[4:5] offset:3328
	global_load_dword v143, v244, s[0:1] offset:3456
	global_load_dword v159, v244, s[4:5] offset:3456
	s_add_u32 s0, s0, 0x1000
	s_addc_u32 s1, s1, 0
	s_add_u32 s4, s4, 0x1000
	s_addc_u32 s5, s5, 0
	s_waitcnt vmcnt(32)
	v_mul_f32_e32 v160, s2, v160
	v_mul_f32_e32 v190, s2, v190
	v_mul_f32_e32 v248, v64, v190
	v_mul_f32_e32 v249, v80, v190
	v_fma_f32 v80, v80, v160, -v248
	v_fma_f32 v64, v64, v160, v249
	v_mul_f32_e32 v161, s2, v161
	v_mul_f32_e32 v191, s2, v191
	v_mul_f32_e32 v250, v65, v191
	v_mul_f32_e32 v251, v81, v191
	v_fma_f32 v81, v81, v161, -v250
	v_fma_f32 v65, v65, v161, v251
	v_mul_f32_e32 v162, s2, v162
	v_mul_f32_e32 v192, s2, v192
	v_mul_f32_e32 v248, v66, v192
	v_mul_f32_e32 v249, v82, v192
	v_fma_f32 v82, v82, v162, -v248
	v_fma_f32 v66, v66, v162, v249
	v_mul_f32_e32 v163, s2, v163
	v_mul_f32_e32 v193, s2, v193
	v_mul_f32_e32 v250, v67, v193
	v_mul_f32_e32 v251, v83, v193
	v_fma_f32 v83, v83, v163, -v250
	v_fma_f32 v67, v67, v163, v251
	v_mul_f32_e32 v164, s2, v164
	v_mul_f32_e32 v194, s2, v194
	v_mul_f32_e32 v248, v68, v194
	v_mul_f32_e32 v249, v84, v194
	v_fma_f32 v84, v84, v164, -v248
	v_fma_f32 v68, v68, v164, v249
	v_mul_f32_e32 v165, s2, v165
	v_mul_f32_e32 v195, s2, v195
	v_mul_f32_e32 v250, v69, v195
	v_mul_f32_e32 v251, v85, v195
	v_fma_f32 v85, v85, v165, -v250
	v_fma_f32 v69, v69, v165, v251
	v_mul_f32_e32 v166, s2, v166
	v_mul_f32_e32 v196, s2, v196
	v_mul_f32_e32 v248, v70, v196
	v_mul_f32_e32 v249, v86, v196
	v_fma_f32 v86, v86, v166, -v248
	v_fma_f32 v70, v70, v166, v249
	v_mul_f32_e32 v167, s2, v167
	v_mul_f32_e32 v197, s2, v197
	v_mul_f32_e32 v250, v71, v197
	v_mul_f32_e32 v251, v87, v197
	v_fma_f32 v87, v87, v167, -v250
	v_fma_f32 v71, v71, v167, v251
	v_mul_f32_e32 v168, s2, v168
	v_mul_f32_e32 v198, s2, v198
	v_mul_f32_e32 v248, v72, v198
	v_mul_f32_e32 v249, v88, v198
	v_fma_f32 v88, v88, v168, -v248
	v_fma_f32 v72, v72, v168, v249
	v_mul_f32_e32 v169, s2, v169
	v_mul_f32_e32 v199, s2, v199
	v_mul_f32_e32 v250, v73, v199
	v_mul_f32_e32 v251, v89, v199
	v_fma_f32 v89, v89, v169, -v250
	v_fma_f32 v73, v73, v169, v251
	v_mul_f32_e32 v170, s2, v170
	v_mul_f32_e32 v200, s2, v200
	v_mul_f32_e32 v248, v74, v200
	v_mul_f32_e32 v249, v90, v200
	v_fma_f32 v90, v90, v170, -v248
	v_fma_f32 v74, v74, v170, v249
	v_mul_f32_e32 v171, s2, v171
	v_mul_f32_e32 v201, s2, v201
	v_mul_f32_e32 v250, v75, v201
	v_mul_f32_e32 v251, v91, v201
	v_fma_f32 v91, v91, v171, -v250
	v_fma_f32 v75, v75, v171, v251
	v_mul_f32_e32 v172, s2, v172
	v_mul_f32_e32 v206, s2, v206
	v_mul_f32_e32 v248, v76, v206
	v_mul_f32_e32 v249, v92, v206
	v_fma_f32 v92, v92, v172, -v248
	v_fma_f32 v76, v76, v172, v249
	v_mul_f32_e32 v173, s2, v173
	v_mul_f32_e32 v207, s2, v207
	v_mul_f32_e32 v250, v77, v207
	v_mul_f32_e32 v251, v93, v207
	v_fma_f32 v93, v93, v173, -v250
; DI void phase_gemm_qkv(const Params& p, bf16_t* sm) {
;     ...
;         const int row = EPI_ROW4(mi, i);
;         const int col = n0 + ewn * 64 + er;
;         float x1 = acc[mi][0][i], x2 = acc[mi][1][i];
;         if (n0 < 1024) {
;           int pos = row & (SEQ - 1);
;           float c = p.ropeC[pos * 32 + er], s = p.ropeS[pos * 32 + er];
;           float o1 = x1 * c - x2 * s, o2 = x2 * c + x1 * s;
;           if (n0 < 512) { o1 *= 0.125f; o2 *= 0.125f; }
;           x1 = o1; x2 = o2;
	v_fma_f32 v77, v77, v173, v251
	v_mul_f32_e32 v174, s2, v174
	v_mul_f32_e32 v208, s2, v208
	v_mul_f32_e32 v248, v78, v208
	v_mul_f32_e32 v249, v94, v208
	v_fma_f32 v94, v94, v174, -v248
	v_fma_f32 v78, v78, v174, v249
	v_mul_f32_e32 v175, s2, v175
	v_mul_f32_e32 v209, s2, v209
	v_mul_f32_e32 v250, v79, v209
	v_mul_f32_e32 v251, v95, v209
	v_fma_f32 v95, v95, v175, -v250
	v_fma_f32 v79, v79, v175, v251
	global_load_dword v160, v244, s[0:1] offset:0
	global_load_dword v190, v244, s[4:5] offset:0
	global_load_dword v161, v244, s[0:1] offset:128
	global_load_dword v191, v244, s[4:5] offset:128
	global_load_dword v162, v244, s[0:1] offset:256
	global_load_dword v192, v244, s[4:5] offset:256
	global_load_dword v163, v244, s[0:1] offset:384
	global_load_dword v193, v244, s[4:5] offset:384
	global_load_dword v164, v244, s[0:1] offset:1024
	global_load_dword v194, v244, s[4:5] offset:1024
	global_load_dword v165, v244, s[0:1] offset:1152
	global_load_dword v195, v244, s[4:5] offset:1152
	global_load_dword v166, v244, s[0:1] offset:1280
	global_load_dword v196, v244, s[4:5] offset:1280
	global_load_dword v167, v244, s[0:1] offset:1408
	global_load_dword v197, v244, s[4:5] offset:1408
	global_load_dword v168, v244, s[0:1] offset:2048
	global_load_dword v198, v244, s[4:5] offset:2048
	global_load_dword v169, v244, s[0:1] offset:2176
	global_load_dword v199, v244, s[4:5] offset:2176
	global_load_dword v170, v244, s[0:1] offset:2304
	global_load_dword v200, v244, s[4:5] offset:2304
	global_load_dword v171, v244, s[0:1] offset:2432
	global_load_dword v201, v244, s[4:5] offset:2432
	global_load_dword v172, v244, s[0:1] offset:3072
	global_load_dword v206, v244, s[4:5] offset:3072
	global_load_dword v173, v244, s[0:1] offset:3200
	global_load_dword v207, v244, s[4:5] offset:3200
	global_load_dword v174, v244, s[0:1] offset:3328
	global_load_dword v208, v244, s[4:5] offset:3328
	global_load_dword v175, v244, s[0:1] offset:3456
	global_load_dword v209, v244, s[4:5] offset:3456
	s_add_u32 s0, s0, 0x1000
	s_addc_u32 s1, s1, 0
	s_add_u32 s4, s4, 0x1000
	s_addc_u32 s5, s5, 0
	s_waitcnt vmcnt(32)
	v_mul_f32_e32 v128, s2, v128
	v_mul_f32_e32 v144, s2, v144
	v_mul_f32_e32 v248, v32, v144
	v_mul_f32_e32 v249, v48, v144
	v_fma_f32 v48, v48, v128, -v248
	v_fma_f32 v32, v32, v128, v249
	v_mul_f32_e32 v129, s2, v129
	v_mul_f32_e32 v145, s2, v145
	v_mul_f32_e32 v250, v33, v145
	v_mul_f32_e32 v251, v49, v145
	v_fma_f32 v49, v49, v129, -v250
	v_fma_f32 v33, v33, v129, v251
	v_mul_f32_e32 v130, s2, v130
	v_mul_f32_e32 v146, s2, v146
	v_mul_f32_e32 v248, v34, v146
	v_mul_f32_e32 v249, v50, v146
	v_fma_f32 v50, v50, v130, -v248
	v_fma_f32 v34, v34, v130, v249
	v_mul_f32_e32 v131, s2, v131
	v_mul_f32_e32 v147, s2, v147
	v_mul_f32_e32 v250, v35, v147
	v_mul_f32_e32 v251, v51, v147
	v_fma_f32 v51, v51, v131, -v250
	v_fma_f32 v35, v35, v131, v251
	v_mul_f32_e32 v132, s2, v132
	v_mul_f32_e32 v148, s2, v148
	v_mul_f32_e32 v248, v36, v148
	v_mul_f32_e32 v249, v52, v148
	v_fma_f32 v52, v52, v132, -v248
	v_fma_f32 v36, v36, v132, v249
	v_mul_f32_e32 v133, s2, v133
	v_mul_f32_e32 v149, s2, v149
	v_mul_f32_e32 v250, v37, v149
	v_mul_f32_e32 v251, v53, v149
	v_fma_f32 v53, v53, v133, -v250
	v_fma_f32 v37, v37, v133, v251
	v_mul_f32_e32 v134, s2, v134
	v_mul_f32_e32 v150, s2, v150
	v_mul_f32_e32 v248, v38, v150
	v_mul_f32_e32 v249, v54, v150
	v_fma_f32 v54, v54, v134, -v248
	v_fma_f32 v38, v38, v134, v249
	v_mul_f32_e32 v135, s2, v135
	v_mul_f32_e32 v151, s2, v151
	v_mul_f32_e32 v250, v39, v151
	v_mul_f32_e32 v251, v55, v151
	v_fma_f32 v55, v55, v135, -v250
	v_fma_f32 v39, v39, v135, v251
	v_mul_f32_e32 v136, s2, v136
	v_mul_f32_e32 v152, s2, v152
	v_mul_f32_e32 v248, v40, v152
	v_mul_f32_e32 v249, v56, v152
	v_fma_f32 v56, v56, v136, -v248
	v_fma_f32 v40, v40, v136, v249
	v_mul_f32_e32 v137, s2, v137
	v_mul_f32_e32 v153, s2, v153
	v_mul_f32_e32 v250, v41, v153
	v_mul_f32_e32 v251, v57, v153
	v_fma_f32 v57, v57, v137, -v250
	v_fma_f32 v41, v41, v137, v251
	v_mul_f32_e32 v138, s2, v138
	v_mul_f32_e32 v154, s2, v154
	v_mul_f32_e32 v248, v42, v154
	v_mul_f32_e32 v249, v58, v154
	v_fma_f32 v58, v58, v138, -v248
	v_fma_f32 v42, v42, v138, v249
	v_mul_f32_e32 v139, s2, v139
	v_mul_f32_e32 v155, s2, v155
	v_mul_f32_e32 v250, v43, v155
	v_mul_f32_e32 v251, v59, v155
	v_fma_f32 v59, v59, v139, -v250
	v_fma_f32 v43, v43, v139, v251
	v_mul_f32_e32 v140, s2, v140
	v_mul_f32_e32 v156, s2, v156
	v_mul_f32_e32 v248, v44, v156
	v_mul_f32_e32 v249, v60, v156
	v_fma_f32 v60, v60, v140, -v248
	v_fma_f32 v44, v44, v140, v249
	v_mul_f32_e32 v141, s2, v141
	v_mul_f32_e32 v157, s2, v157
	v_mul_f32_e32 v250, v45, v157
	v_mul_f32_e32 v251, v61, v157
	v_fma_f32 v61, v61, v141, -v250
	v_fma_f32 v45, v45, v141, v251
	v_mul_f32_e32 v142, s2, v142
	v_mul_f32_e32 v158, s2, v158
	v_mul_f32_e32 v248, v46, v158
	v_mul_f32_e32 v249, v62, v158
	v_fma_f32 v62, v62, v142, -v248
	v_fma_f32 v46, v46, v142, v249
	v_mul_f32_e32 v143, s2, v143
	v_mul_f32_e32 v159, s2, v159
	v_mul_f32_e32 v250, v47, v159
	v_mul_f32_e32 v251, v63, v159
	v_fma_f32 v63, v63, v143, -v250
	v_fma_f32 v47, v47, v143, v251
	s_waitcnt vmcnt(0)
; DI bf16_t f2bf(float x) { unsigned u = __float_as_uint(x); u += 0x7fffu + ((u >> 16) & 1u); return (bf16_t)(u >> 16); }
; DI void phase_gemm_qkv(const Params& p, bf16_t* sm) {
;     ...
;         if (n0 < 1024) {
;           int pos = row & (SEQ - 1);
;           float c = p.ropeC[pos * 32 + er], s = p.ropeS[pos * 32 + er];
;           float o1 = x1 * c - x2 * s, o2 = x2 * c + x1 * s;
;           if (n0 < 512) { o1 *= 0.125f; o2 *= 0.125f; }
;           x1 = o1; x2 = o2;
;         }
;         qkv[(size_t)row * 1536 + col] = f2bf(x1);
;         qkv[(size_t)row * 1536 + col + 32] = f2bf(x2);
	v_mul_f32_e32 v160, s2, v160
	v_mul_f32_e32 v190, s2, v190
	v_mul_f32_e32 v248, v0, v190
	v_mul_f32_e32 v249, v16, v190
	v_fma_f32 v16, v16, v160, -v248
	v_fma_f32 v0, v0, v160, v249
	v_mul_f32_e32 v161, s2, v161
	v_mul_f32_e32 v191, s2, v191
	v_mul_f32_e32 v250, v1, v191
	v_mul_f32_e32 v251, v17, v191
	v_fma_f32 v17, v17, v161, -v250
	v_fma_f32 v1, v1, v161, v251
	v_mul_f32_e32 v162, s2, v162
	v_mul_f32_e32 v192, s2, v192
	v_mul_f32_e32 v248, v2, v192
	v_mul_f32_e32 v249, v18, v192
	v_fma_f32 v18, v18, v162, -v248
	v_fma_f32 v2, v2, v162, v249
	v_mul_f32_e32 v163, s2, v163
	v_mul_f32_e32 v193, s2, v193
	v_mul_f32_e32 v250, v3, v193
	v_mul_f32_e32 v251, v19, v193
	v_fma_f32 v19, v19, v163, -v250
	v_fma_f32 v3, v3, v163, v251
	v_mul_f32_e32 v164, s2, v164
	v_mul_f32_e32 v194, s2, v194
	v_mul_f32_e32 v248, v4, v194
	v_mul_f32_e32 v249, v20, v194
	v_fma_f32 v20, v20, v164, -v248
	v_fma_f32 v4, v4, v164, v249
	v_mul_f32_e32 v165, s2, v165
	v_mul_f32_e32 v195, s2, v195
	v_mul_f32_e32 v250, v5, v195
	v_mul_f32_e32 v251, v21, v195
	v_fma_f32 v21, v21, v165, -v250
	v_fma_f32 v5, v5, v165, v251
	v_mul_f32_e32 v166, s2, v166
	v_mul_f32_e32 v196, s2, v196
	v_mul_f32_e32 v248, v6, v196
	v_mul_f32_e32 v249, v22, v196
	v_fma_f32 v22, v22, v166, -v248
	v_fma_f32 v6, v6, v166, v249
	v_mul_f32_e32 v167, s2, v167
	v_mul_f32_e32 v197, s2, v197
	v_mul_f32_e32 v250, v7, v197
	v_mul_f32_e32 v251, v23, v197
	v_fma_f32 v23, v23, v167, -v250
	v_fma_f32 v7, v7, v167, v251
	v_mul_f32_e32 v168, s2, v168
	v_mul_f32_e32 v198, s2, v198
	v_mul_f32_e32 v248, v8, v198
	v_mul_f32_e32 v249, v24, v198
	v_fma_f32 v24, v24, v168, -v248
	v_fma_f32 v8, v8, v168, v249
	v_mul_f32_e32 v169, s2, v169
	v_mul_f32_e32 v199, s2, v199
	v_mul_f32_e32 v250, v9, v199
	v_mul_f32_e32 v251, v25, v199
	v_fma_f32 v25, v25, v169, -v250
	v_fma_f32 v9, v9, v169, v251
	v_mul_f32_e32 v170, s2, v170
	v_mul_f32_e32 v200, s2, v200
	v_mul_f32_e32 v248, v10, v200
	v_mul_f32_e32 v249, v26, v200
	v_fma_f32 v26, v26, v170, -v248
	v_fma_f32 v10, v10, v170, v249
	v_mul_f32_e32 v171, s2, v171
	v_mul_f32_e32 v201, s2, v201
	v_mul_f32_e32 v250, v11, v201
	v_mul_f32_e32 v251, v27, v201
	v_fma_f32 v27, v27, v171, -v250
	v_fma_f32 v11, v11, v171, v251
	v_mul_f32_e32 v172, s2, v172
	v_mul_f32_e32 v206, s2, v206
	v_mul_f32_e32 v248, v12, v206
	v_mul_f32_e32 v249, v28, v206
	v_fma_f32 v28, v28, v172, -v248
	v_fma_f32 v12, v12, v172, v249
	v_mul_f32_e32 v173, s2, v173
	v_mul_f32_e32 v207, s2, v207
	v_mul_f32_e32 v250, v13, v207
	v_mul_f32_e32 v251, v29, v207
	v_fma_f32 v29, v29, v173, -v250
	v_fma_f32 v13, v13, v173, v251
	v_mul_f32_e32 v174, s2, v174
	v_mul_f32_e32 v208, s2, v208
	v_mul_f32_e32 v248, v14, v208
	v_mul_f32_e32 v249, v30, v208
	v_fma_f32 v30, v30, v174, -v248
	v_fma_f32 v14, v14, v174, v249
	v_mul_f32_e32 v175, s2, v175
	v_mul_f32_e32 v209, s2, v209
	v_mul_f32_e32 v250, v15, v209
	v_mul_f32_e32 v251, v31, v209
	v_fma_f32 v31, v31, v175, -v250
	v_fma_f32 v15, v15, v175, v251
.Lqkv0_store:
	s_nop 1
	v_bfe_u32 v248, v112, 16, 1
	v_bfe_u32 v249, v96, 16, 1
	v_add3_u32 v248, v112, v248, s13
	v_add3_u32 v249, v96, v249, s13
	global_store_short_d16_hi v247, v248, s[8:9]
	global_store_short_d16_hi v247, v249, s[8:9] offset:64
	v_add_u32_e32 v247, 0xc00, v247
	v_bfe_u32 v250, v113, 16, 1
	v_bfe_u32 v251, v97, 16, 1
	v_add3_u32 v250, v113, v250, s13
	v_add3_u32 v251, v97, v251, s13
	global_store_short_d16_hi v247, v250, s[8:9]
	global_store_short_d16_hi v247, v251, s[8:9] offset:64
	v_add_u32_e32 v247, 0xc00, v247
	v_bfe_u32 v248, v114, 16, 1
	v_bfe_u32 v249, v98, 16, 1
	v_add3_u32 v248, v114, v248, s13
	v_add3_u32 v249, v98, v249, s13
	global_store_short_d16_hi v247, v248, s[8:9]
	global_store_short_d16_hi v247, v249, s[8:9] offset:64
	v_add_u32_e32 v247, 0xc00, v247
	v_bfe_u32 v250, v115, 16, 1
	v_bfe_u32 v251, v99, 16, 1
	v_add3_u32 v250, v115, v250, s13
	v_add3_u32 v251, v99, v251, s13
	global_store_short_d16_hi v247, v250, s[8:9]
	global_store_short_d16_hi v247, v251, s[8:9] offset:64
	v_add_u32_e32 v247, 0x3c00, v247
	v_bfe_u32 v248, v116, 16, 1
	v_bfe_u32 v249, v100, 16, 1
	v_add3_u32 v248, v116, v248, s13
	v_add3_u32 v249, v100, v249, s13
	global_store_short_d16_hi v247, v248, s[8:9]
	global_store_short_d16_hi v247, v249, s[8:9] offset:64
	v_add_u32_e32 v247, 0xc00, v247
	v_bfe_u32 v250, v117, 16, 1
	v_bfe_u32 v251, v101, 16, 1
	v_add3_u32 v250, v117, v250, s13
	v_add3_u32 v251, v101, v251, s13
	global_store_short_d16_hi v247, v250, s[8:9]
	global_store_short_d16_hi v247, v251, s[8:9] offset:64
	v_add_u32_e32 v247, 0xc00, v247
	v_bfe_u32 v248, v118, 16, 1
	v_bfe_u32 v249, v102, 16, 1
	v_add3_u32 v248, v118, v248, s13
	v_add3_u32 v249, v102, v249, s13
	global_store_short_d16_hi v247, v248, s[8:9]
	global_store_short_d16_hi v247, v249, s[8:9] offset:64
	v_add_u32_e32 v247, 0xc00, v247
	v_bfe_u32 v250, v119, 16, 1
	v_bfe_u32 v251, v103, 16, 1
	v_add3_u32 v250, v119, v250, s13
	v_add3_u32 v251, v103, v251, s13
	global_store_short_d16_hi v247, v250, s[8:9]
	global_store_short_d16_hi v247, v251, s[8:9] offset:64
	v_add_u32_e32 v247, 0x3c00, v247
	v_bfe_u32 v248, v120, 16, 1
	v_bfe_u32 v249, v104, 16, 1
	v_add3_u32 v248, v120, v248, s13
	v_add3_u32 v249, v104, v249, s13
	global_store_short_d16_hi v247, v248, s[8:9]
	global_store_short_d16_hi v247, v249, s[8:9] offset:64
	v_add_u32_e32 v247, 0xc00, v247
	v_bfe_u32 v250, v121, 16, 1
	v_bfe_u32 v251, v105, 16, 1
	v_add3_u32 v250, v121, v250, s13
	v_add3_u32 v251, v105, v251, s13
	global_store_short_d16_hi v247, v250, s[8:9]
	global_store_short_d16_hi v247, v251, s[8:9] offset:64
	v_add_u32_e32 v247, 0xc00, v247
	v_bfe_u32 v248, v122, 16, 1
	v_bfe_u32 v249, v106, 16, 1
; DI bf16_t f2bf(float x) { unsigned u = __float_as_uint(x); u += 0x7fffu + ((u >> 16) & 1u); return (bf16_t)(u >> 16); }
; DI void phase_gemm_qkv(const Params& p, bf16_t* sm) {
;     ...
;         qkv[(size_t)row * 1536 + col] = f2bf(x1);
;         qkv[(size_t)row * 1536 + col + 32] = f2bf(x2);
	v_add3_u32 v248, v122, v248, s13
	v_add3_u32 v249, v106, v249, s13
	global_store_short_d16_hi v247, v248, s[8:9]
	global_store_short_d16_hi v247, v249, s[8:9] offset:64
	v_add_u32_e32 v247, 0xc00, v247
	v_bfe_u32 v250, v123, 16, 1
	v_bfe_u32 v251, v107, 16, 1
	v_add3_u32 v250, v123, v250, s13
	v_add3_u32 v251, v107, v251, s13
	global_store_short_d16_hi v247, v250, s[8:9]
	global_store_short_d16_hi v247, v251, s[8:9] offset:64
	v_add_u32_e32 v247, 0x3c00, v247
	v_bfe_u32 v248, v124, 16, 1
	v_bfe_u32 v249, v108, 16, 1
	v_add3_u32 v248, v124, v248, s13
	v_add3_u32 v249, v108, v249, s13
	global_store_short_d16_hi v247, v248, s[8:9]
	global_store_short_d16_hi v247, v249, s[8:9] offset:64
	v_add_u32_e32 v247, 0xc00, v247
	v_bfe_u32 v250, v125, 16, 1
	v_bfe_u32 v251, v109, 16, 1
	v_add3_u32 v250, v125, v250, s13
	v_add3_u32 v251, v109, v251, s13
	global_store_short_d16_hi v247, v250, s[8:9]
	global_store_short_d16_hi v247, v251, s[8:9] offset:64
	v_add_u32_e32 v247, 0xc00, v247
	v_bfe_u32 v248, v126, 16, 1
	v_bfe_u32 v249, v110, 16, 1
	v_add3_u32 v248, v126, v248, s13
	v_add3_u32 v249, v110, v249, s13
	global_store_short_d16_hi v247, v248, s[8:9]
	global_store_short_d16_hi v247, v249, s[8:9] offset:64
	v_add_u32_e32 v247, 0xc00, v247
	v_bfe_u32 v250, v127, 16, 1
	v_bfe_u32 v251, v111, 16, 1
	v_add3_u32 v250, v127, v250, s13
	v_add3_u32 v251, v111, v251, s13
	global_store_short_d16_hi v247, v250, s[8:9]
	global_store_short_d16_hi v247, v251, s[8:9] offset:64
	v_add_u32_e32 v247, 0x3c00, v247
	v_bfe_u32 v248, v80, 16, 1
	v_bfe_u32 v249, v64, 16, 1
	v_add3_u32 v248, v80, v248, s13
	v_add3_u32 v249, v64, v249, s13
	global_store_short_d16_hi v247, v248, s[8:9]
	global_store_short_d16_hi v247, v249, s[8:9] offset:64
	v_add_u32_e32 v247, 0xc00, v247
	v_bfe_u32 v250, v81, 16, 1
	v_bfe_u32 v251, v65, 16, 1
	v_add3_u32 v250, v81, v250, s13
	v_add3_u32 v251, v65, v251, s13
	global_store_short_d16_hi v247, v250, s[8:9]
	global_store_short_d16_hi v247, v251, s[8:9] offset:64
	v_add_u32_e32 v247, 0xc00, v247
	v_bfe_u32 v248, v82, 16, 1
	v_bfe_u32 v249, v66, 16, 1
	v_add3_u32 v248, v82, v248, s13
	v_add3_u32 v249, v66, v249, s13
	global_store_short_d16_hi v247, v248, s[8:9]
	global_store_short_d16_hi v247, v249, s[8:9] offset:64
	v_add_u32_e32 v247, 0xc00, v247
	v_bfe_u32 v250, v83, 16, 1
	v_bfe_u32 v251, v67, 16, 1
	v_add3_u32 v250, v83, v250, s13
	v_add3_u32 v251, v67, v251, s13
	global_store_short_d16_hi v247, v250, s[8:9]
	global_store_short_d16_hi v247, v251, s[8:9] offset:64
	v_add_u32_e32 v247, 0x3c00, v247
	v_bfe_u32 v248, v84, 16, 1
	v_bfe_u32 v249, v68, 16, 1
	v_add3_u32 v248, v84, v248, s13
	v_add3_u32 v249, v68, v249, s13
	global_store_short_d16_hi v247, v248, s[8:9]
	global_store_short_d16_hi v247, v249, s[8:9] offset:64
	v_add_u32_e32 v247, 0xc00, v247
	v_bfe_u32 v250, v85, 16, 1
	v_bfe_u32 v251, v69, 16, 1
	v_add3_u32 v250, v85, v250, s13
	v_add3_u32 v251, v69, v251, s13
	global_store_short_d16_hi v247, v250, s[8:9]
	global_store_short_d16_hi v247, v251, s[8:9] offset:64
	v_add_u32_e32 v247, 0xc00, v247
	v_bfe_u32 v248, v86, 16, 1
	v_bfe_u32 v249, v70, 16, 1
	v_add3_u32 v248, v86, v248, s13
	v_add3_u32 v249, v70, v249, s13
	global_store_short_d16_hi v247, v248, s[8:9]
	global_store_short_d16_hi v247, v249, s[8:9] offset:64
	v_add_u32_e32 v247, 0xc00, v247
	v_bfe_u32 v250, v87, 16, 1
	v_bfe_u32 v251, v71, 16, 1
	v_add3_u32 v250, v87, v250, s13
	v_add3_u32 v251, v71, v251, s13
	global_store_short_d16_hi v247, v250, s[8:9]
	global_store_short_d16_hi v247, v251, s[8:9] offset:64
	v_add_u32_e32 v247, 0x3c00, v247
	v_bfe_u32 v248, v88, 16, 1
	v_bfe_u32 v249, v72, 16, 1
	v_add3_u32 v248, v88, v248, s13
	v_add3_u32 v249, v72, v249, s13
	global_store_short_d16_hi v247, v248, s[8:9]
	global_store_short_d16_hi v247, v249, s[8:9] offset:64
	v_add_u32_e32 v247, 0xc00, v247
	v_bfe_u32 v250, v89, 16, 1
	v_bfe_u32 v251, v73, 16, 1
	v_add3_u32 v250, v89, v250, s13
	v_add3_u32 v251, v73, v251, s13
	global_store_short_d16_hi v247, v250, s[8:9]
	global_store_short_d16_hi v247, v251, s[8:9] offset:64
	v_add_u32_e32 v247, 0xc00, v247
	v_bfe_u32 v248, v90, 16, 1
	v_bfe_u32 v249, v74, 16, 1
	v_add3_u32 v248, v90, v248, s13
	v_add3_u32 v249, v74, v249, s13
	global_store_short_d16_hi v247, v248, s[8:9]
	global_store_short_d16_hi v247, v249, s[8:9] offset:64
	v_add_u32_e32 v247, 0xc00, v247
	v_bfe_u32 v250, v91, 16, 1
	v_bfe_u32 v251, v75, 16, 1
	v_add3_u32 v250, v91, v250, s13
	v_add3_u32 v251, v75, v251, s13
	global_store_short_d16_hi v247, v250, s[8:9]
	global_store_short_d16_hi v247, v251, s[8:9] offset:64
	v_add_u32_e32 v247, 0x3c00, v247
	v_bfe_u32 v248, v92, 16, 1
	v_bfe_u32 v249, v76, 16, 1
	v_add3_u32 v248, v92, v248, s13
	v_add3_u32 v249, v76, v249, s13
	global_store_short_d16_hi v247, v248, s[8:9]
	global_store_short_d16_hi v247, v249, s[8:9] offset:64
	v_add_u32_e32 v247, 0xc00, v247
	v_bfe_u32 v250, v93, 16, 1
	v_bfe_u32 v251, v77, 16, 1
	v_add3_u32 v250, v93, v250, s13
	v_add3_u32 v251, v77, v251, s13
	global_store_short_d16_hi v247, v250, s[8:9]
	global_store_short_d16_hi v247, v251, s[8:9] offset:64
	v_add_u32_e32 v247, 0xc00, v247
	v_bfe_u32 v248, v94, 16, 1
	v_bfe_u32 v249, v78, 16, 1
	v_add3_u32 v248, v94, v248, s13
	v_add3_u32 v249, v78, v249, s13
	global_store_short_d16_hi v247, v248, s[8:9]
	global_store_short_d16_hi v247, v249, s[8:9] offset:64
	v_add_u32_e32 v247, 0xc00, v247
	v_bfe_u32 v250, v95, 16, 1
	v_bfe_u32 v251, v79, 16, 1
	v_add3_u32 v250, v95, v250, s13
	v_add3_u32 v251, v79, v251, s13
	global_store_short_d16_hi v247, v250, s[8:9]
	global_store_short_d16_hi v247, v251, s[8:9] offset:64
	v_add_u32_e32 v247, 0x3c00, v247
; DI bf16_t f2bf(float x) { unsigned u = __float_as_uint(x); u += 0x7fffu + ((u >> 16) & 1u); return (bf16_t)(u >> 16); }
; DI void phase_gemm_qkv(const Params& p, bf16_t* sm) {
;     ...
;         qkv[(size_t)row * 1536 + col] = f2bf(x1);
;         qkv[(size_t)row * 1536 + col + 32] = f2bf(x2);
	v_bfe_u32 v248, v48, 16, 1
	v_bfe_u32 v249, v32, 16, 1
	v_add3_u32 v248, v48, v248, s13
	v_add3_u32 v249, v32, v249, s13
	global_store_short_d16_hi v247, v248, s[8:9]
	global_store_short_d16_hi v247, v249, s[8:9] offset:64
	v_add_u32_e32 v247, 0xc00, v247
	v_bfe_u32 v250, v49, 16, 1
	v_bfe_u32 v251, v33, 16, 1
	v_add3_u32 v250, v49, v250, s13
	v_add3_u32 v251, v33, v251, s13
	global_store_short_d16_hi v247, v250, s[8:9]
	global_store_short_d16_hi v247, v251, s[8:9] offset:64
	v_add_u32_e32 v247, 0xc00, v247
	v_bfe_u32 v248, v50, 16, 1
	v_bfe_u32 v249, v34, 16, 1
	v_add3_u32 v248, v50, v248, s13
	v_add3_u32 v249, v34, v249, s13
	global_store_short_d16_hi v247, v248, s[8:9]
	global_store_short_d16_hi v247, v249, s[8:9] offset:64
	v_add_u32_e32 v247, 0xc00, v247
	v_bfe_u32 v250, v51, 16, 1
	v_bfe_u32 v251, v35, 16, 1
	v_add3_u32 v250, v51, v250, s13
	v_add3_u32 v251, v35, v251, s13
	global_store_short_d16_hi v247, v250, s[8:9]
	global_store_short_d16_hi v247, v251, s[8:9] offset:64
	v_add_u32_e32 v247, 0x3c00, v247
	v_bfe_u32 v248, v52, 16, 1
	v_bfe_u32 v249, v36, 16, 1
	v_add3_u32 v248, v52, v248, s13
	v_add3_u32 v249, v36, v249, s13
	global_store_short_d16_hi v247, v248, s[8:9]
	global_store_short_d16_hi v247, v249, s[8:9] offset:64
	v_add_u32_e32 v247, 0xc00, v247
	v_bfe_u32 v250, v53, 16, 1
	v_bfe_u32 v251, v37, 16, 1
	v_add3_u32 v250, v53, v250, s13
	v_add3_u32 v251, v37, v251, s13
	global_store_short_d16_hi v247, v250, s[8:9]
	global_store_short_d16_hi v247, v251, s[8:9] offset:64
	v_add_u32_e32 v247, 0xc00, v247
	v_bfe_u32 v248, v54, 16, 1
	v_bfe_u32 v249, v38, 16, 1
	v_add3_u32 v248, v54, v248, s13
	v_add3_u32 v249, v38, v249, s13
	global_store_short_d16_hi v247, v248, s[8:9]
	global_store_short_d16_hi v247, v249, s[8:9] offset:64
	v_add_u32_e32 v247, 0xc00, v247
	v_bfe_u32 v250, v55, 16, 1
	v_bfe_u32 v251, v39, 16, 1
	v_add3_u32 v250, v55, v250, s13
	v_add3_u32 v251, v39, v251, s13
	global_store_short_d16_hi v247, v250, s[8:9]
	global_store_short_d16_hi v247, v251, s[8:9] offset:64
	v_add_u32_e32 v247, 0x3c00, v247
	v_bfe_u32 v248, v56, 16, 1
	v_bfe_u32 v249, v40, 16, 1
	v_add3_u32 v248, v56, v248, s13
	v_add3_u32 v249, v40, v249, s13
	global_store_short_d16_hi v247, v248, s[8:9]
	global_store_short_d16_hi v247, v249, s[8:9] offset:64
	v_add_u32_e32 v247, 0xc00, v247
	v_bfe_u32 v250, v57, 16, 1
	v_bfe_u32 v251, v41, 16, 1
	v_add3_u32 v250, v57, v250, s13
	v_add3_u32 v251, v41, v251, s13
	global_store_short_d16_hi v247, v250, s[8:9]
	global_store_short_d16_hi v247, v251, s[8:9] offset:64
	v_add_u32_e32 v247, 0xc00, v247
	v_bfe_u32 v248, v58, 16, 1
	v_bfe_u32 v249, v42, 16, 1
	v_add3_u32 v248, v58, v248, s13
	v_add3_u32 v249, v42, v249, s13
	global_store_short_d16_hi v247, v248, s[8:9]
	global_store_short_d16_hi v247, v249, s[8:9] offset:64
	v_add_u32_e32 v247, 0xc00, v247
	v_bfe_u32 v250, v59, 16, 1
	v_bfe_u32 v251, v43, 16, 1
	v_add3_u32 v250, v59, v250, s13
	v_add3_u32 v251, v43, v251, s13
	global_store_short_d16_hi v247, v250, s[8:9]
	global_store_short_d16_hi v247, v251, s[8:9] offset:64
	v_add_u32_e32 v247, 0x3c00, v247
	v_bfe_u32 v248, v60, 16, 1
	v_bfe_u32 v249, v44, 16, 1
	v_add3_u32 v248, v60, v248, s13
	v_add3_u32 v249, v44, v249, s13
	global_store_short_d16_hi v247, v248, s[8:9]
	global_store_short_d16_hi v247, v249, s[8:9] offset:64
	v_add_u32_e32 v247, 0xc00, v247
	v_bfe_u32 v250, v61, 16, 1
	v_bfe_u32 v251, v45, 16, 1
	v_add3_u32 v250, v61, v250, s13
	v_add3_u32 v251, v45, v251, s13
	global_store_short_d16_hi v247, v250, s[8:9]
	global_store_short_d16_hi v247, v251, s[8:9] offset:64
	v_add_u32_e32 v247, 0xc00, v247
	v_bfe_u32 v248, v62, 16, 1
	v_bfe_u32 v249, v46, 16, 1
	v_add3_u32 v248, v62, v248, s13
	v_add3_u32 v249, v46, v249, s13
	global_store_short_d16_hi v247, v248, s[8:9]
	global_store_short_d16_hi v247, v249, s[8:9] offset:64
	v_add_u32_e32 v247, 0xc00, v247
	v_bfe_u32 v250, v63, 16, 1
	v_bfe_u32 v251, v47, 16, 1
	v_add3_u32 v250, v63, v250, s13
	v_add3_u32 v251, v47, v251, s13
	global_store_short_d16_hi v247, v250, s[8:9]
	global_store_short_d16_hi v247, v251, s[8:9] offset:64
; DI bf16_t f2bf(float x) { unsigned u = __float_as_uint(x); u += 0x7fffu + ((u >> 16) & 1u); return (bf16_t)(u >> 16); }
; DI void phase_gemm_qkv(const Params& p, bf16_t* sm) {
;     ...
;         qkv[(size_t)row * 1536 + col] = f2bf(x1);
;         qkv[(size_t)row * 1536 + col + 32] = f2bf(x2);
	v_add_u32_e32 v247, 0x3c00, v247
	v_bfe_u32 v248, v16, 16, 1
	v_bfe_u32 v249, v0, 16, 1
	v_add3_u32 v248, v16, v248, s13
	v_add3_u32 v249, v0, v249, s13
	global_store_short_d16_hi v247, v248, s[8:9]
	global_store_short_d16_hi v247, v249, s[8:9] offset:64
	v_add_u32_e32 v247, 0xc00, v247
	v_bfe_u32 v250, v17, 16, 1
	v_bfe_u32 v251, v1, 16, 1
	v_add3_u32 v250, v17, v250, s13
	v_add3_u32 v251, v1, v251, s13
	global_store_short_d16_hi v247, v250, s[8:9]
	global_store_short_d16_hi v247, v251, s[8:9] offset:64
	v_add_u32_e32 v247, 0xc00, v247
	v_bfe_u32 v248, v18, 16, 1
	v_bfe_u32 v249, v2, 16, 1
	v_add3_u32 v248, v18, v248, s13
	v_add3_u32 v249, v2, v249, s13
	global_store_short_d16_hi v247, v248, s[8:9]
	global_store_short_d16_hi v247, v249, s[8:9] offset:64
	v_add_u32_e32 v247, 0xc00, v247
	v_bfe_u32 v250, v19, 16, 1
	v_bfe_u32 v251, v3, 16, 1
	v_add3_u32 v250, v19, v250, s13
	v_add3_u32 v251, v3, v251, s13
	global_store_short_d16_hi v247, v250, s[8:9]
	global_store_short_d16_hi v247, v251, s[8:9] offset:64
	v_add_u32_e32 v247, 0x3c00, v247
	v_bfe_u32 v248, v20, 16, 1
	v_bfe_u32 v249, v4, 16, 1
	v_add3_u32 v248, v20, v248, s13
	v_add3_u32 v249, v4, v249, s13
	global_store_short_d16_hi v247, v248, s[8:9]
	global_store_short_d16_hi v247, v249, s[8:9] offset:64
	v_add_u32_e32 v247, 0xc00, v247
	v_bfe_u32 v250, v21, 16, 1
	v_bfe_u32 v251, v5, 16, 1
	v_add3_u32 v250, v21, v250, s13
	v_add3_u32 v251, v5, v251, s13
	global_store_short_d16_hi v247, v250, s[8:9]
	global_store_short_d16_hi v247, v251, s[8:9] offset:64
	v_add_u32_e32 v247, 0xc00, v247
	v_bfe_u32 v248, v22, 16, 1
	v_bfe_u32 v249, v6, 16, 1
	v_add3_u32 v248, v22, v248, s13
	v_add3_u32 v249, v6, v249, s13
	global_store_short_d16_hi v247, v248, s[8:9]
	global_store_short_d16_hi v247, v249, s[8:9] offset:64
	v_add_u32_e32 v247, 0xc00, v247
	v_bfe_u32 v250, v23, 16, 1
	v_bfe_u32 v251, v7, 16, 1
	v_add3_u32 v250, v23, v250, s13
	v_add3_u32 v251, v7, v251, s13
	global_store_short_d16_hi v247, v250, s[8:9]
	global_store_short_d16_hi v247, v251, s[8:9] offset:64
	v_add_u32_e32 v247, 0x3c00, v247
	v_bfe_u32 v248, v24, 16, 1
	v_bfe_u32 v249, v8, 16, 1
	v_add3_u32 v248, v24, v248, s13
	v_add3_u32 v249, v8, v249, s13
	global_store_short_d16_hi v247, v248, s[8:9]
	global_store_short_d16_hi v247, v249, s[8:9] offset:64
	v_add_u32_e32 v247, 0xc00, v247
	v_bfe_u32 v250, v25, 16, 1
	v_bfe_u32 v251, v9, 16, 1
	v_add3_u32 v250, v25, v250, s13
	v_add3_u32 v251, v9, v251, s13
	global_store_short_d16_hi v247, v250, s[8:9]
	global_store_short_d16_hi v247, v251, s[8:9] offset:64
	v_add_u32_e32 v247, 0xc00, v247
	v_bfe_u32 v248, v26, 16, 1
	v_bfe_u32 v249, v10, 16, 1
	v_add3_u32 v248, v26, v248, s13
	v_add3_u32 v249, v10, v249, s13
	global_store_short_d16_hi v247, v248, s[8:9]
	global_store_short_d16_hi v247, v249, s[8:9] offset:64
	v_add_u32_e32 v247, 0xc00, v247
	v_bfe_u32 v250, v27, 16, 1
	v_bfe_u32 v251, v11, 16, 1
	v_add3_u32 v250, v27, v250, s13
	v_add3_u32 v251, v11, v251, s13
	global_store_short_d16_hi v247, v250, s[8:9]
	global_store_short_d16_hi v247, v251, s[8:9] offset:64
	v_add_u32_e32 v247, 0x3c00, v247
	v_bfe_u32 v248, v28, 16, 1
	v_bfe_u32 v249, v12, 16, 1
	v_add3_u32 v248, v28, v248, s13
	v_add3_u32 v249, v12, v249, s13
	global_store_short_d16_hi v247, v248, s[8:9]
	global_store_short_d16_hi v247, v249, s[8:9] offset:64
	v_add_u32_e32 v247, 0xc00, v247
	v_bfe_u32 v250, v29, 16, 1
	v_bfe_u32 v251, v13, 16, 1
	v_add3_u32 v250, v29, v250, s13
	v_add3_u32 v251, v13, v251, s13
	global_store_short_d16_hi v247, v250, s[8:9]
	global_store_short_d16_hi v247, v251, s[8:9] offset:64
	v_add_u32_e32 v247, 0xc00, v247
	v_bfe_u32 v248, v30, 16, 1
	v_bfe_u32 v249, v14, 16, 1
	v_add3_u32 v248, v30, v248, s13
	v_add3_u32 v249, v14, v249, s13
	global_store_short_d16_hi v247, v248, s[8:9]
	global_store_short_d16_hi v247, v249, s[8:9] offset:64
	v_add_u32_e32 v247, 0xc00, v247
	v_bfe_u32 v250, v31, 16, 1
	v_bfe_u32 v251, v15, 16, 1
	v_add3_u32 v250, v31, v250, s13
	v_add3_u32 v251, v15, v251, s13
	global_store_short_d16_hi v247, v250, s[8:9]
	global_store_short_d16_hi v247, v251, s[8:9] offset:64
	s_branch .LBB0_193

; DI float bf2f(bf16_t b) { return __uint_as_float(((unsigned)b) << 16); }
; template <bool PASS2>
; DI void rwkv_item(const Params& p, int l, int item, int lane, const bf16_t* rkv, const bf16_t* lo2, float* rwst) {
;   const int b = item / (8 * NCHR), head = (item / NCHR) % 8, c = item % NCHR;
;   const int ch = head * 64 + lane;
;   const float mu_r = p.in[I_RW_MU_RKV][(size_t)l * 1536 + ch], mu_k = p.in[I_RW_MU_RKV][(size_t)l * 1536 + 512 + ch];
;   const float kkw = p.in[I_RW_K_K][l * 512 + ch], kaw = p.in[I_RW_K_A][l * 512 + ch];
;   const float rkw = p.in[I_RW_R_K][l * 512 + ch];
;   const float gnw = p.in[I_RW_GN_W][l * 512 + ch], gnb = p.in[I_RW_GN_B][l * 512 + ch];
;   const size_t tok0 = (size_t)b * SEQ + (size_t)c * LCR;
;   float* stS = rwst + ((size_t)((b * 8 + head) * NCHR + c)) * 4096;
;   float* stP = (float*)p.yc + ((size_t)((b * 8 + head) * NCHR + c)) * 4096;
;   float S[64], P[64];
; #pragma unroll
;   for (int j = 0; j < 64; j++) { S[j] = 0.f; P[j] = (j == lane) ? 1.f : 0.f; }
;   if (PASS2 && c > 0) {
;     const float4* sp = (const float4*)(stS - 4096 + lane * 64);
; #pragma unroll
;     for (int j = 0; j < 16; j++) { float4 v = sp[j]; S[4 * j] = v.x; S[4 * j + 1] = v.y; S[4 * j + 2] = v.z; S[4 * j + 3] = v.w; }
;   }
;   float rp_prev = 0.f, kp_prev = 0.f;
;   if (c > 0) { rp_prev = bf2f(rkv[(tok0 - 1) * 1536 + ch]); kp_prev = bf2f(rkv[(tok0 - 1) * 1536 + 512 + ch]); }
.LBB0_1157:
	s_or_b64 exec, exec, s[0:1]
	s_add_u32 s0, s60, 0xd558000
	s_addc_u32 s1, s61, 0
	s_waitcnt lgkmcnt(0)
	v_mov_b32_e32 v0, v210
	v_mov_b32_e32 v1, v210
	v_writelane_b32 v255, s0, 42
	s_barrier
	s_nop 0
	v_writelane_b32 v255, s1, 43
	v_bfe_u32 v1, v1, 6, 2
	v_readlane_b32 s0, v252, 1
	v_readlane_b32 s1, v252, 2
	s_nop 0
	v_mul_lo_u32 v1, v1, s0
	v_readlane_b32 s0, v252, 26
	s_nop 1
	v_add_u32_e32 v201, s0, v1
	s_movk_i32 s0, 0x800
	v_cmp_gt_i32_e32 vcc, s0, v201
	s_and_saveexec_b64 s[0:1], vcc
	s_cbranch_execz .LBB0_1168
	v_and_b32_e32 v0, 63, v210
	v_lshrrev_b32_e32 v1, 6, v210
	v_and_b32_e32 v1, 3, v1
	v_lshlrev_b32_e32 v1, 10, v1
	v_lshrrev_b32_e32 v2, 5, v0
	v_lshl_add_u32 v2, v2, 4, v1
	v_lshl_add_u32 v1, v0, 2, v1
	v_readlane_b32 s36, v252, 3
	v_readlane_b32 s37, v252, 4
	v_readlane_b32 s17, v252, 1
	v_readfirstlane_b32 s16, v201
	s_sub_u32 s36, s36, 0x180
	s_subb_u32 s37, s37, 0
	s_lshl_b32 s17, s17, 2
	s_load_dwordx2 s[2:3], s[36:37], 0x170
	s_load_dwordx2 s[12:13], s[36:37], 0x68
	s_load_dwordx2 s[14:15], s[36:37], 0xb8
	s_load_dwordx2 s[34:35], s[36:37], 0xc0
	s_waitcnt lgkmcnt(0)
.Lrwp1a_item:
	s_lshr_b32 s19, s16, 10
	s_bfe_u32 s20, s16, 0x30007
	s_and_b32 s21, s16, 127
	s_lshl_b32 s22, s19, 14
	s_lshl_b32 s23, s21, 7
	s_add_u32 s22, s22, s23
	v_lshl_add_u32 v3, s20, 6, v0
	v_lshlrev_b32_e32 v4, 2, v3
	v_lshlrev_b32_e32 v232, 1, v3
	s_add_u32 s28, s12, 0x800
	s_addc_u32 s29, s13, 0
	global_load_dword v10, v4, s[28:29]
	s_add_u32 s28, s14, 0x0
	s_addc_u32 s29, s15, 0
	global_load_dword v11, v4, s[28:29]
	s_add_u32 s28, s34, 0x0
	s_addc_u32 s29, s35, 0
	global_load_dword v12, v4, s[28:29]
	s_add_u32 s4, s2, 0x17558000
	s_addc_u32 s5, s3, 0
	s_add_u32 s6, s2, 0x3558000
	s_addc_u32 s7, s3, 0
	s_add_u32 s8, s2, 0x11558000
	s_addc_u32 s9, s3, 0
	s_add_u32 s10, s2, 0x13558000
	s_addc_u32 s11, s3, 0
	s_lshl_b32 s23, s19, 3
	s_add_u32 s23, s23, s20
	s_lshl_b32 s23, s23, 7
	s_add_u32 s23, s23, s21
	s_lshr_b32 s25, s23, 18
	s_lshl_b32 s24, s23, 14
	s_add_u32 s24, s24, s2
	s_addc_u32 s25, s25, s3
	s_add_u32 s24, s24, 0x1d558000
	s_addc_u32 s25, s25, 0
	s_add_u32 s26, s24, 0x2000
	s_addc_u32 s27, s25, 0
	s_lshr_b32 s41, s23, 18
	s_lshl_b32 s40, s23, 14
	s_add_u32 s40, s40, s2
	s_addc_u32 s41, s41, s3
	s_add_u32 s40, s40, 0xd558000
	s_addc_u32 s41, s41, 0
	s_add_u32 s38, s40, 0x2000
	s_addc_u32 s39, s41, 0
	v_and_b32_e32 v5, 63, v210
	v_and_b32_e32 v6, 31, v5
	v_lshrrev_b32_e32 v7, 5, v5
	v_lshlrev_b32_e32 v26, 8, v6
	v_lshl_add_u32 v26, v7, 4, v26
	s_mul_i32 s28, s22, 0xc00
	s_lshl_b32 s29, s22, 10
	s_waitcnt vmcnt(0)
	v_lshlrev_b32_e32 v27, 2, v7
	v_sub_u32_e32 v27, v6, v27
	v_add_u32_e32 v3, s28, v232
	v_add_u32_e32 v4, s29, v232
	v_mov_b32_e32 v6, 0
	v_mov_b32_e32 v7, 0
	s_cmp_eq_u32 s21, 0
	s_cbranch_scc1 .Lrwp1a_noprev
	global_load_ushort v7, v3, s[4:5] offset:-2048
.Lrwp1a_noprev:
	v_mov_b32_e32 v64, 0
	v_cmp_eq_u32_e64 s[28:29], 0, v27
	s_nop 1
	v_cndmask_b32_e64 v128, 0, 1.0, s[28:29]
	v_mov_b32_e32 v65, 0
	v_cmp_eq_u32_e64 s[28:29], 1, v27
	s_nop 1
	v_cndmask_b32_e64 v129, 0, 1.0, s[28:29]
	v_mov_b32_e32 v66, 0
	v_cmp_eq_u32_e64 s[28:29], 2, v27
	s_nop 1
	v_cndmask_b32_e64 v130, 0, 1.0, s[28:29]
	v_mov_b32_e32 v67, 0
	v_cmp_eq_u32_e64 s[28:29], 3, v27
	s_nop 1
	v_cndmask_b32_e64 v131, 0, 1.0, s[28:29]
	v_mov_b32_e32 v68, 0
	v_cmp_eq_u32_e64 s[28:29], 8, v27
	s_nop 1
	v_cndmask_b32_e64 v132, 0, 1.0, s[28:29]
	v_mov_b32_e32 v69, 0
	v_cmp_eq_u32_e64 s[28:29], 9, v27
	s_nop 1
	v_cndmask_b32_e64 v133, 0, 1.0, s[28:29]
	v_mov_b32_e32 v70, 0
	v_cmp_eq_u32_e64 s[28:29], 10, v27
	s_nop 1
	v_cndmask_b32_e64 v134, 0, 1.0, s[28:29]
	v_mov_b32_e32 v71, 0
	v_cmp_eq_u32_e64 s[28:29], 11, v27
	s_nop 1
	v_cndmask_b32_e64 v135, 0, 1.0, s[28:29]
	v_mov_b32_e32 v72, 0
	v_cmp_eq_u32_e64 s[28:29], 16, v27
	s_nop 1
	v_cndmask_b32_e64 v136, 0, 1.0, s[28:29]
	v_mov_b32_e32 v73, 0
	v_cmp_eq_u32_e64 s[28:29], 17, v27
	s_nop 1
	v_cndmask_b32_e64 v137, 0, 1.0, s[28:29]
	v_mov_b32_e32 v74, 0
	v_cmp_eq_u32_e64 s[28:29], 18, v27
	s_nop 1
	v_cndmask_b32_e64 v138, 0, 1.0, s[28:29]
	v_mov_b32_e32 v75, 0
	v_cmp_eq_u32_e64 s[28:29], 19, v27
	s_nop 1
	v_cndmask_b32_e64 v139, 0, 1.0, s[28:29]
	v_mov_b32_e32 v76, 0
	v_cmp_eq_u32_e64 s[28:29], 24, v27
	s_nop 1
	v_cndmask_b32_e64 v140, 0, 1.0, s[28:29]
	v_mov_b32_e32 v77, 0
	v_cmp_eq_u32_e64 s[28:29], 25, v27
	s_nop 1
	v_cndmask_b32_e64 v141, 0, 1.0, s[28:29]
	v_mov_b32_e32 v78, 0
	v_cmp_eq_u32_e64 s[28:29], 26, v27
	s_nop 1
	v_cndmask_b32_e64 v142, 0, 1.0, s[28:29]
	v_mov_b32_e32 v79, 0
	v_cmp_eq_u32_e64 s[28:29], 27, v27
	s_nop 1
	v_cndmask_b32_e64 v143, 0, 1.0, s[28:29]
	v_mov_b32_e32 v80, 0
	v_mov_b32_e32 v144, 0
	v_mov_b32_e32 v81, 0
	v_mov_b32_e32 v145, 0
	v_mov_b32_e32 v82, 0
	v_mov_b32_e32 v146, 0
	v_mov_b32_e32 v83, 0
	v_mov_b32_e32 v147, 0
	v_mov_b32_e32 v84, 0
	v_mov_b32_e32 v148, 0
	v_mov_b32_e32 v85, 0
	v_mov_b32_e32 v149, 0
	v_mov_b32_e32 v86, 0
	v_mov_b32_e32 v150, 0
	v_mov_b32_e32 v87, 0
	v_mov_b32_e32 v151, 0
	v_mov_b32_e32 v88, 0
	v_mov_b32_e32 v152, 0
	v_mov_b32_e32 v89, 0
	v_mov_b32_e32 v153, 0
	v_mov_b32_e32 v90, 0
	v_mov_b32_e32 v154, 0
	v_mov_b32_e32 v91, 0
	v_mov_b32_e32 v155, 0
	v_mov_b32_e32 v92, 0
	v_mov_b32_e32 v156, 0
	v_mov_b32_e32 v93, 0
	v_mov_b32_e32 v157, 0
	v_mov_b32_e32 v94, 0
	v_mov_b32_e32 v158, 0
	v_mov_b32_e32 v95, 0
	v_mov_b32_e32 v159, 0
	v_mov_b32_e32 v96, 0
	v_mov_b32_e32 v160, 0
	v_mov_b32_e32 v97, 0
	v_mov_b32_e32 v161, 0
	v_mov_b32_e32 v98, 0
	v_mov_b32_e32 v162, 0
	v_mov_b32_e32 v99, 0
	v_mov_b32_e32 v163, 0
	v_mov_b32_e32 v100, 0
	v_mov_b32_e32 v164, 0
	v_mov_b32_e32 v101, 0
	v_mov_b32_e32 v165, 0
	v_mov_b32_e32 v102, 0
	v_mov_b32_e32 v166, 0
	v_mov_b32_e32 v103, 0
; DI float bf2f(bf16_t b) { return __uint_as_float(((unsigned)b) << 16); }
; DI float rl(float x, int l) { return __int_as_float(__builtin_amdgcn_readlane(__float_as_int(x), l)); }
; template <bool PASS2>
; DI void rwkv_item(const Params& p, int l, int item, int lane, const bf16_t* rkv, const bf16_t* lo2, float* rwst) {
;     ...
;   auto load_raw = [&](size_t tk) __attribute__((always_inline)) {
;     Raw x;
;     x.rp = rkv[tk * 1536 + ch]; x.kp = rkv[tk * 1536 + 512 + ch]; x.v = p.vbuf[tk * 512 + ch];
;     x.ew = ewb[tk * 512 + ch]; x.a = ab[tk * 512 + ch]; x.g = PASS2 ? gb[tk * 512 + ch] : (bf16_t)0;
;     return x;
;   };
;   auto derive = [&](const Raw& x, float rpp, float kpp) __attribute__((always_inline)) {
;     Der d;
;     const float rp = bf2f(x.rp), kp = bf2f(x.kp), a = bf2f(x.a);
;     d.rr = rp + (rpp - rp) * mu_r;
;     const float k = kp + (kpp - kp) * mu_k;
;     d.wdec = __expf(-bf2f(x.ew));
;     float kkv = k * kkw;
;     const float nrm = wave_sum(kkv * kkv);
;     kkv *= rsqrtf(fmaxf(nrm, 1e-24f));
;     d.kf = k * (1.f + (a - 1.f) * kaw);
;     d.av = -kkv; d.bv = kkv * a;
;     d.v = bf2f(x.v); d.gg = bf2f(x.g);
;     return d;
;   };
;   Raw rawB = load_raw(tok0);
;   Der cur = derive(rawB, rp_prev, kp_prev);
;   float rpA = bf2f(rawB.rp), kpA = bf2f(rawB.kp);
;   rawB = load_raw(tok0 + 1);
; #pragma unroll 1
;   for (int t = 0; t < LCR; t++) {
;     Raw rawC = rawB;
;     if (t + 2 < LCR) rawC = load_raw(tok0 + t + 2);
;     Der nxt = cur;
;     if (t + 1 < LCR) nxt = derive(rawB, rpA, kpA);
;     const float rr = cur.rr, wdec = cur.wdec, kf = cur.kf, av = cur.av, bv = cur.bv, v = cur.v, gg = cur.gg;
;     float sa0 = 0.f, sa1 = 0.f, pa0 = 0.f, pa1 = 0.f;
; #pragma unroll
;     for (int j = 0; j < 64; j += 2) {
;       const float a0 = rl(av, j), a1 = rl(av, j + 1);
;       sa0 += S[j] * a0; sa1 += S[j + 1] * a1;
;       if (!PASS2) { pa0 += P[j] * a0; pa1 += P[j + 1] * a1; }
;     }
;     const float sa = sa0 + sa1, pa = pa0 + pa1;
	v_mov_b32_e32 v167, 0
	v_mov_b32_e32 v104, 0
	v_mov_b32_e32 v168, 0
	v_mov_b32_e32 v105, 0
	v_mov_b32_e32 v169, 0
	v_mov_b32_e32 v106, 0
	v_mov_b32_e32 v170, 0
	v_mov_b32_e32 v107, 0
	v_mov_b32_e32 v171, 0
	v_mov_b32_e32 v108, 0
	v_mov_b32_e32 v172, 0
	v_mov_b32_e32 v109, 0
	v_mov_b32_e32 v173, 0
	v_mov_b32_e32 v110, 0
	v_mov_b32_e32 v174, 0
	v_mov_b32_e32 v111, 0
	v_mov_b32_e32 v175, 0
	v_mov_b32_e32 v112, 0
	v_cmp_eq_u32_e64 s[28:29], 0, v27
	s_nop 1
	v_cndmask_b32_e64 v176, 0, 1.0, s[28:29]
	v_mov_b32_e32 v113, 0
	v_cmp_eq_u32_e64 s[28:29], 1, v27
	s_nop 1
	v_cndmask_b32_e64 v177, 0, 1.0, s[28:29]
	v_mov_b32_e32 v114, 0
	v_cmp_eq_u32_e64 s[28:29], 2, v27
	s_nop 1
	v_cndmask_b32_e64 v178, 0, 1.0, s[28:29]
	v_mov_b32_e32 v115, 0
	v_cmp_eq_u32_e64 s[28:29], 3, v27
	s_nop 1
	v_cndmask_b32_e64 v179, 0, 1.0, s[28:29]
	v_mov_b32_e32 v116, 0
	v_cmp_eq_u32_e64 s[28:29], 8, v27
	s_nop 1
	v_cndmask_b32_e64 v180, 0, 1.0, s[28:29]
	v_mov_b32_e32 v117, 0
	v_cmp_eq_u32_e64 s[28:29], 9, v27
	s_nop 1
	v_cndmask_b32_e64 v181, 0, 1.0, s[28:29]
	v_mov_b32_e32 v118, 0
	v_cmp_eq_u32_e64 s[28:29], 10, v27
	s_nop 1
	v_cndmask_b32_e64 v182, 0, 1.0, s[28:29]
	v_mov_b32_e32 v119, 0
	v_cmp_eq_u32_e64 s[28:29], 11, v27
	s_nop 1
	v_cndmask_b32_e64 v183, 0, 1.0, s[28:29]
	v_mov_b32_e32 v120, 0
	v_cmp_eq_u32_e64 s[28:29], 16, v27
	s_nop 1
	v_cndmask_b32_e64 v184, 0, 1.0, s[28:29]
	v_mov_b32_e32 v121, 0
	v_cmp_eq_u32_e64 s[28:29], 17, v27
	s_nop 1
	v_cndmask_b32_e64 v185, 0, 1.0, s[28:29]
	v_mov_b32_e32 v122, 0
	v_cmp_eq_u32_e64 s[28:29], 18, v27
	s_nop 1
	v_cndmask_b32_e64 v186, 0, 1.0, s[28:29]
	v_mov_b32_e32 v123, 0
	v_cmp_eq_u32_e64 s[28:29], 19, v27
	s_nop 1
	v_cndmask_b32_e64 v187, 0, 1.0, s[28:29]
	v_mov_b32_e32 v124, 0
	v_cmp_eq_u32_e64 s[28:29], 24, v27
	s_nop 1
	v_cndmask_b32_e64 v188, 0, 1.0, s[28:29]
	v_mov_b32_e32 v125, 0
	v_cmp_eq_u32_e64 s[28:29], 25, v27
	s_nop 1
	v_cndmask_b32_e64 v189, 0, 1.0, s[28:29]
	v_mov_b32_e32 v126, 0
	v_cmp_eq_u32_e64 s[28:29], 26, v27
	s_nop 1
	v_cndmask_b32_e64 v190, 0, 1.0, s[28:29]
	v_mov_b32_e32 v127, 0
	v_cmp_eq_u32_e64 s[28:29], 27, v27
	s_nop 1
	v_cndmask_b32_e64 v191, 0, 1.0, s[28:29]
	global_load_ushort v192, v3, s[4:5] offset:1024
	global_load_ushort v193, v4, s[6:7]
	global_load_ushort v194, v4, s[8:9]
	global_load_ushort v195, v4, s[10:11]
	v_add_u32_e32 v3, 0xc00, v3
	v_add_u32_e32 v4, 0x400, v4
	global_load_ushort v196, v3, s[4:5] offset:1024
	global_load_ushort v197, v4, s[6:7]
	global_load_ushort v198, v4, s[8:9]
	global_load_ushort v199, v4, s[10:11]
	v_add_u32_e32 v3, 0xc00, v3
	v_add_u32_e32 v4, 0x400, v4
	global_load_ushort v200, v3, s[4:5] offset:1024
	global_load_ushort v201, v4, s[6:7]
	global_load_ushort v202, v4, s[8:9]
	global_load_ushort v203, v4, s[10:11]
	v_add_u32_e32 v3, 0xc00, v3
	v_add_u32_e32 v4, 0x400, v4
	global_load_ushort v204, v3, s[4:5] offset:1024
	global_load_ushort v205, v4, s[6:7]
	global_load_ushort v206, v4, s[8:9]
	global_load_ushort v207, v4, s[10:11]
	v_add_u32_e32 v3, 0xc00, v3
	v_add_u32_e32 v4, 0x400, v4
	s_waitcnt vmcnt(0)
	v_lshlrev_b32_e32 v6, 16, v6
	v_lshlrev_b32_e32 v7, 16, v7
	v_mov_b32_e32 v8, 1.0
	s_movk_i32 s36, 0x7fff
	v_lshlrev_b32_e32 v27, 16, v192
	v_sub_f32_e32 v29, v7, v27
	v_fma_f32 v29, v29, v10, v27
	v_mov_b32_e32 v7, v27
	v_lshlrev_b32_e32 v30, 16, v194
	v_mul_f32_e32 v30, 0xbfb8aa3b, v30
	v_exp_f32_e32 v30, v30
	v_lshlrev_b32_e32 v31, 16, v195
	v_mul_f32_e32 v211, v29, v11
	v_add_f32_e32 v212, -1.0, v31
	v_fma_f32 v212, v212, v12, 1.0
	v_mul_f32_e32 v212, v29, v212
	v_mul_f32_e32 v213, v211, v211
	v_mov_b32_e32 v214, 0
	v_lshlrev_b32_e32 v20, 16, v193
	s_nop 1
	v_permlane32_swap_b32 v213, v214
	s_nop 0
	v_add_f32_e32 v213, v213, v214
	s_nop 1
	v_add_f32_dpp v213, v213, v213 quad_perm:[1,0,3,2] row_mask:0xf bank_mask:0xf
	s_nop 1
	v_add_f32_dpp v213, v213, v213 quad_perm:[2,3,0,1] row_mask:0xf bank_mask:0xf
	s_nop 1
	v_add_f32_dpp v213, v213, v213 row_half_mirror row_mask:0xf bank_mask:0xf
	s_nop 1
	v_add_f32_dpp v213, v213, v213 row_mirror row_mask:0xf bank_mask:0xf
	s_nop 1
	v_add_f32_dpp v213, v213, v213 row_bcast:15 row_mask:0xa bank_mask:0xf
	s_nop 1
	v_readlane_b32 s28, v213, 31
	v_readlane_b32 s30, v213, 63
	s_nop 1
	v_mov_b32_e32 v215, s28
	v_max_f32_e32 v215, 0x179abe15, v215
	v_rsq_f32_e32 v215, v215
	v_mov_b32_e32 v19, v20
	v_mul_f32_e32 v211, v211, v215
	v_mul_f32_e64 v24, -v211, v8
	v_mul_f32_e32 v216, v211, v31
	v_mul_f32_e32 v8, v8, v30
	v_rcp_f32_e32 v217, v8
	s_nop 0
	v_mul_f32_e32 v16, v216, v217
	v_mul_f32_e32 v17, v212, v217
	s_nop 1
	v_permlane32_swap_b32 v16, v17
	ds_write_b32 v1, v24
	ds_read_b128 v[32:35], v2 offset:0
	ds_read_b128 v[36:39], v2 offset:32
	ds_read_b128 v[40:43], v2 offset:64
	ds_read_b128 v[44:47], v2 offset:96
	ds_read_b128 v[48:51], v2 offset:128
	ds_read_b128 v[52:55], v2 offset:160
	ds_read_b128 v[56:59], v2 offset:192
	ds_read_b128 v[60:63], v2 offset:224
	s_waitcnt lgkmcnt(7)
	v_pk_mul_f32 v[220:221], v[64:65], v[32:33]
	v_pk_mul_f32 v[224:225], v[128:129], v[32:33]
	v_pk_mul_f32 v[222:223], v[80:81], v[32:33]
	v_pk_mul_f32 v[226:227], v[144:145], v[32:33]
	v_pk_fma_f32 v[220:221], v[66:67], v[34:35], v[220:221]
	v_pk_fma_f32 v[224:225], v[130:131], v[34:35], v[224:225]
	v_pk_fma_f32 v[222:223], v[82:83], v[34:35], v[222:223]
	v_pk_fma_f32 v[226:227], v[146:147], v[34:35], v[226:227]
	s_waitcnt lgkmcnt(6)
	v_pk_fma_f32 v[220:221], v[68:69], v[36:37], v[220:221]
	v_pk_fma_f32 v[224:225], v[132:133], v[36:37], v[224:225]
	v_pk_fma_f32 v[222:223], v[84:85], v[36:37], v[222:223]
	v_pk_fma_f32 v[226:227], v[148:149], v[36:37], v[226:227]
	v_pk_fma_f32 v[220:221], v[70:71], v[38:39], v[220:221]
	v_pk_fma_f32 v[224:225], v[134:135], v[38:39], v[224:225]
	v_pk_fma_f32 v[222:223], v[86:87], v[38:39], v[222:223]
	v_pk_fma_f32 v[226:227], v[150:151], v[38:39], v[226:227]
	s_waitcnt lgkmcnt(5)
; DI float rl(float x, int l) { return __int_as_float(__builtin_amdgcn_readlane(__float_as_int(x), l)); }
; template <bool PASS2>
; DI void rwkv_item(const Params& p, int l, int item, int lane, const bf16_t* rkv, const bf16_t* lo2, float* rwst) {
;     ...
;   for (int t = 0; t < LCR; t++) {
;     Raw rawC = rawB;
;     if (t + 2 < LCR) rawC = load_raw(tok0 + t + 2);
;     Der nxt = cur;
;     if (t + 1 < LCR) nxt = derive(rawB, rpA, kpA);
;     const float rr = cur.rr, wdec = cur.wdec, kf = cur.kf, av = cur.av, bv = cur.bv, v = cur.v, gg = cur.gg;
;     float sa0 = 0.f, sa1 = 0.f, pa0 = 0.f, pa1 = 0.f;
; #pragma unroll
;     for (int j = 0; j < 64; j += 2) {
;       const float a0 = rl(av, j), a1 = rl(av, j + 1);
;       sa0 += S[j] * a0; sa1 += S[j + 1] * a1;
;       if (!PASS2) { pa0 += P[j] * a0; pa1 += P[j + 1] * a1; }
;     }
;     const float sa = sa0 + sa1, pa = pa0 + pa1;
;     float y0 = 0.f, y1 = 0.f;
; #pragma unroll
;     for (int j = 0; j < 64; j += 2) {
;       const float w0 = rl(wdec, j), b0 = rl(bv, j), k0 = rl(kf, j);
;       const float w1 = rl(wdec, j + 1), b1 = rl(bv, j + 1), k1 = rl(kf, j + 1);
;       S[j] = S[j] * w0 + sa * b0 + v * k0;
;       S[j + 1] = S[j + 1] * w1 + sa * b1 + v * k1;
;       if (!PASS2) {
;         P[j] = P[j] * w0 + pa * b0;
;         P[j + 1] = P[j + 1] * w1 + pa * b1;
	v_pk_fma_f32 v[220:221], v[72:73], v[40:41], v[220:221]
	v_pk_fma_f32 v[224:225], v[136:137], v[40:41], v[224:225]
	v_pk_fma_f32 v[222:223], v[88:89], v[40:41], v[222:223]
	v_pk_fma_f32 v[226:227], v[152:153], v[40:41], v[226:227]
	v_pk_fma_f32 v[220:221], v[74:75], v[42:43], v[220:221]
	v_pk_fma_f32 v[224:225], v[138:139], v[42:43], v[224:225]
	v_pk_fma_f32 v[222:223], v[90:91], v[42:43], v[222:223]
	v_pk_fma_f32 v[226:227], v[154:155], v[42:43], v[226:227]
	s_waitcnt lgkmcnt(4)
	v_pk_fma_f32 v[220:221], v[76:77], v[44:45], v[220:221]
	v_pk_fma_f32 v[224:225], v[140:141], v[44:45], v[224:225]
	v_pk_fma_f32 v[222:223], v[92:93], v[44:45], v[222:223]
	v_pk_fma_f32 v[226:227], v[156:157], v[44:45], v[226:227]
	v_pk_fma_f32 v[220:221], v[78:79], v[46:47], v[220:221]
	v_pk_fma_f32 v[224:225], v[142:143], v[46:47], v[224:225]
	v_pk_fma_f32 v[222:223], v[94:95], v[46:47], v[222:223]
	v_pk_fma_f32 v[226:227], v[158:159], v[46:47], v[226:227]
	s_waitcnt lgkmcnt(3)
	v_pk_fma_f32 v[220:221], v[96:97], v[48:49], v[220:221]
	v_pk_fma_f32 v[224:225], v[160:161], v[48:49], v[224:225]
	v_pk_fma_f32 v[222:223], v[112:113], v[48:49], v[222:223]
	v_pk_fma_f32 v[226:227], v[176:177], v[48:49], v[226:227]
	v_pk_fma_f32 v[220:221], v[98:99], v[50:51], v[220:221]
	v_pk_fma_f32 v[224:225], v[162:163], v[50:51], v[224:225]
	v_pk_fma_f32 v[222:223], v[114:115], v[50:51], v[222:223]
	v_pk_fma_f32 v[226:227], v[178:179], v[50:51], v[226:227]
	s_waitcnt lgkmcnt(2)
	v_pk_fma_f32 v[220:221], v[100:101], v[52:53], v[220:221]
	v_pk_fma_f32 v[224:225], v[164:165], v[52:53], v[224:225]
	v_pk_fma_f32 v[222:223], v[116:117], v[52:53], v[222:223]
	v_pk_fma_f32 v[226:227], v[180:181], v[52:53], v[226:227]
	v_pk_fma_f32 v[220:221], v[102:103], v[54:55], v[220:221]
	v_pk_fma_f32 v[224:225], v[166:167], v[54:55], v[224:225]
	v_pk_fma_f32 v[222:223], v[118:119], v[54:55], v[222:223]
	v_pk_fma_f32 v[226:227], v[182:183], v[54:55], v[226:227]
	s_waitcnt lgkmcnt(1)
	v_pk_fma_f32 v[220:221], v[104:105], v[56:57], v[220:221]
	v_pk_fma_f32 v[224:225], v[168:169], v[56:57], v[224:225]
	v_pk_fma_f32 v[222:223], v[120:121], v[56:57], v[222:223]
	v_pk_fma_f32 v[226:227], v[184:185], v[56:57], v[226:227]
	v_pk_fma_f32 v[220:221], v[106:107], v[58:59], v[220:221]
	v_pk_fma_f32 v[224:225], v[170:171], v[58:59], v[224:225]
	v_pk_fma_f32 v[222:223], v[122:123], v[58:59], v[222:223]
	v_pk_fma_f32 v[226:227], v[186:187], v[58:59], v[226:227]
	s_waitcnt lgkmcnt(0)
	v_pk_fma_f32 v[220:221], v[108:109], v[60:61], v[220:221]
	v_pk_fma_f32 v[224:225], v[172:173], v[60:61], v[224:225]
	v_pk_fma_f32 v[222:223], v[124:125], v[60:61], v[222:223]
	v_pk_fma_f32 v[226:227], v[188:189], v[60:61], v[226:227]
	v_pk_fma_f32 v[220:221], v[110:111], v[62:63], v[220:221]
	v_pk_fma_f32 v[224:225], v[174:175], v[62:63], v[224:225]
	v_pk_fma_f32 v[222:223], v[126:127], v[62:63], v[222:223]
	v_pk_fma_f32 v[226:227], v[190:191], v[62:63], v[226:227]
	v_add_f32_e32 v18, v220, v221
	v_add_f32_e32 v228, v222, v223
	s_nop 1
	v_permlane32_swap_b32 v18, v228
	s_nop 0
	v_add_f32_e32 v18, v18, v228
	v_add_f32_e32 v229, v224, v225
	v_add_f32_e32 v230, v226, v227
	s_nop 1
	v_permlane32_swap_b32 v229, v230
	s_nop 0
	v_add_f32_e32 v229, v229, v230
	s_mov_b32 s18, 0
.Lrwp1a_loop:
	s_nop 1
	v_permlane32_swap_b32 v18, v19
	v_mov_b32_e32 v231, 0
	s_nop 1
	v_permlane32_swap_b32 v229, v231
	s_nop 1
	v_mfma_f32_32x32x2_f32 v[64:79], v16, v18, v[64:79]
	v_mfma_f32_32x32x2_f32 v[80:95], v16, v19, v[80:95]
	v_mfma_f32_32x32x2_f32 v[96:111], v17, v18, v[96:111]
	v_mfma_f32_32x32x2_f32 v[112:127], v17, v19, v[112:127]
	v_mfma_f32_32x32x2_f32 v[128:143], v16, v229, v[128:143]
	v_mfma_f32_32x32x2_f32 v[144:159], v16, v231, v[144:159]
	v_mfma_f32_32x32x2_f32 v[160:175], v17, v229, v[160:175]
	v_mfma_f32_32x32x2_f32 v[176:191], v17, v231, v[176:191]
	global_load_ushort v192, v3, s[4:5] offset:1024
	global_load_ushort v193, v4, s[6:7]
	global_load_ushort v194, v4, s[8:9]
	global_load_ushort v195, v4, s[10:11]
	v_add_u32_e32 v3, 0xc00, v3
	v_add_u32_e32 v4, 0x400, v4
	s_waitcnt vmcnt(12)
	v_lshlrev_b32_e32 v27, 16, v196
	v_sub_f32_e32 v29, v7, v27
	v_fma_f32 v29, v29, v10, v27
	v_mov_b32_e32 v7, v27
	v_lshlrev_b32_e32 v30, 16, v198
	v_mul_f32_e32 v30, 0xbfb8aa3b, v30
	v_exp_f32_e32 v30, v30
	v_lshlrev_b32_e32 v31, 16, v199
	v_mul_f32_e32 v211, v29, v11
	v_add_f32_e32 v212, -1.0, v31
	v_fma_f32 v212, v212, v12, 1.0
	v_mul_f32_e32 v212, v29, v212
	v_mul_f32_e32 v213, v211, v211
	v_mov_b32_e32 v214, 0
	v_lshlrev_b32_e32 v21, 16, v197
	s_nop 1
	v_permlane32_swap_b32 v213, v214
	s_nop 0
	v_add_f32_e32 v213, v213, v214
	s_nop 1
	v_add_f32_dpp v213, v213, v213 quad_perm:[1,0,3,2] row_mask:0xf bank_mask:0xf
	s_nop 1
	v_add_f32_dpp v213, v213, v213 quad_perm:[2,3,0,1] row_mask:0xf bank_mask:0xf
	s_nop 1
	v_add_f32_dpp v213, v213, v213 row_half_mirror row_mask:0xf bank_mask:0xf
	s_nop 1
	v_add_f32_dpp v213, v213, v213 row_mirror row_mask:0xf bank_mask:0xf
	s_nop 1
	v_add_f32_dpp v213, v213, v213 row_bcast:15 row_mask:0xa bank_mask:0xf
	s_nop 1
	v_readlane_b32 s28, v213, 31
	v_readlane_b32 s31, v213, 63
	s_nop 1
	v_mov_b32_e32 v215, s28
	v_max_f32_e32 v215, 0x179abe15, v215
	v_rsq_f32_e32 v215, v215
	v_mov_b32_e32 v19, v21
	v_mul_f32_e32 v211, v211, v215
	v_mul_f32_e64 v24, -v211, v8
	v_mul_f32_e32 v216, v211, v31
	v_mul_f32_e32 v8, v8, v30
	v_rcp_f32_e32 v217, v8
	s_nop 0
	v_mul_f32_e32 v16, v216, v217
	v_mul_f32_e32 v17, v212, v217
	s_nop 1
	v_permlane32_swap_b32 v16, v17
	ds_write_b32 v1, v24
	ds_read_b128 v[32:35], v2 offset:0
	ds_read_b128 v[36:39], v2 offset:32
	ds_read_b128 v[40:43], v2 offset:64
	ds_read_b128 v[44:47], v2 offset:96
	ds_read_b128 v[48:51], v2 offset:128
	ds_read_b128 v[52:55], v2 offset:160
	ds_read_b128 v[56:59], v2 offset:192
	ds_read_b128 v[60:63], v2 offset:224
	s_waitcnt lgkmcnt(7)
; DI float rl(float x, int l) { return __int_as_float(__builtin_amdgcn_readlane(__float_as_int(x), l)); }
; template <bool PASS2>
; DI void rwkv_item(const Params& p, int l, int item, int lane, const bf16_t* rkv, const bf16_t* lo2, float* rwst) {
;     ...
;   for (int t = 0; t < LCR; t++) {
;     Raw rawC = rawB;
;     if (t + 2 < LCR) rawC = load_raw(tok0 + t + 2);
;     Der nxt = cur;
;     if (t + 1 < LCR) nxt = derive(rawB, rpA, kpA);
;     const float rr = cur.rr, wdec = cur.wdec, kf = cur.kf, av = cur.av, bv = cur.bv, v = cur.v, gg = cur.gg;
;     float sa0 = 0.f, sa1 = 0.f, pa0 = 0.f, pa1 = 0.f;
; #pragma unroll
;     for (int j = 0; j < 64; j += 2) {
;       const float a0 = rl(av, j), a1 = rl(av, j + 1);
;       sa0 += S[j] * a0; sa1 += S[j + 1] * a1;
;       if (!PASS2) { pa0 += P[j] * a0; pa1 += P[j + 1] * a1; }
;     }
;     const float sa = sa0 + sa1, pa = pa0 + pa1;
;     float y0 = 0.f, y1 = 0.f;
; #pragma unroll
;     for (int j = 0; j < 64; j += 2) {
;       const float w0 = rl(wdec, j), b0 = rl(bv, j), k0 = rl(kf, j);
;       const float w1 = rl(wdec, j + 1), b1 = rl(bv, j + 1), k1 = rl(kf, j + 1);
;       S[j] = S[j] * w0 + sa * b0 + v * k0;
;       S[j + 1] = S[j + 1] * w1 + sa * b1 + v * k1;
;       if (!PASS2) {
;         P[j] = P[j] * w0 + pa * b0;
;         P[j + 1] = P[j + 1] * w1 + pa * b1;
	v_pk_mul_f32 v[220:221], v[64:65], v[32:33]
	v_pk_mul_f32 v[224:225], v[128:129], v[32:33]
	v_pk_mul_f32 v[222:223], v[80:81], v[32:33]
	v_pk_mul_f32 v[226:227], v[144:145], v[32:33]
	v_pk_fma_f32 v[220:221], v[66:67], v[34:35], v[220:221]
	v_pk_fma_f32 v[224:225], v[130:131], v[34:35], v[224:225]
	v_pk_fma_f32 v[222:223], v[82:83], v[34:35], v[222:223]
	v_pk_fma_f32 v[226:227], v[146:147], v[34:35], v[226:227]
	s_waitcnt lgkmcnt(6)
	v_pk_fma_f32 v[220:221], v[68:69], v[36:37], v[220:221]
	v_pk_fma_f32 v[224:225], v[132:133], v[36:37], v[224:225]
	v_pk_fma_f32 v[222:223], v[84:85], v[36:37], v[222:223]
	v_pk_fma_f32 v[226:227], v[148:149], v[36:37], v[226:227]
	v_pk_fma_f32 v[220:221], v[70:71], v[38:39], v[220:221]
	v_pk_fma_f32 v[224:225], v[134:135], v[38:39], v[224:225]
	v_pk_fma_f32 v[222:223], v[86:87], v[38:39], v[222:223]
	v_pk_fma_f32 v[226:227], v[150:151], v[38:39], v[226:227]
	s_waitcnt lgkmcnt(5)
	v_pk_fma_f32 v[220:221], v[72:73], v[40:41], v[220:221]
	v_pk_fma_f32 v[224:225], v[136:137], v[40:41], v[224:225]
	v_pk_fma_f32 v[222:223], v[88:89], v[40:41], v[222:223]
	v_pk_fma_f32 v[226:227], v[152:153], v[40:41], v[226:227]
	v_pk_fma_f32 v[220:221], v[74:75], v[42:43], v[220:221]
	v_pk_fma_f32 v[224:225], v[138:139], v[42:43], v[224:225]
	v_pk_fma_f32 v[222:223], v[90:91], v[42:43], v[222:223]
	v_pk_fma_f32 v[226:227], v[154:155], v[42:43], v[226:227]
	s_waitcnt lgkmcnt(4)
	v_pk_fma_f32 v[220:221], v[76:77], v[44:45], v[220:221]
	v_pk_fma_f32 v[224:225], v[140:141], v[44:45], v[224:225]
	v_pk_fma_f32 v[222:223], v[92:93], v[44:45], v[222:223]
	v_pk_fma_f32 v[226:227], v[156:157], v[44:45], v[226:227]
	v_pk_fma_f32 v[220:221], v[78:79], v[46:47], v[220:221]
	v_pk_fma_f32 v[224:225], v[142:143], v[46:47], v[224:225]
	v_pk_fma_f32 v[222:223], v[94:95], v[46:47], v[222:223]
	v_pk_fma_f32 v[226:227], v[158:159], v[46:47], v[226:227]
	s_waitcnt lgkmcnt(3)
	v_pk_fma_f32 v[220:221], v[96:97], v[48:49], v[220:221]
	v_pk_fma_f32 v[224:225], v[160:161], v[48:49], v[224:225]
	v_pk_fma_f32 v[222:223], v[112:113], v[48:49], v[222:223]
	v_pk_fma_f32 v[226:227], v[176:177], v[48:49], v[226:227]
	v_pk_fma_f32 v[220:221], v[98:99], v[50:51], v[220:221]
	v_pk_fma_f32 v[224:225], v[162:163], v[50:51], v[224:225]
	v_pk_fma_f32 v[222:223], v[114:115], v[50:51], v[222:223]
	v_pk_fma_f32 v[226:227], v[178:179], v[50:51], v[226:227]
	s_waitcnt lgkmcnt(2)
	v_pk_fma_f32 v[220:221], v[100:101], v[52:53], v[220:221]
	v_pk_fma_f32 v[224:225], v[164:165], v[52:53], v[224:225]
	v_pk_fma_f32 v[222:223], v[116:117], v[52:53], v[222:223]
	v_pk_fma_f32 v[226:227], v[180:181], v[52:53], v[226:227]
	v_pk_fma_f32 v[220:221], v[102:103], v[54:55], v[220:221]
	v_pk_fma_f32 v[224:225], v[166:167], v[54:55], v[224:225]
	v_pk_fma_f32 v[222:223], v[118:119], v[54:55], v[222:223]
	v_pk_fma_f32 v[226:227], v[182:183], v[54:55], v[226:227]
	s_waitcnt lgkmcnt(1)
	v_pk_fma_f32 v[220:221], v[104:105], v[56:57], v[220:221]
	v_pk_fma_f32 v[224:225], v[168:169], v[56:57], v[224:225]
	v_pk_fma_f32 v[222:223], v[120:121], v[56:57], v[222:223]
	v_pk_fma_f32 v[226:227], v[184:185], v[56:57], v[226:227]
	v_pk_fma_f32 v[220:221], v[106:107], v[58:59], v[220:221]
	v_pk_fma_f32 v[224:225], v[170:171], v[58:59], v[224:225]
	v_pk_fma_f32 v[222:223], v[122:123], v[58:59], v[222:223]
	v_pk_fma_f32 v[226:227], v[186:187], v[58:59], v[226:227]
	s_waitcnt lgkmcnt(0)
	v_pk_fma_f32 v[220:221], v[108:109], v[60:61], v[220:221]
	v_pk_fma_f32 v[224:225], v[172:173], v[60:61], v[224:225]
	v_pk_fma_f32 v[222:223], v[124:125], v[60:61], v[222:223]
	v_pk_fma_f32 v[226:227], v[188:189], v[60:61], v[226:227]
	v_pk_fma_f32 v[220:221], v[110:111], v[62:63], v[220:221]
	v_pk_fma_f32 v[224:225], v[174:175], v[62:63], v[224:225]
	v_pk_fma_f32 v[222:223], v[126:127], v[62:63], v[222:223]
	v_pk_fma_f32 v[226:227], v[190:191], v[62:63], v[226:227]
	v_add_f32_e32 v18, v220, v221
	v_add_f32_e32 v228, v222, v223
	s_nop 1
	v_permlane32_swap_b32 v18, v228
	s_nop 0
	v_add_f32_e32 v18, v18, v228
	v_add_f32_e32 v229, v224, v225
	v_add_f32_e32 v230, v226, v227
	s_nop 1
	v_permlane32_swap_b32 v229, v230
	s_nop 0
	v_add_f32_e32 v229, v229, v230
	s_nop 1
	v_permlane32_swap_b32 v18, v19
	v_mov_b32_e32 v231, 0
	s_nop 1
	v_permlane32_swap_b32 v229, v231
	s_nop 1
	v_mfma_f32_32x32x2_f32 v[64:79], v16, v18, v[64:79]
	v_mfma_f32_32x32x2_f32 v[80:95], v16, v19, v[80:95]
	v_mfma_f32_32x32x2_f32 v[96:111], v17, v18, v[96:111]
	v_mfma_f32_32x32x2_f32 v[112:127], v17, v19, v[112:127]
	v_mfma_f32_32x32x2_f32 v[128:143], v16, v229, v[128:143]
	v_mfma_f32_32x32x2_f32 v[144:159], v16, v231, v[144:159]
	v_mfma_f32_32x32x2_f32 v[160:175], v17, v229, v[160:175]
	v_mfma_f32_32x32x2_f32 v[176:191], v17, v231, v[176:191]
	global_load_ushort v196, v3, s[4:5] offset:1024
	global_load_ushort v197, v4, s[6:7]
	global_load_ushort v198, v4, s[8:9]
	global_load_ushort v199, v4, s[10:11]
	v_add_u32_e32 v3, 0xc00, v3
	v_add_u32_e32 v4, 0x400, v4
	s_waitcnt vmcnt(12)
; DI float rl(float x, int l) { return __int_as_float(__builtin_amdgcn_readlane(__float_as_int(x), l)); }
; template <bool PASS2>
; DI void rwkv_item(const Params& p, int l, int item, int lane, const bf16_t* rkv, const bf16_t* lo2, float* rwst) {
;     ...
;   for (int t = 0; t < LCR; t++) {
;     Raw rawC = rawB;
;     if (t + 2 < LCR) rawC = load_raw(tok0 + t + 2);
;     Der nxt = cur;
;     if (t + 1 < LCR) nxt = derive(rawB, rpA, kpA);
;     const float rr = cur.rr, wdec = cur.wdec, kf = cur.kf, av = cur.av, bv = cur.bv, v = cur.v, gg = cur.gg;
;     float sa0 = 0.f, sa1 = 0.f, pa0 = 0.f, pa1 = 0.f;
; #pragma unroll
;     for (int j = 0; j < 64; j += 2) {
;       const float a0 = rl(av, j), a1 = rl(av, j + 1);
;       sa0 += S[j] * a0; sa1 += S[j + 1] * a1;
;       if (!PASS2) { pa0 += P[j] * a0; pa1 += P[j + 1] * a1; }
;     }
;     const float sa = sa0 + sa1, pa = pa0 + pa1;
;     float y0 = 0.f, y1 = 0.f;
; #pragma unroll
;     for (int j = 0; j < 64; j += 2) {
;       const float w0 = rl(wdec, j), b0 = rl(bv, j), k0 = rl(kf, j);
;       const float w1 = rl(wdec, j + 1), b1 = rl(bv, j + 1), k1 = rl(kf, j + 1);
;       S[j] = S[j] * w0 + sa * b0 + v * k0;
;       S[j + 1] = S[j + 1] * w1 + sa * b1 + v * k1;
;       if (!PASS2) {
;         P[j] = P[j] * w0 + pa * b0;
;         P[j + 1] = P[j + 1] * w1 + pa * b1;
	v_lshlrev_b32_e32 v27, 16, v200
	v_sub_f32_e32 v29, v7, v27
	v_fma_f32 v29, v29, v10, v27
	v_mov_b32_e32 v7, v27
	v_lshlrev_b32_e32 v30, 16, v202
	v_mul_f32_e32 v30, 0xbfb8aa3b, v30
	v_exp_f32_e32 v30, v30
	v_lshlrev_b32_e32 v31, 16, v203
	v_mul_f32_e32 v211, v29, v11
	v_add_f32_e32 v212, -1.0, v31
	v_fma_f32 v212, v212, v12, 1.0
	v_mul_f32_e32 v212, v29, v212
	v_mul_f32_e32 v213, v211, v211
	v_mov_b32_e32 v214, 0
	v_lshlrev_b32_e32 v20, 16, v201
	s_nop 1
	v_permlane32_swap_b32 v213, v214
	s_nop 0
	v_add_f32_e32 v213, v213, v214
	s_nop 1
	v_add_f32_dpp v213, v213, v213 quad_perm:[1,0,3,2] row_mask:0xf bank_mask:0xf
	s_nop 1
	v_add_f32_dpp v213, v213, v213 quad_perm:[2,3,0,1] row_mask:0xf bank_mask:0xf
	s_nop 1
	v_add_f32_dpp v213, v213, v213 row_half_mirror row_mask:0xf bank_mask:0xf
	s_nop 1
	v_add_f32_dpp v213, v213, v213 row_mirror row_mask:0xf bank_mask:0xf
	s_nop 1
	v_add_f32_dpp v213, v213, v213 row_bcast:15 row_mask:0xa bank_mask:0xf
	s_nop 1
	v_readlane_b32 s28, v213, 31
	v_readlane_b32 s30, v213, 63
	s_nop 1
	v_mov_b32_e32 v215, s28
	v_max_f32_e32 v215, 0x179abe15, v215
	v_rsq_f32_e32 v215, v215
	v_mov_b32_e32 v19, v20
	v_mul_f32_e32 v211, v211, v215
	v_mul_f32_e64 v24, -v211, v8
	v_mul_f32_e32 v216, v211, v31
	v_mul_f32_e32 v8, v8, v30
	v_rcp_f32_e32 v217, v8
	s_nop 0
	v_mul_f32_e32 v16, v216, v217
	v_mul_f32_e32 v17, v212, v217
	s_nop 1
	v_permlane32_swap_b32 v16, v17
	ds_write_b32 v1, v24
	ds_read_b128 v[32:35], v2 offset:0
	ds_read_b128 v[36:39], v2 offset:32
	ds_read_b128 v[40:43], v2 offset:64
	ds_read_b128 v[44:47], v2 offset:96
	ds_read_b128 v[48:51], v2 offset:128
	ds_read_b128 v[52:55], v2 offset:160
	ds_read_b128 v[56:59], v2 offset:192
	ds_read_b128 v[60:63], v2 offset:224
	s_waitcnt lgkmcnt(7)
	v_pk_mul_f32 v[220:221], v[64:65], v[32:33]
	v_pk_mul_f32 v[224:225], v[128:129], v[32:33]
	v_pk_mul_f32 v[222:223], v[80:81], v[32:33]
	v_pk_mul_f32 v[226:227], v[144:145], v[32:33]
	v_pk_fma_f32 v[220:221], v[66:67], v[34:35], v[220:221]
	v_pk_fma_f32 v[224:225], v[130:131], v[34:35], v[224:225]
	v_pk_fma_f32 v[222:223], v[82:83], v[34:35], v[222:223]
	v_pk_fma_f32 v[226:227], v[146:147], v[34:35], v[226:227]
	s_waitcnt lgkmcnt(6)
	v_pk_fma_f32 v[220:221], v[68:69], v[36:37], v[220:221]
	v_pk_fma_f32 v[224:225], v[132:133], v[36:37], v[224:225]
	v_pk_fma_f32 v[222:223], v[84:85], v[36:37], v[222:223]
	v_pk_fma_f32 v[226:227], v[148:149], v[36:37], v[226:227]
	v_pk_fma_f32 v[220:221], v[70:71], v[38:39], v[220:221]
	v_pk_fma_f32 v[224:225], v[134:135], v[38:39], v[224:225]
	v_pk_fma_f32 v[222:223], v[86:87], v[38:39], v[222:223]
	v_pk_fma_f32 v[226:227], v[150:151], v[38:39], v[226:227]
	s_waitcnt lgkmcnt(5)
	v_pk_fma_f32 v[220:221], v[72:73], v[40:41], v[220:221]
	v_pk_fma_f32 v[224:225], v[136:137], v[40:41], v[224:225]
	v_pk_fma_f32 v[222:223], v[88:89], v[40:41], v[222:223]
	v_pk_fma_f32 v[226:227], v[152:153], v[40:41], v[226:227]
	v_pk_fma_f32 v[220:221], v[74:75], v[42:43], v[220:221]
	v_pk_fma_f32 v[224:225], v[138:139], v[42:43], v[224:225]
	v_pk_fma_f32 v[222:223], v[90:91], v[42:43], v[222:223]
	v_pk_fma_f32 v[226:227], v[154:155], v[42:43], v[226:227]
	s_waitcnt lgkmcnt(4)
	v_pk_fma_f32 v[220:221], v[76:77], v[44:45], v[220:221]
	v_pk_fma_f32 v[224:225], v[140:141], v[44:45], v[224:225]
	v_pk_fma_f32 v[222:223], v[92:93], v[44:45], v[222:223]
	v_pk_fma_f32 v[226:227], v[156:157], v[44:45], v[226:227]
	v_pk_fma_f32 v[220:221], v[78:79], v[46:47], v[220:221]
	v_pk_fma_f32 v[224:225], v[142:143], v[46:47], v[224:225]
	v_pk_fma_f32 v[222:223], v[94:95], v[46:47], v[222:223]
	v_pk_fma_f32 v[226:227], v[158:159], v[46:47], v[226:227]
	s_waitcnt lgkmcnt(3)
	v_pk_fma_f32 v[220:221], v[96:97], v[48:49], v[220:221]
	v_pk_fma_f32 v[224:225], v[160:161], v[48:49], v[224:225]
	v_pk_fma_f32 v[222:223], v[112:113], v[48:49], v[222:223]
	v_pk_fma_f32 v[226:227], v[176:177], v[48:49], v[226:227]
	v_pk_fma_f32 v[220:221], v[98:99], v[50:51], v[220:221]
	v_pk_fma_f32 v[224:225], v[162:163], v[50:51], v[224:225]
	v_pk_fma_f32 v[222:223], v[114:115], v[50:51], v[222:223]
	v_pk_fma_f32 v[226:227], v[178:179], v[50:51], v[226:227]
	s_waitcnt lgkmcnt(2)
	v_pk_fma_f32 v[220:221], v[100:101], v[52:53], v[220:221]
	v_pk_fma_f32 v[224:225], v[164:165], v[52:53], v[224:225]
	v_pk_fma_f32 v[222:223], v[116:117], v[52:53], v[222:223]
	v_pk_fma_f32 v[226:227], v[180:181], v[52:53], v[226:227]
	v_pk_fma_f32 v[220:221], v[102:103], v[54:55], v[220:221]
	v_pk_fma_f32 v[224:225], v[166:167], v[54:55], v[224:225]
	v_pk_fma_f32 v[222:223], v[118:119], v[54:55], v[222:223]
	v_pk_fma_f32 v[226:227], v[182:183], v[54:55], v[226:227]
	s_waitcnt lgkmcnt(1)
	v_pk_fma_f32 v[220:221], v[104:105], v[56:57], v[220:221]
	v_pk_fma_f32 v[224:225], v[168:169], v[56:57], v[224:225]
	v_pk_fma_f32 v[222:223], v[120:121], v[56:57], v[222:223]
	v_pk_fma_f32 v[226:227], v[184:185], v[56:57], v[226:227]
	v_pk_fma_f32 v[220:221], v[106:107], v[58:59], v[220:221]
	v_pk_fma_f32 v[224:225], v[170:171], v[58:59], v[224:225]
	v_pk_fma_f32 v[222:223], v[122:123], v[58:59], v[222:223]
	v_pk_fma_f32 v[226:227], v[186:187], v[58:59], v[226:227]
	s_waitcnt lgkmcnt(0)
; DI float rl(float x, int l) { return __int_as_float(__builtin_amdgcn_readlane(__float_as_int(x), l)); }
; template <bool PASS2>
; DI void rwkv_item(const Params& p, int l, int item, int lane, const bf16_t* rkv, const bf16_t* lo2, float* rwst) {
;     ...
;   for (int t = 0; t < LCR; t++) {
;     Raw rawC = rawB;
;     if (t + 2 < LCR) rawC = load_raw(tok0 + t + 2);
;     Der nxt = cur;
;     if (t + 1 < LCR) nxt = derive(rawB, rpA, kpA);
;     const float rr = cur.rr, wdec = cur.wdec, kf = cur.kf, av = cur.av, bv = cur.bv, v = cur.v, gg = cur.gg;
;     float sa0 = 0.f, sa1 = 0.f, pa0 = 0.f, pa1 = 0.f;
; #pragma unroll
;     for (int j = 0; j < 64; j += 2) {
;       const float a0 = rl(av, j), a1 = rl(av, j + 1);
;       sa0 += S[j] * a0; sa1 += S[j + 1] * a1;
;       if (!PASS2) { pa0 += P[j] * a0; pa1 += P[j + 1] * a1; }
;     }
;     const float sa = sa0 + sa1, pa = pa0 + pa1;
;     float y0 = 0.f, y1 = 0.f;
; #pragma unroll
;     for (int j = 0; j < 64; j += 2) {
;       const float w0 = rl(wdec, j), b0 = rl(bv, j), k0 = rl(kf, j);
;       const float w1 = rl(wdec, j + 1), b1 = rl(bv, j + 1), k1 = rl(kf, j + 1);
;       S[j] = S[j] * w0 + sa * b0 + v * k0;
;       S[j + 1] = S[j + 1] * w1 + sa * b1 + v * k1;
;       if (!PASS2) {
;         P[j] = P[j] * w0 + pa * b0;
;         P[j + 1] = P[j + 1] * w1 + pa * b1;
	v_pk_fma_f32 v[220:221], v[108:109], v[60:61], v[220:221]
	v_pk_fma_f32 v[224:225], v[172:173], v[60:61], v[224:225]
	v_pk_fma_f32 v[222:223], v[124:125], v[60:61], v[222:223]
	v_pk_fma_f32 v[226:227], v[188:189], v[60:61], v[226:227]
	v_pk_fma_f32 v[220:221], v[110:111], v[62:63], v[220:221]
	v_pk_fma_f32 v[224:225], v[174:175], v[62:63], v[224:225]
	v_pk_fma_f32 v[222:223], v[126:127], v[62:63], v[222:223]
	v_pk_fma_f32 v[226:227], v[190:191], v[62:63], v[226:227]
	v_add_f32_e32 v18, v220, v221
	v_add_f32_e32 v228, v222, v223
	s_nop 1
	v_permlane32_swap_b32 v18, v228
	s_nop 0
	v_add_f32_e32 v18, v18, v228
	v_add_f32_e32 v229, v224, v225
	v_add_f32_e32 v230, v226, v227
	s_nop 1
	v_permlane32_swap_b32 v229, v230
	s_nop 0
	v_add_f32_e32 v229, v229, v230
	s_nop 1
	v_permlane32_swap_b32 v18, v19
	v_mov_b32_e32 v231, 0
	s_nop 1
	v_permlane32_swap_b32 v229, v231
	s_nop 1
	v_mfma_f32_32x32x2_f32 v[64:79], v16, v18, v[64:79]
	v_mfma_f32_32x32x2_f32 v[80:95], v16, v19, v[80:95]
	v_mfma_f32_32x32x2_f32 v[96:111], v17, v18, v[96:111]
	v_mfma_f32_32x32x2_f32 v[112:127], v17, v19, v[112:127]
	v_mfma_f32_32x32x2_f32 v[128:143], v16, v229, v[128:143]
	v_mfma_f32_32x32x2_f32 v[144:159], v16, v231, v[144:159]
	v_mfma_f32_32x32x2_f32 v[160:175], v17, v229, v[160:175]
	v_mfma_f32_32x32x2_f32 v[176:191], v17, v231, v[176:191]
	global_load_ushort v200, v3, s[4:5] offset:1024
	global_load_ushort v201, v4, s[6:7]
	global_load_ushort v202, v4, s[8:9]
	global_load_ushort v203, v4, s[10:11]
	v_add_u32_e32 v3, 0xc00, v3
	v_add_u32_e32 v4, 0x400, v4
	s_waitcnt vmcnt(12)
	v_lshlrev_b32_e32 v27, 16, v204
	v_sub_f32_e32 v29, v7, v27
	v_fma_f32 v29, v29, v10, v27
	v_mov_b32_e32 v7, v27
	v_lshlrev_b32_e32 v30, 16, v206
	v_mul_f32_e32 v30, 0xbfb8aa3b, v30
	v_exp_f32_e32 v30, v30
	v_lshlrev_b32_e32 v31, 16, v207
	v_mul_f32_e32 v211, v29, v11
	v_add_f32_e32 v212, -1.0, v31
	v_fma_f32 v212, v212, v12, 1.0
	v_mul_f32_e32 v212, v29, v212
	v_mul_f32_e32 v213, v211, v211
	v_mov_b32_e32 v214, 0
	v_lshlrev_b32_e32 v21, 16, v205
	s_nop 1
	v_permlane32_swap_b32 v213, v214
	s_nop 0
	v_add_f32_e32 v213, v213, v214
	s_nop 1
	v_add_f32_dpp v213, v213, v213 quad_perm:[1,0,3,2] row_mask:0xf bank_mask:0xf
	s_nop 1
	v_add_f32_dpp v213, v213, v213 quad_perm:[2,3,0,1] row_mask:0xf bank_mask:0xf
	s_nop 1
	v_add_f32_dpp v213, v213, v213 row_half_mirror row_mask:0xf bank_mask:0xf
	s_nop 1
	v_add_f32_dpp v213, v213, v213 row_mirror row_mask:0xf bank_mask:0xf
	s_nop 1
	v_add_f32_dpp v213, v213, v213 row_bcast:15 row_mask:0xa bank_mask:0xf
	s_nop 1
	v_readlane_b32 s28, v213, 31
	v_readlane_b32 s31, v213, 63
	s_nop 1
	v_mov_b32_e32 v215, s28
	v_max_f32_e32 v215, 0x179abe15, v215
	v_rsq_f32_e32 v215, v215
	v_mov_b32_e32 v19, v21
	v_mul_f32_e32 v211, v211, v215
	v_mul_f32_e64 v24, -v211, v8
	v_mul_f32_e32 v216, v211, v31
	v_mul_f32_e32 v8, v8, v30
	v_rcp_f32_e32 v217, v8
	s_nop 0
	v_mul_f32_e32 v16, v216, v217
	v_mul_f32_e32 v17, v212, v217
	s_nop 1
	v_permlane32_swap_b32 v16, v17
	ds_write_b32 v1, v24
	ds_read_b128 v[32:35], v2 offset:0
	ds_read_b128 v[36:39], v2 offset:32
	ds_read_b128 v[40:43], v2 offset:64
	ds_read_b128 v[44:47], v2 offset:96
	ds_read_b128 v[48:51], v2 offset:128
	ds_read_b128 v[52:55], v2 offset:160
	ds_read_b128 v[56:59], v2 offset:192
	ds_read_b128 v[60:63], v2 offset:224
	s_waitcnt lgkmcnt(7)
	v_pk_mul_f32 v[220:221], v[64:65], v[32:33]
	v_pk_mul_f32 v[224:225], v[128:129], v[32:33]
	v_pk_mul_f32 v[222:223], v[80:81], v[32:33]
	v_pk_mul_f32 v[226:227], v[144:145], v[32:33]
	v_pk_fma_f32 v[220:221], v[66:67], v[34:35], v[220:221]
	v_pk_fma_f32 v[224:225], v[130:131], v[34:35], v[224:225]
	v_pk_fma_f32 v[222:223], v[82:83], v[34:35], v[222:223]
	v_pk_fma_f32 v[226:227], v[146:147], v[34:35], v[226:227]
	s_waitcnt lgkmcnt(6)
	v_pk_fma_f32 v[220:221], v[68:69], v[36:37], v[220:221]
	v_pk_fma_f32 v[224:225], v[132:133], v[36:37], v[224:225]
	v_pk_fma_f32 v[222:223], v[84:85], v[36:37], v[222:223]
	v_pk_fma_f32 v[226:227], v[148:149], v[36:37], v[226:227]
	v_pk_fma_f32 v[220:221], v[70:71], v[38:39], v[220:221]
	v_pk_fma_f32 v[224:225], v[134:135], v[38:39], v[224:225]
	v_pk_fma_f32 v[222:223], v[86:87], v[38:39], v[222:223]
	v_pk_fma_f32 v[226:227], v[150:151], v[38:39], v[226:227]
	s_waitcnt lgkmcnt(5)
	v_pk_fma_f32 v[220:221], v[72:73], v[40:41], v[220:221]
	v_pk_fma_f32 v[224:225], v[136:137], v[40:41], v[224:225]
	v_pk_fma_f32 v[222:223], v[88:89], v[40:41], v[222:223]
	v_pk_fma_f32 v[226:227], v[152:153], v[40:41], v[226:227]
	v_pk_fma_f32 v[220:221], v[74:75], v[42:43], v[220:221]
	v_pk_fma_f32 v[224:225], v[138:139], v[42:43], v[224:225]
	v_pk_fma_f32 v[222:223], v[90:91], v[42:43], v[222:223]
	v_pk_fma_f32 v[226:227], v[154:155], v[42:43], v[226:227]
	s_waitcnt lgkmcnt(4)
	v_pk_fma_f32 v[220:221], v[76:77], v[44:45], v[220:221]
	v_pk_fma_f32 v[224:225], v[140:141], v[44:45], v[224:225]
	v_pk_fma_f32 v[222:223], v[92:93], v[44:45], v[222:223]
	v_pk_fma_f32 v[226:227], v[156:157], v[44:45], v[226:227]
	v_pk_fma_f32 v[220:221], v[78:79], v[46:47], v[220:221]
	v_pk_fma_f32 v[224:225], v[142:143], v[46:47], v[224:225]
	v_pk_fma_f32 v[222:223], v[94:95], v[46:47], v[222:223]
	v_pk_fma_f32 v[226:227], v[158:159], v[46:47], v[226:227]
	s_waitcnt lgkmcnt(3)
	v_pk_fma_f32 v[220:221], v[96:97], v[48:49], v[220:221]
	v_pk_fma_f32 v[224:225], v[160:161], v[48:49], v[224:225]
	v_pk_fma_f32 v[222:223], v[112:113], v[48:49], v[222:223]
	v_pk_fma_f32 v[226:227], v[176:177], v[48:49], v[226:227]
	v_pk_fma_f32 v[220:221], v[98:99], v[50:51], v[220:221]
	v_pk_fma_f32 v[224:225], v[162:163], v[50:51], v[224:225]
	v_pk_fma_f32 v[222:223], v[114:115], v[50:51], v[222:223]
	v_pk_fma_f32 v[226:227], v[178:179], v[50:51], v[226:227]
	s_waitcnt lgkmcnt(2)
; DI float rl(float x, int l) { return __int_as_float(__builtin_amdgcn_readlane(__float_as_int(x), l)); }
; template <bool PASS2>
; DI void rwkv_item(const Params& p, int l, int item, int lane, const bf16_t* rkv, const bf16_t* lo2, float* rwst) {
;     ...
;   for (int t = 0; t < LCR; t++) {
;     Raw rawC = rawB;
;     if (t + 2 < LCR) rawC = load_raw(tok0 + t + 2);
;     Der nxt = cur;
;     if (t + 1 < LCR) nxt = derive(rawB, rpA, kpA);
;     const float rr = cur.rr, wdec = cur.wdec, kf = cur.kf, av = cur.av, bv = cur.bv, v = cur.v, gg = cur.gg;
;     float sa0 = 0.f, sa1 = 0.f, pa0 = 0.f, pa1 = 0.f;
; #pragma unroll
;     for (int j = 0; j < 64; j += 2) {
;       const float a0 = rl(av, j), a1 = rl(av, j + 1);
;       sa0 += S[j] * a0; sa1 += S[j + 1] * a1;
;       if (!PASS2) { pa0 += P[j] * a0; pa1 += P[j + 1] * a1; }
;     }
;     const float sa = sa0 + sa1, pa = pa0 + pa1;
;     float y0 = 0.f, y1 = 0.f;
; #pragma unroll
;     for (int j = 0; j < 64; j += 2) {
;       const float w0 = rl(wdec, j), b0 = rl(bv, j), k0 = rl(kf, j);
;       const float w1 = rl(wdec, j + 1), b1 = rl(bv, j + 1), k1 = rl(kf, j + 1);
;       S[j] = S[j] * w0 + sa * b0 + v * k0;
;       S[j + 1] = S[j + 1] * w1 + sa * b1 + v * k1;
;       if (!PASS2) {
;         P[j] = P[j] * w0 + pa * b0;
;         P[j + 1] = P[j + 1] * w1 + pa * b1;
	v_pk_fma_f32 v[220:221], v[100:101], v[52:53], v[220:221]
	v_pk_fma_f32 v[224:225], v[164:165], v[52:53], v[224:225]
	v_pk_fma_f32 v[222:223], v[116:117], v[52:53], v[222:223]
	v_pk_fma_f32 v[226:227], v[180:181], v[52:53], v[226:227]
	v_pk_fma_f32 v[220:221], v[102:103], v[54:55], v[220:221]
	v_pk_fma_f32 v[224:225], v[166:167], v[54:55], v[224:225]
	v_pk_fma_f32 v[222:223], v[118:119], v[54:55], v[222:223]
	v_pk_fma_f32 v[226:227], v[182:183], v[54:55], v[226:227]
	s_waitcnt lgkmcnt(1)
	v_pk_fma_f32 v[220:221], v[104:105], v[56:57], v[220:221]
	v_pk_fma_f32 v[224:225], v[168:169], v[56:57], v[224:225]
	v_pk_fma_f32 v[222:223], v[120:121], v[56:57], v[222:223]
	v_pk_fma_f32 v[226:227], v[184:185], v[56:57], v[226:227]
	v_pk_fma_f32 v[220:221], v[106:107], v[58:59], v[220:221]
	v_pk_fma_f32 v[224:225], v[170:171], v[58:59], v[224:225]
	v_pk_fma_f32 v[222:223], v[122:123], v[58:59], v[222:223]
	v_pk_fma_f32 v[226:227], v[186:187], v[58:59], v[226:227]
	s_waitcnt lgkmcnt(0)
	v_pk_fma_f32 v[220:221], v[108:109], v[60:61], v[220:221]
	v_pk_fma_f32 v[224:225], v[172:173], v[60:61], v[224:225]
	v_pk_fma_f32 v[222:223], v[124:125], v[60:61], v[222:223]
	v_pk_fma_f32 v[226:227], v[188:189], v[60:61], v[226:227]
	v_pk_fma_f32 v[220:221], v[110:111], v[62:63], v[220:221]
	v_pk_fma_f32 v[224:225], v[174:175], v[62:63], v[224:225]
	v_pk_fma_f32 v[222:223], v[126:127], v[62:63], v[222:223]
	v_pk_fma_f32 v[226:227], v[190:191], v[62:63], v[226:227]
	v_add_f32_e32 v18, v220, v221
	v_add_f32_e32 v228, v222, v223
	s_nop 1
	v_permlane32_swap_b32 v18, v228
	s_nop 0
	v_add_f32_e32 v18, v18, v228
	v_add_f32_e32 v229, v224, v225
	v_add_f32_e32 v230, v226, v227
	s_nop 1
	v_permlane32_swap_b32 v229, v230
	s_nop 0
	v_add_f32_e32 v229, v229, v230
	s_nop 1
	v_permlane32_swap_b32 v18, v19
	v_mov_b32_e32 v231, 0
	s_nop 1
	v_permlane32_swap_b32 v229, v231
	s_nop 1
	v_mfma_f32_32x32x2_f32 v[64:79], v16, v18, v[64:79]
	v_mfma_f32_32x32x2_f32 v[80:95], v16, v19, v[80:95]
	v_mfma_f32_32x32x2_f32 v[96:111], v17, v18, v[96:111]
	v_mfma_f32_32x32x2_f32 v[112:127], v17, v19, v[112:127]
	v_mfma_f32_32x32x2_f32 v[128:143], v16, v229, v[128:143]
	v_mfma_f32_32x32x2_f32 v[144:159], v16, v231, v[144:159]
	v_mfma_f32_32x32x2_f32 v[160:175], v17, v229, v[160:175]
	v_mfma_f32_32x32x2_f32 v[176:191], v17, v231, v[176:191]
	global_load_ushort v204, v3, s[4:5] offset:1024
	global_load_ushort v205, v4, s[6:7]
	global_load_ushort v206, v4, s[8:9]
	global_load_ushort v207, v4, s[10:11]
	v_add_u32_e32 v3, 0xc00, v3
	v_add_u32_e32 v4, 0x400, v4
	s_waitcnt vmcnt(12)
	v_mov_b32_e32 v218, v8
	v_lshlrev_b32_e32 v27, 16, v192
	v_sub_f32_e32 v29, v7, v27
	v_fma_f32 v29, v29, v10, v27
	v_mov_b32_e32 v7, v27
	v_lshlrev_b32_e32 v30, 16, v194
	v_mul_f32_e32 v30, 0xbfb8aa3b, v30
	v_exp_f32_e32 v30, v30
	v_lshlrev_b32_e32 v31, 16, v195
	v_mul_f32_e32 v211, v29, v11
	v_add_f32_e32 v212, -1.0, v31
	v_fma_f32 v212, v212, v12, 1.0
	v_mul_f32_e32 v212, v29, v212
	v_mul_f32_e32 v213, v211, v211
	v_mov_b32_e32 v214, 0
	v_lshlrev_b32_e32 v20, 16, v193
	s_nop 1
	v_permlane32_swap_b32 v213, v214
	s_nop 0
	v_add_f32_e32 v213, v213, v214
	s_nop 1
	v_add_f32_dpp v213, v213, v213 quad_perm:[1,0,3,2] row_mask:0xf bank_mask:0xf
	s_nop 1
	v_add_f32_dpp v213, v213, v213 quad_perm:[2,3,0,1] row_mask:0xf bank_mask:0xf
	s_nop 1
	v_add_f32_dpp v213, v213, v213 row_half_mirror row_mask:0xf bank_mask:0xf
	s_nop 1
	v_add_f32_dpp v213, v213, v213 row_mirror row_mask:0xf bank_mask:0xf
	s_nop 1
	v_add_f32_dpp v213, v213, v213 row_bcast:15 row_mask:0xa bank_mask:0xf
	s_nop 1
	v_readlane_b32 s28, v213, 31
	v_readlane_b32 s30, v213, 63
	s_nop 1
	v_mov_b32_e32 v215, s28
	v_max_f32_e32 v215, 0x179abe15, v215
	v_rsq_f32_e32 v215, v215
	v_mov_b32_e32 v19, v20
	v_mul_f32_e32 v211, v211, v215
	v_mul_f32_e64 v24, -v211, v8
	v_mul_f32_e32 v216, v211, v31
	v_mul_f32_e32 v8, v8, v30
	v_rcp_f32_e32 v217, v8
	s_nop 0
	v_mul_f32_e32 v16, v216, v217
	v_mul_f32_e32 v17, v212, v217
	s_nop 1
	v_permlane32_swap_b32 v16, v17
	ds_write_b32 v1, v24
	ds_read_b128 v[32:35], v2 offset:0
	ds_read_b128 v[36:39], v2 offset:32
	ds_read_b128 v[40:43], v2 offset:64
	ds_read_b128 v[44:47], v2 offset:96
	ds_read_b128 v[48:51], v2 offset:128
	ds_read_b128 v[52:55], v2 offset:160
	ds_read_b128 v[56:59], v2 offset:192
	ds_read_b128 v[60:63], v2 offset:224
	s_waitcnt lgkmcnt(7)
	v_pk_mul_f32 v[220:221], v[64:65], v[32:33]
	v_pk_mul_f32 v[224:225], v[128:129], v[32:33]
	v_pk_mul_f32 v[222:223], v[80:81], v[32:33]
	v_pk_mul_f32 v[226:227], v[144:145], v[32:33]
	v_pk_fma_f32 v[220:221], v[66:67], v[34:35], v[220:221]
	v_pk_fma_f32 v[224:225], v[130:131], v[34:35], v[224:225]
	v_pk_fma_f32 v[222:223], v[82:83], v[34:35], v[222:223]
	v_pk_fma_f32 v[226:227], v[146:147], v[34:35], v[226:227]
	s_waitcnt lgkmcnt(6)
	v_pk_fma_f32 v[220:221], v[68:69], v[36:37], v[220:221]
	v_pk_fma_f32 v[224:225], v[132:133], v[36:37], v[224:225]
	v_pk_fma_f32 v[222:223], v[84:85], v[36:37], v[222:223]
	v_pk_fma_f32 v[226:227], v[148:149], v[36:37], v[226:227]
	v_pk_fma_f32 v[220:221], v[70:71], v[38:39], v[220:221]
	v_pk_fma_f32 v[224:225], v[134:135], v[38:39], v[224:225]
	v_pk_fma_f32 v[222:223], v[86:87], v[38:39], v[222:223]
	v_pk_fma_f32 v[226:227], v[150:151], v[38:39], v[226:227]
	s_waitcnt lgkmcnt(5)
	v_pk_fma_f32 v[220:221], v[72:73], v[40:41], v[220:221]
	v_pk_fma_f32 v[224:225], v[136:137], v[40:41], v[224:225]
	v_pk_fma_f32 v[222:223], v[88:89], v[40:41], v[222:223]
	v_pk_fma_f32 v[226:227], v[152:153], v[40:41], v[226:227]
	v_pk_fma_f32 v[220:221], v[74:75], v[42:43], v[220:221]
	v_pk_fma_f32 v[224:225], v[138:139], v[42:43], v[224:225]
	v_pk_fma_f32 v[222:223], v[90:91], v[42:43], v[222:223]
	v_pk_fma_f32 v[226:227], v[154:155], v[42:43], v[226:227]
	s_waitcnt lgkmcnt(4)
; DI float rl(float x, int l) { return __int_as_float(__builtin_amdgcn_readlane(__float_as_int(x), l)); }
; template <bool PASS2>
; DI void rwkv_item(const Params& p, int l, int item, int lane, const bf16_t* rkv, const bf16_t* lo2, float* rwst) {
;     ...
;   for (int t = 0; t < LCR; t++) {
;     Raw rawC = rawB;
;     if (t + 2 < LCR) rawC = load_raw(tok0 + t + 2);
;     Der nxt = cur;
;     if (t + 1 < LCR) nxt = derive(rawB, rpA, kpA);
;     const float rr = cur.rr, wdec = cur.wdec, kf = cur.kf, av = cur.av, bv = cur.bv, v = cur.v, gg = cur.gg;
;     float sa0 = 0.f, sa1 = 0.f, pa0 = 0.f, pa1 = 0.f;
; #pragma unroll
;     for (int j = 0; j < 64; j += 2) {
;       const float a0 = rl(av, j), a1 = rl(av, j + 1);
;       sa0 += S[j] * a0; sa1 += S[j + 1] * a1;
;       if (!PASS2) { pa0 += P[j] * a0; pa1 += P[j + 1] * a1; }
;     }
;     const float sa = sa0 + sa1, pa = pa0 + pa1;
;     float y0 = 0.f, y1 = 0.f;
; #pragma unroll
;     for (int j = 0; j < 64; j += 2) {
;       const float w0 = rl(wdec, j), b0 = rl(bv, j), k0 = rl(kf, j);
;       const float w1 = rl(wdec, j + 1), b1 = rl(bv, j + 1), k1 = rl(kf, j + 1);
;       S[j] = S[j] * w0 + sa * b0 + v * k0;
;       S[j + 1] = S[j + 1] * w1 + sa * b1 + v * k1;
;       if (!PASS2) {
;         P[j] = P[j] * w0 + pa * b0;
;         P[j + 1] = P[j + 1] * w1 + pa * b1;
	v_pk_fma_f32 v[220:221], v[76:77], v[44:45], v[220:221]
	v_pk_fma_f32 v[224:225], v[140:141], v[44:45], v[224:225]
	v_pk_fma_f32 v[222:223], v[92:93], v[44:45], v[222:223]
	v_pk_fma_f32 v[226:227], v[156:157], v[44:45], v[226:227]
	v_pk_fma_f32 v[220:221], v[78:79], v[46:47], v[220:221]
	v_pk_fma_f32 v[224:225], v[142:143], v[46:47], v[224:225]
	v_pk_fma_f32 v[222:223], v[94:95], v[46:47], v[222:223]
	v_pk_fma_f32 v[226:227], v[158:159], v[46:47], v[226:227]
	s_waitcnt lgkmcnt(3)
	v_pk_fma_f32 v[220:221], v[96:97], v[48:49], v[220:221]
	v_pk_fma_f32 v[224:225], v[160:161], v[48:49], v[224:225]
	v_pk_fma_f32 v[222:223], v[112:113], v[48:49], v[222:223]
	v_pk_fma_f32 v[226:227], v[176:177], v[48:49], v[226:227]
	v_pk_fma_f32 v[220:221], v[98:99], v[50:51], v[220:221]
	v_pk_fma_f32 v[224:225], v[162:163], v[50:51], v[224:225]
	v_pk_fma_f32 v[222:223], v[114:115], v[50:51], v[222:223]
	v_pk_fma_f32 v[226:227], v[178:179], v[50:51], v[226:227]
	s_waitcnt lgkmcnt(2)
	v_pk_fma_f32 v[220:221], v[100:101], v[52:53], v[220:221]
	v_pk_fma_f32 v[224:225], v[164:165], v[52:53], v[224:225]
	v_pk_fma_f32 v[222:223], v[116:117], v[52:53], v[222:223]
	v_pk_fma_f32 v[226:227], v[180:181], v[52:53], v[226:227]
	v_pk_fma_f32 v[220:221], v[102:103], v[54:55], v[220:221]
	v_pk_fma_f32 v[224:225], v[166:167], v[54:55], v[224:225]
	v_pk_fma_f32 v[222:223], v[118:119], v[54:55], v[222:223]
	v_pk_fma_f32 v[226:227], v[182:183], v[54:55], v[226:227]
	s_waitcnt lgkmcnt(1)
	v_pk_fma_f32 v[220:221], v[104:105], v[56:57], v[220:221]
	v_pk_fma_f32 v[224:225], v[168:169], v[56:57], v[224:225]
	v_pk_fma_f32 v[222:223], v[120:121], v[56:57], v[222:223]
	v_pk_fma_f32 v[226:227], v[184:185], v[56:57], v[226:227]
	v_pk_fma_f32 v[220:221], v[106:107], v[58:59], v[220:221]
	v_pk_fma_f32 v[224:225], v[170:171], v[58:59], v[224:225]
	v_pk_fma_f32 v[222:223], v[122:123], v[58:59], v[222:223]
	v_pk_fma_f32 v[226:227], v[186:187], v[58:59], v[226:227]
	s_waitcnt lgkmcnt(0)
	v_pk_fma_f32 v[220:221], v[108:109], v[60:61], v[220:221]
	v_pk_fma_f32 v[224:225], v[172:173], v[60:61], v[224:225]
	v_pk_fma_f32 v[222:223], v[124:125], v[60:61], v[222:223]
	v_pk_fma_f32 v[226:227], v[188:189], v[60:61], v[226:227]
	v_pk_fma_f32 v[220:221], v[110:111], v[62:63], v[220:221]
	v_pk_fma_f32 v[224:225], v[174:175], v[62:63], v[224:225]
	v_pk_fma_f32 v[222:223], v[126:127], v[62:63], v[222:223]
	v_pk_fma_f32 v[226:227], v[190:191], v[62:63], v[226:227]
	v_add_f32_e32 v18, v220, v221
	v_add_f32_e32 v228, v222, v223
	s_nop 1
	v_permlane32_swap_b32 v18, v228
	s_nop 0
	v_add_f32_e32 v18, v18, v228
	v_add_f32_e32 v229, v224, v225
	v_add_f32_e32 v230, v226, v227
	s_nop 1
	v_permlane32_swap_b32 v229, v230
	s_nop 0
	v_add_f32_e32 v229, v229, v230
	s_add_u32 s18, s18, 4
	s_cmp_lt_u32 s18, 128
	s_cbranch_scc1 .Lrwp1a_loop
; template <bool PASS2>
; DI void rwkv_item(const Params& p, int l, int item, int lane, const bf16_t* rkv, const bf16_t* lo2, float* rwst) {
;     ...
;   if (!PASS2) {
;     float4* sp = (float4*)(stS + lane * 64);
;     float4* pp = (float4*)(stP + lane * 64);
; #pragma unroll
;     for (int j = 0; j < 16; j++) {
;       sp[j] = make_float4(S[4 * j], S[4 * j + 1], S[4 * j + 2], S[4 * j + 3]);
;       pp[j] = make_float4(P[4 * j], P[4 * j + 1], P[4 * j + 2], P[4 * j + 3]);
;     }
;   }
; template <int Q>
; DI void run_phase(const Params& p, int l, bf16_t* sm) {
;     ...
;     for (int it = wave * gridDim.x + blockIdx.x; it < 16 * NCHR; it += gridDim.x * 4) rwkv_item<false>(p, l, __builtin_amdgcn_readfirstlane(it), lane, rkv, lo2, rwst);
	ds_write_b32 v1, v218
	ds_read_b128 v[32:35], v2 offset:0
	ds_read_b128 v[36:39], v2 offset:32
	ds_read_b128 v[40:43], v2 offset:64
	ds_read_b128 v[44:47], v2 offset:96
	ds_read_b128 v[48:51], v2 offset:128
	ds_read_b128 v[52:55], v2 offset:160
	ds_read_b128 v[56:59], v2 offset:192
	ds_read_b128 v[60:63], v2 offset:224
	s_waitcnt lgkmcnt(0)
	s_nop 7
	s_nop 7
	s_nop 3
	v_pk_mul_f32 v[64:65], v[64:65], v[32:33]
	v_pk_mul_f32 v[128:129], v[128:129], v[32:33]
	v_pk_mul_f32 v[66:67], v[66:67], v[34:35]
	v_pk_mul_f32 v[130:131], v[130:131], v[34:35]
	v_pk_mul_f32 v[68:69], v[68:69], v[36:37]
	v_pk_mul_f32 v[132:133], v[132:133], v[36:37]
	v_pk_mul_f32 v[70:71], v[70:71], v[38:39]
	v_pk_mul_f32 v[134:135], v[134:135], v[38:39]
	v_pk_mul_f32 v[72:73], v[72:73], v[40:41]
	v_pk_mul_f32 v[136:137], v[136:137], v[40:41]
	v_pk_mul_f32 v[74:75], v[74:75], v[42:43]
	v_pk_mul_f32 v[138:139], v[138:139], v[42:43]
	v_pk_mul_f32 v[76:77], v[76:77], v[44:45]
	v_pk_mul_f32 v[140:141], v[140:141], v[44:45]
	v_pk_mul_f32 v[78:79], v[78:79], v[46:47]
	v_pk_mul_f32 v[142:143], v[142:143], v[46:47]
	v_pk_mul_f32 v[80:81], v[80:81], v[32:33]
	v_pk_mul_f32 v[144:145], v[144:145], v[32:33]
	v_pk_mul_f32 v[82:83], v[82:83], v[34:35]
	v_pk_mul_f32 v[146:147], v[146:147], v[34:35]
	v_pk_mul_f32 v[84:85], v[84:85], v[36:37]
	v_pk_mul_f32 v[148:149], v[148:149], v[36:37]
	v_pk_mul_f32 v[86:87], v[86:87], v[38:39]
	v_pk_mul_f32 v[150:151], v[150:151], v[38:39]
	v_pk_mul_f32 v[88:89], v[88:89], v[40:41]
	v_pk_mul_f32 v[152:153], v[152:153], v[40:41]
	v_pk_mul_f32 v[90:91], v[90:91], v[42:43]
	v_pk_mul_f32 v[154:155], v[154:155], v[42:43]
	v_pk_mul_f32 v[92:93], v[92:93], v[44:45]
	v_pk_mul_f32 v[156:157], v[156:157], v[44:45]
	v_pk_mul_f32 v[94:95], v[94:95], v[46:47]
	v_pk_mul_f32 v[158:159], v[158:159], v[46:47]
	v_pk_mul_f32 v[96:97], v[96:97], v[48:49]
	v_pk_mul_f32 v[160:161], v[160:161], v[48:49]
	v_pk_mul_f32 v[98:99], v[98:99], v[50:51]
	v_pk_mul_f32 v[162:163], v[162:163], v[50:51]
	v_pk_mul_f32 v[100:101], v[100:101], v[52:53]
	v_pk_mul_f32 v[164:165], v[164:165], v[52:53]
	v_pk_mul_f32 v[102:103], v[102:103], v[54:55]
	v_pk_mul_f32 v[166:167], v[166:167], v[54:55]
	v_pk_mul_f32 v[104:105], v[104:105], v[56:57]
	v_pk_mul_f32 v[168:169], v[168:169], v[56:57]
	v_pk_mul_f32 v[106:107], v[106:107], v[58:59]
	v_pk_mul_f32 v[170:171], v[170:171], v[58:59]
	v_pk_mul_f32 v[108:109], v[108:109], v[60:61]
	v_pk_mul_f32 v[172:173], v[172:173], v[60:61]
	v_pk_mul_f32 v[110:111], v[110:111], v[62:63]
	v_pk_mul_f32 v[174:175], v[174:175], v[62:63]
	v_pk_mul_f32 v[112:113], v[112:113], v[48:49]
	v_pk_mul_f32 v[176:177], v[176:177], v[48:49]
	v_pk_mul_f32 v[114:115], v[114:115], v[50:51]
	v_pk_mul_f32 v[178:179], v[178:179], v[50:51]
	v_pk_mul_f32 v[116:117], v[116:117], v[52:53]
	v_pk_mul_f32 v[180:181], v[180:181], v[52:53]
	v_pk_mul_f32 v[118:119], v[118:119], v[54:55]
	v_pk_mul_f32 v[182:183], v[182:183], v[54:55]
	v_pk_mul_f32 v[120:121], v[120:121], v[56:57]
	v_pk_mul_f32 v[184:185], v[184:185], v[56:57]
	v_pk_mul_f32 v[122:123], v[122:123], v[58:59]
	v_pk_mul_f32 v[186:187], v[186:187], v[58:59]
	v_pk_mul_f32 v[124:125], v[124:125], v[60:61]
	v_pk_mul_f32 v[188:189], v[188:189], v[60:61]
	v_pk_mul_f32 v[126:127], v[126:127], v[62:63]
	v_pk_mul_f32 v[190:191], v[190:191], v[62:63]
	global_store_dwordx4 v26, v[64:67], s[24:25] offset:0
	global_store_dwordx4 v26, v[128:131], s[40:41] offset:0
	global_store_dwordx4 v26, v[68:71], s[24:25] offset:32
	global_store_dwordx4 v26, v[132:135], s[40:41] offset:32
	global_store_dwordx4 v26, v[72:75], s[24:25] offset:64
	global_store_dwordx4 v26, v[136:139], s[40:41] offset:64
	global_store_dwordx4 v26, v[76:79], s[24:25] offset:96
	global_store_dwordx4 v26, v[140:143], s[40:41] offset:96
	global_store_dwordx4 v26, v[80:83], s[26:27] offset:0
	global_store_dwordx4 v26, v[144:147], s[38:39] offset:0
	global_store_dwordx4 v26, v[84:87], s[26:27] offset:32
	global_store_dwordx4 v26, v[148:151], s[38:39] offset:32
	global_store_dwordx4 v26, v[88:91], s[26:27] offset:64
	global_store_dwordx4 v26, v[152:155], s[38:39] offset:64
	global_store_dwordx4 v26, v[92:95], s[26:27] offset:96
	global_store_dwordx4 v26, v[156:159], s[38:39] offset:96
	global_store_dwordx4 v26, v[96:99], s[24:25] offset:128
	global_store_dwordx4 v26, v[160:163], s[40:41] offset:128
	global_store_dwordx4 v26, v[100:103], s[24:25] offset:160
	global_store_dwordx4 v26, v[164:167], s[40:41] offset:160
	global_store_dwordx4 v26, v[104:107], s[24:25] offset:192
	global_store_dwordx4 v26, v[168:171], s[40:41] offset:192
	global_store_dwordx4 v26, v[108:111], s[24:25] offset:224
	global_store_dwordx4 v26, v[172:175], s[40:41] offset:224
	global_store_dwordx4 v26, v[112:115], s[26:27] offset:128
	global_store_dwordx4 v26, v[176:179], s[38:39] offset:128
	global_store_dwordx4 v26, v[116:119], s[26:27] offset:160
	global_store_dwordx4 v26, v[180:183], s[38:39] offset:160
	global_store_dwordx4 v26, v[120:123], s[26:27] offset:192
	global_store_dwordx4 v26, v[184:187], s[38:39] offset:192
	global_store_dwordx4 v26, v[124:127], s[26:27] offset:224
	global_store_dwordx4 v26, v[188:191], s[38:39] offset:224
	s_waitcnt vmcnt(0)
	s_add_u32 s16, s16, s17
	s_cmpk_lt_i32 s16, 0x800
	s_cbranch_scc1 .Lrwp1a_item

; DI float bf2f(bf16_t b) { return __uint_as_float(((unsigned)b) << 16); }
; template <bool PASS2>
; DI void rwkv_item(const Params& p, int l, int item, int lane, const bf16_t* rkv, const bf16_t* lo2, float* rwst) {
;   const int b = item / (8 * NCHR), head = (item / NCHR) % 8, c = item % NCHR;
;   const int ch = head * 64 + lane;
;   const float mu_r = p.in[I_RW_MU_RKV][(size_t)l * 1536 + ch], mu_k = p.in[I_RW_MU_RKV][(size_t)l * 1536 + 512 + ch];
;   const float kkw = p.in[I_RW_K_K][l * 512 + ch], kaw = p.in[I_RW_K_A][l * 512 + ch];
;   const float rkw = p.in[I_RW_R_K][l * 512 + ch];
;   const float gnw = p.in[I_RW_GN_W][l * 512 + ch], gnb = p.in[I_RW_GN_B][l * 512 + ch];
;   const size_t tok0 = (size_t)b * SEQ + (size_t)c * LCR;
;   float* stS = rwst + ((size_t)((b * 8 + head) * NCHR + c)) * 4096;
;   float* stP = (float*)p.yc + ((size_t)((b * 8 + head) * NCHR + c)) * 4096;
;   float S[64], P[64];
; #pragma unroll
;   for (int j = 0; j < 64; j++) { S[j] = 0.f; P[j] = (j == lane) ? 1.f : 0.f; }
;   if (PASS2 && c > 0) {
;     const float4* sp = (const float4*)(stS - 4096 + lane * 64);
; #pragma unroll
;     for (int j = 0; j < 16; j++) { float4 v = sp[j]; S[4 * j] = v.x; S[4 * j + 1] = v.y; S[4 * j + 2] = v.z; S[4 * j + 3] = v.w; }
;   }
;   float rp_prev = 0.f, kp_prev = 0.f;
;   if (c > 0) { rp_prev = bf2f(rkv[(tok0 - 1) * 1536 + ch]); kp_prev = bf2f(rkv[(tok0 - 1) * 1536 + 512 + ch]); }
.LBB0_1423:
	v_writelane_b32 v255, s80, 54
	s_or_b64 exec, exec, s[0:1]
	s_waitcnt lgkmcnt(0)
	v_mov_b32_e32 v0, v210
	v_mov_b32_e32 v1, v210
	s_barrier
	v_readlane_b32 s0, v252, 1
	v_bfe_u32 v1, v1, 6, 2
	v_readlane_b32 s1, v252, 2
	v_mul_lo_u32 v1, v1, s0
	v_readlane_b32 s0, v252, 26
	s_nop 1
	v_add_u32_e32 v80, s0, v1
	s_movk_i32 s0, 0x800
	v_cmp_gt_i32_e32 vcc, s0, v80
	s_mov_b64 s[86:87], exec
	v_writelane_b32 v255, s64, 10
	v_writelane_b32 v253, s48, 17
	s_and_b64 s[2:3], s[86:87], vcc
	v_writelane_b32 v255, s65, 11
	v_writelane_b32 v253, s49, 18
	v_writelane_b32 v255, s66, 12
	v_writelane_b32 v253, s50, 19
	v_writelane_b32 v255, s67, 13
	v_writelane_b32 v253, s51, 20
	v_writelane_b32 v255, s68, 14
	v_writelane_b32 v253, s52, 21
	v_writelane_b32 v255, s69, 15
	v_writelane_b32 v253, s53, 22
	v_writelane_b32 v255, s70, 16
	v_writelane_b32 v253, s54, 23
	v_writelane_b32 v255, s71, 17
	v_writelane_b32 v253, s55, 24
	v_writelane_b32 v255, s72, 18
	v_writelane_b32 v253, s56, 25
	v_writelane_b32 v255, s73, 19
	v_writelane_b32 v253, s57, 26
	v_writelane_b32 v255, s74, 20
	v_writelane_b32 v253, s58, 27
	v_writelane_b32 v255, s75, 21
	v_writelane_b32 v253, s59, 28
	v_writelane_b32 v255, s76, 22
	v_writelane_b32 v253, s60, 29
	v_writelane_b32 v255, s77, 23
	v_writelane_b32 v253, s61, 30
	v_writelane_b32 v255, s78, 24
	v_writelane_b32 v253, s62, 31
	v_writelane_b32 v255, s79, 25
	v_writelane_b32 v253, s63, 32
	v_writelane_b32 v255, s97, 55
	s_mov_b64 exec, s[2:3]
	s_cbranch_execz .LBB0_1437
	v_and_b32_e32 v0, 63, v210
	v_lshrrev_b32_e32 v1, 6, v210
	v_and_b32_e32 v1, 3, v1
	v_lshlrev_b32_e32 v1, 10, v1
	v_lshrrev_b32_e32 v2, 5, v0
	v_lshl_add_u32 v2, v2, 4, v1
	v_lshl_add_u32 v1, v0, 2, v1
	v_readlane_b32 s56, v252, 3
	v_readlane_b32 s57, v252, 4
	v_readlane_b32 s17, v252, 1
	v_readfirstlane_b32 s16, v80
	s_sub_u32 s56, s56, 0x180
	s_subb_u32 s57, s57, 0
	s_lshl_b32 s17, s17, 2
	s_load_dwordx2 s[2:3], s[56:57], 0x170
	s_load_dwordx2 s[44:45], s[56:57], 0x68
	s_load_dwordx2 s[46:47], s[56:57], 0xb8
	s_load_dwordx2 s[58:59], s[56:57], 0xc0
	s_load_dwordx2 s[50:51], s[56:57], 0xc8
	s_load_dwordx2 s[52:53], s[56:57], 0xd0
	s_load_dwordx2 s[54:55], s[56:57], 0xd8
	s_waitcnt lgkmcnt(0)
.Lrwp2a_item:
	s_lshr_b32 s19, s16, 10
	s_bfe_u32 s20, s16, 0x30007
	s_and_b32 s21, s16, 127
	s_lshl_b32 s22, s19, 14
	s_lshl_b32 s23, s21, 7
	s_add_u32 s22, s22, s23
	v_lshl_add_u32 v3, s20, 6, v0
	v_lshlrev_b32_e32 v4, 2, v3
	v_lshlrev_b32_e32 v208, 1, v3
	s_add_u32 s28, s44, 0x0
	s_addc_u32 s29, s45, 0
	global_load_dword v9, v4, s[28:29]
	s_add_u32 s28, s44, 0x800
	s_addc_u32 s29, s45, 0
	global_load_dword v10, v4, s[28:29]
	s_add_u32 s28, s46, 0x0
	s_addc_u32 s29, s47, 0
	global_load_dword v11, v4, s[28:29]
	s_add_u32 s28, s58, 0x0
	s_addc_u32 s29, s59, 0
	global_load_dword v12, v4, s[28:29]
	s_add_u32 s28, s50, 0x0
	s_addc_u32 s29, s51, 0
	global_load_dword v13, v4, s[28:29]
	s_add_u32 s28, s52, 0x0
	s_addc_u32 s29, s53, 0
	global_load_dword v14, v4, s[28:29]
	s_add_u32 s28, s54, 0x0
	s_addc_u32 s29, s55, 0
	global_load_dword v15, v4, s[28:29]
	s_add_u32 s4, s2, 0x17558000
	s_addc_u32 s5, s3, 0
	s_add_u32 s6, s2, 0x3558000
	s_addc_u32 s7, s3, 0
	s_add_u32 s8, s2, 0x11558000
	s_addc_u32 s9, s3, 0
	s_add_u32 s10, s2, 0x13558000
	s_addc_u32 s11, s3, 0
	s_add_u32 s12, s2, 0x15558000
	s_addc_u32 s13, s3, 0
	s_add_u32 s14, s2, 0xd558000
	s_addc_u32 s15, s3, 0
	s_lshl_b32 s23, s19, 3
	s_add_u32 s23, s23, s20
	s_lshl_b32 s23, s23, 7
	s_add_u32 s23, s23, s21
	s_sub_u32 s23, s23, 1
	s_lshr_b32 s25, s23, 18
	s_lshl_b32 s24, s23, 14
	s_add_u32 s24, s24, s2
	s_addc_u32 s25, s25, s3
	s_add_u32 s24, s24, 0x1d558000
	s_addc_u32 s25, s25, 0
	s_add_u32 s26, s24, 0x2000
	s_addc_u32 s27, s25, 0
	v_and_b32_e32 v5, 63, v210
	v_and_b32_e32 v6, 31, v5
	v_lshrrev_b32_e32 v7, 5, v5
	v_lshlrev_b32_e32 v26, 8, v6
	v_lshl_add_u32 v26, v7, 4, v26
	s_mul_i32 s28, s22, 0xc00
	s_lshl_b32 s29, s22, 10
	s_waitcnt vmcnt(0)
	v_add_u32_e32 v3, s28, v208
	v_add_u32_e32 v4, s29, v208
	v_add_u32_e32 v5, s29, v208
	v_mov_b32_e32 v6, 0
	v_mov_b32_e32 v7, 0
	s_cmp_eq_u32 s21, 0
	s_cbranch_scc1 .Lrwp2a_noprev
	global_load_ushort v6, v3, s[4:5] offset:-3072
	global_load_ushort v7, v3, s[4:5] offset:-2048
.Lrwp2a_noprev:
	v_mov_b32_e32 v64, 0
	v_mov_b32_e32 v65, 0
	v_mov_b32_e32 v66, 0
	v_mov_b32_e32 v67, 0
	v_mov_b32_e32 v68, 0
	v_mov_b32_e32 v69, 0
	v_mov_b32_e32 v70, 0
	v_mov_b32_e32 v71, 0
	v_mov_b32_e32 v72, 0
	v_mov_b32_e32 v73, 0
	v_mov_b32_e32 v74, 0
	v_mov_b32_e32 v75, 0
	v_mov_b32_e32 v76, 0
	v_mov_b32_e32 v77, 0
	v_mov_b32_e32 v78, 0
	v_mov_b32_e32 v79, 0
	v_mov_b32_e32 v80, 0
	v_mov_b32_e32 v81, 0
	v_mov_b32_e32 v82, 0
	v_mov_b32_e32 v83, 0
	v_mov_b32_e32 v84, 0
	v_mov_b32_e32 v85, 0
	v_mov_b32_e32 v86, 0
	v_mov_b32_e32 v87, 0
	v_mov_b32_e32 v88, 0
	v_mov_b32_e32 v89, 0
	v_mov_b32_e32 v90, 0
	v_mov_b32_e32 v91, 0
	v_mov_b32_e32 v92, 0
	v_mov_b32_e32 v93, 0
	v_mov_b32_e32 v94, 0
	v_mov_b32_e32 v95, 0
	v_mov_b32_e32 v96, 0
	v_mov_b32_e32 v97, 0
	v_mov_b32_e32 v98, 0
	v_mov_b32_e32 v99, 0
	v_mov_b32_e32 v100, 0
	v_mov_b32_e32 v101, 0
	v_mov_b32_e32 v102, 0
	v_mov_b32_e32 v103, 0
	v_mov_b32_e32 v104, 0
	v_mov_b32_e32 v105, 0
	v_mov_b32_e32 v106, 0
	v_mov_b32_e32 v107, 0
	v_mov_b32_e32 v108, 0
	v_mov_b32_e32 v109, 0
	v_mov_b32_e32 v110, 0
	v_mov_b32_e32 v111, 0
	v_mov_b32_e32 v112, 0
	v_mov_b32_e32 v113, 0
	v_mov_b32_e32 v114, 0
	v_mov_b32_e32 v115, 0
	v_mov_b32_e32 v116, 0
	v_mov_b32_e32 v117, 0
	v_mov_b32_e32 v118, 0
	v_mov_b32_e32 v119, 0
	v_mov_b32_e32 v120, 0
	v_mov_b32_e32 v121, 0
	v_mov_b32_e32 v122, 0
	v_mov_b32_e32 v123, 0
	v_mov_b32_e32 v124, 0
	v_mov_b32_e32 v125, 0
	v_mov_b32_e32 v126, 0
	v_mov_b32_e32 v127, 0
	s_cmp_eq_u32 s21, 0
	s_cbranch_scc1 .Lrwp2a_nostate
	global_load_dwordx4 v[64:67], v26, s[24:25] offset:0
	global_load_dwordx4 v[68:71], v26, s[24:25] offset:32
	global_load_dwordx4 v[72:75], v26, s[24:25] offset:64
	global_load_dwordx4 v[76:79], v26, s[24:25] offset:96
	global_load_dwordx4 v[80:83], v26, s[26:27] offset:0
	global_load_dwordx4 v[84:87], v26, s[26:27] offset:32
	global_load_dwordx4 v[88:91], v26, s[26:27] offset:64
	global_load_dwordx4 v[92:95], v26, s[26:27] offset:96
	global_load_dwordx4 v[96:99], v26, s[24:25] offset:128
	global_load_dwordx4 v[100:103], v26, s[24:25] offset:160
	global_load_dwordx4 v[104:107], v26, s[24:25] offset:192
	global_load_dwordx4 v[108:111], v26, s[24:25] offset:224
	global_load_dwordx4 v[112:115], v26, s[26:27] offset:128
	global_load_dwordx4 v[116:119], v26, s[26:27] offset:160
	global_load_dwordx4 v[120:123], v26, s[26:27] offset:192
	global_load_dwordx4 v[124:127], v26, s[26:27] offset:224
; DI float bf2f(bf16_t b) { return __uint_as_float(((unsigned)b) << 16); }
; DI float rl(float x, int l) { return __int_as_float(__builtin_amdgcn_readlane(__float_as_int(x), l)); }
; template <bool PASS2>
; DI void rwkv_item(const Params& p, int l, int item, int lane, const bf16_t* rkv, const bf16_t* lo2, float* rwst) {
;     ...
;   auto load_raw = [&](size_t tk) __attribute__((always_inline)) {
;     Raw x;
;     x.rp = rkv[tk * 1536 + ch]; x.kp = rkv[tk * 1536 + 512 + ch]; x.v = p.vbuf[tk * 512 + ch];
;     x.ew = ewb[tk * 512 + ch]; x.a = ab[tk * 512 + ch]; x.g = PASS2 ? gb[tk * 512 + ch] : (bf16_t)0;
;     return x;
;   };
;   auto derive = [&](const Raw& x, float rpp, float kpp) __attribute__((always_inline)) {
;     Der d;
;     const float rp = bf2f(x.rp), kp = bf2f(x.kp), a = bf2f(x.a);
;     d.rr = rp + (rpp - rp) * mu_r;
;     const float k = kp + (kpp - kp) * mu_k;
;     d.wdec = __expf(-bf2f(x.ew));
;     float kkv = k * kkw;
;     const float nrm = wave_sum(kkv * kkv);
;     kkv *= rsqrtf(fmaxf(nrm, 1e-24f));
;     d.kf = k * (1.f + (a - 1.f) * kaw);
;     d.av = -kkv; d.bv = kkv * a;
;     d.v = bf2f(x.v); d.gg = bf2f(x.g);
;     return d;
;   };
;   Raw rawB = load_raw(tok0);
;   Der cur = derive(rawB, rp_prev, kp_prev);
;   float rpA = bf2f(rawB.rp), kpA = bf2f(rawB.kp);
;   rawB = load_raw(tok0 + 1);
; #pragma unroll 1
;   for (int t = 0; t < LCR; t++) {
;     Raw rawC = rawB;
;     if (t + 2 < LCR) rawC = load_raw(tok0 + t + 2);
;     Der nxt = cur;
;     if (t + 1 < LCR) nxt = derive(rawB, rpA, kpA);
;     const float rr = cur.rr, wdec = cur.wdec, kf = cur.kf, av = cur.av, bv = cur.bv, v = cur.v, gg = cur.gg;
;     float sa0 = 0.f, sa1 = 0.f, pa0 = 0.f, pa1 = 0.f;
; #pragma unroll
;     for (int j = 0; j < 64; j += 2) {
;       const float a0 = rl(av, j), a1 = rl(av, j + 1);
;       sa0 += S[j] * a0; sa1 += S[j + 1] * a1;
;       if (!PASS2) { pa0 += P[j] * a0; pa1 += P[j + 1] * a1; }
;     }
;     const float sa = sa0 + sa1, pa = pa0 + pa1;
.Lrwp2a_nostate:
	global_load_ushort v160, v3, s[4:5]
	global_load_ushort v161, v3, s[4:5] offset:1024
	global_load_ushort v162, v4, s[6:7]
	global_load_ushort v163, v4, s[8:9]
	global_load_ushort v164, v4, s[10:11]
	global_load_ushort v165, v4, s[12:13]
	v_add_u32_e32 v3, 0xc00, v3
	v_add_u32_e32 v4, 0x400, v4
	global_load_ushort v166, v3, s[4:5]
	global_load_ushort v167, v3, s[4:5] offset:1024
	global_load_ushort v168, v4, s[6:7]
	global_load_ushort v169, v4, s[8:9]
	global_load_ushort v170, v4, s[10:11]
	global_load_ushort v171, v4, s[12:13]
	v_add_u32_e32 v3, 0xc00, v3
	v_add_u32_e32 v4, 0x400, v4
	global_load_ushort v172, v3, s[4:5]
	global_load_ushort v173, v3, s[4:5] offset:1024
	global_load_ushort v174, v4, s[6:7]
	global_load_ushort v175, v4, s[8:9]
	global_load_ushort v176, v4, s[10:11]
	global_load_ushort v177, v4, s[12:13]
	v_add_u32_e32 v3, 0xc00, v3
	v_add_u32_e32 v4, 0x400, v4
	global_load_ushort v178, v3, s[4:5]
	global_load_ushort v179, v3, s[4:5] offset:1024
	global_load_ushort v180, v4, s[6:7]
	global_load_ushort v181, v4, s[8:9]
	global_load_ushort v182, v4, s[10:11]
	global_load_ushort v183, v4, s[12:13]
	v_add_u32_e32 v3, 0xc00, v3
	v_add_u32_e32 v4, 0x400, v4
	s_waitcnt vmcnt(0)
	v_lshlrev_b32_e32 v6, 16, v6
	v_lshlrev_b32_e32 v7, 16, v7
	v_mov_b32_e32 v8, 1.0
	s_movk_i32 s36, 0x7fff
	v_mov_b32_e32 v207, 0x3c800000
	v_lshlrev_b32_e32 v27, 16, v161
	v_sub_f32_e32 v29, v7, v27
	v_fma_f32 v29, v29, v10, v27
	v_mov_b32_e32 v7, v27
	v_lshlrev_b32_e32 v26, 16, v160
	v_sub_f32_e32 v28, v6, v26
	v_fma_f32 v28, v28, v9, v26
	v_mov_b32_e32 v6, v26
	v_lshlrev_b32_e32 v30, 16, v163
	v_mul_f32_e32 v30, 0xbfb8aa3b, v30
	v_exp_f32_e32 v30, v30
	v_lshlrev_b32_e32 v31, 16, v164
	v_mul_f32_e32 v192, v29, v11
	v_add_f32_e32 v193, -1.0, v31
	v_fma_f32 v193, v193, v12, 1.0
	v_mul_f32_e32 v193, v29, v193
	v_mul_f32_e32 v194, v192, v192
	v_mul_f32_e32 v195, v28, v193
	v_mul_f32_e32 v195, v195, v13
	v_lshlrev_b32_e32 v22, 16, v165
	v_lshlrev_b32_e32 v20, 16, v162
	s_nop 1
	v_permlane32_swap_b32 v194, v195
	s_nop 0
	v_add_f32_e32 v194, v194, v195
	s_nop 1
	v_add_f32_dpp v194, v194, v194 quad_perm:[1,0,3,2] row_mask:0xf bank_mask:0xf
	s_nop 1
	v_add_f32_dpp v194, v194, v194 quad_perm:[2,3,0,1] row_mask:0xf bank_mask:0xf
	s_nop 1
	v_add_f32_dpp v194, v194, v194 row_half_mirror row_mask:0xf bank_mask:0xf
	s_nop 1
	v_add_f32_dpp v194, v194, v194 row_mirror row_mask:0xf bank_mask:0xf
	s_nop 1
	v_add_f32_dpp v194, v194, v194 row_bcast:15 row_mask:0xa bank_mask:0xf
	s_nop 1
	v_readlane_b32 s28, v194, 31
	v_readlane_b32 s30, v194, 63
	s_nop 1
	v_mov_b32_e32 v196, s28
	v_max_f32_e32 v196, 0x179abe15, v196
	v_rsq_f32_e32 v196, v196
	v_mov_b32_e32 v19, v20
	v_mul_f32_e32 v192, v192, v196
	v_mul_f32_e64 v24, -v192, v8
	v_mul_f32_e32 v197, v192, v31
	v_mul_f32_e32 v8, v8, v30
	v_rcp_f32_e32 v198, v8
	v_mul_f32_e32 v25, v8, v28
	v_mul_f32_e32 v16, v197, v198
	v_mul_f32_e32 v17, v193, v198
	s_nop 1
	v_permlane32_swap_b32 v16, v17
	ds_write_b32 v1, v24
	ds_write_b32 v1, v25 offset:256
	ds_read_b128 v[32:35], v2 offset:0
	ds_read_b128 v[36:39], v2 offset:32
	ds_read_b128 v[40:43], v2 offset:64
	ds_read_b128 v[44:47], v2 offset:96
	ds_read_b128 v[48:51], v2 offset:128
	ds_read_b128 v[52:55], v2 offset:160
	ds_read_b128 v[56:59], v2 offset:192
	ds_read_b128 v[60:63], v2 offset:224
	s_waitcnt lgkmcnt(7)
	v_pk_mul_f32 v[184:185], v[64:65], v[32:33]
	v_pk_mul_f32 v[186:187], v[80:81], v[32:33]
	v_pk_fma_f32 v[184:185], v[66:67], v[34:35], v[184:185]
	v_pk_fma_f32 v[186:187], v[82:83], v[34:35], v[186:187]
	s_waitcnt lgkmcnt(6)
	v_pk_fma_f32 v[184:185], v[68:69], v[36:37], v[184:185]
	v_pk_fma_f32 v[186:187], v[84:85], v[36:37], v[186:187]
	v_pk_fma_f32 v[184:185], v[70:71], v[38:39], v[184:185]
	v_pk_fma_f32 v[186:187], v[86:87], v[38:39], v[186:187]
	s_waitcnt lgkmcnt(5)
	v_pk_fma_f32 v[184:185], v[72:73], v[40:41], v[184:185]
	v_pk_fma_f32 v[186:187], v[88:89], v[40:41], v[186:187]
	v_pk_fma_f32 v[184:185], v[74:75], v[42:43], v[184:185]
	v_pk_fma_f32 v[186:187], v[90:91], v[42:43], v[186:187]
	s_waitcnt lgkmcnt(4)
	v_pk_fma_f32 v[184:185], v[76:77], v[44:45], v[184:185]
	v_pk_fma_f32 v[186:187], v[92:93], v[44:45], v[186:187]
	v_pk_fma_f32 v[184:185], v[78:79], v[46:47], v[184:185]
	v_pk_fma_f32 v[186:187], v[94:95], v[46:47], v[186:187]
	s_waitcnt lgkmcnt(3)
	v_pk_fma_f32 v[184:185], v[96:97], v[48:49], v[184:185]
	v_pk_fma_f32 v[186:187], v[112:113], v[48:49], v[186:187]
	v_pk_fma_f32 v[184:185], v[98:99], v[50:51], v[184:185]
	v_pk_fma_f32 v[186:187], v[114:115], v[50:51], v[186:187]
	s_waitcnt lgkmcnt(2)
	v_pk_fma_f32 v[184:185], v[100:101], v[52:53], v[184:185]
	v_pk_fma_f32 v[186:187], v[116:117], v[52:53], v[186:187]
	v_pk_fma_f32 v[184:185], v[102:103], v[54:55], v[184:185]
	v_pk_fma_f32 v[186:187], v[118:119], v[54:55], v[186:187]
	s_waitcnt lgkmcnt(1)
	v_pk_fma_f32 v[184:185], v[104:105], v[56:57], v[184:185]
	v_pk_fma_f32 v[186:187], v[120:121], v[56:57], v[186:187]
	v_pk_fma_f32 v[184:185], v[106:107], v[58:59], v[184:185]
	v_pk_fma_f32 v[186:187], v[122:123], v[58:59], v[186:187]
	s_waitcnt lgkmcnt(0)
	v_pk_fma_f32 v[184:185], v[108:109], v[60:61], v[184:185]
	v_pk_fma_f32 v[186:187], v[124:125], v[60:61], v[186:187]
	v_pk_fma_f32 v[184:185], v[110:111], v[62:63], v[184:185]
	v_pk_fma_f32 v[186:187], v[126:127], v[62:63], v[186:187]
	v_add_f32_e32 v18, v184, v185
	v_add_f32_e32 v200, v186, v187
	s_nop 1
	v_permlane32_swap_b32 v18, v200
	s_nop 0
	v_add_f32_e32 v18, v18, v200
	s_mov_b32 s18, 0
; DI float rl(float x, int l) { return __int_as_float(__builtin_amdgcn_readlane(__float_as_int(x), l)); }
; template <bool PASS2>
; DI void rwkv_item(const Params& p, int l, int item, int lane, const bf16_t* rkv, const bf16_t* lo2, float* rwst) {
;     ...
;   for (int t = 0; t < LCR; t++) {
;     Raw rawC = rawB;
;     if (t + 2 < LCR) rawC = load_raw(tok0 + t + 2);
;     Der nxt = cur;
;     if (t + 1 < LCR) nxt = derive(rawB, rpA, kpA);
;     const float rr = cur.rr, wdec = cur.wdec, kf = cur.kf, av = cur.av, bv = cur.bv, v = cur.v, gg = cur.gg;
;     float sa0 = 0.f, sa1 = 0.f, pa0 = 0.f, pa1 = 0.f;
; #pragma unroll
;     for (int j = 0; j < 64; j += 2) {
;       const float a0 = rl(av, j), a1 = rl(av, j + 1);
;       sa0 += S[j] * a0; sa1 += S[j + 1] * a1;
;       if (!PASS2) { pa0 += P[j] * a0; pa1 += P[j + 1] * a1; }
;     }
;     const float sa = sa0 + sa1, pa = pa0 + pa1;
;     float y0 = 0.f, y1 = 0.f;
; #pragma unroll
;     for (int j = 0; j < 64; j += 2) {
;       const float w0 = rl(wdec, j), b0 = rl(bv, j), k0 = rl(kf, j);
;       const float w1 = rl(wdec, j + 1), b1 = rl(bv, j + 1), k1 = rl(kf, j + 1);
;       S[j] = S[j] * w0 + sa * b0 + v * k0;
;       S[j + 1] = S[j + 1] * w1 + sa * b1 + v * k1;
;       if (!PASS2) {
;         P[j] = P[j] * w0 + pa * b0;
;         P[j + 1] = P[j + 1] * w1 + pa * b1;
;       } else {
;         y0 += S[j] * rl(rr, j); y1 += S[j + 1] * rl(rr, j + 1);
;       }
;     }
.Lrwp2a_loop:
	s_nop 1
	v_permlane32_swap_b32 v18, v19
	s_nop 1
	v_mfma_f32_32x32x2_f32 v[64:79], v16, v18, v[64:79]
	v_mfma_f32_32x32x2_f32 v[80:95], v16, v19, v[80:95]
	v_mfma_f32_32x32x2_f32 v[96:111], v17, v18, v[96:111]
	v_mfma_f32_32x32x2_f32 v[112:127], v17, v19, v[112:127]
	global_load_ushort v160, v3, s[4:5]
	global_load_ushort v161, v3, s[4:5] offset:1024
	global_load_ushort v162, v4, s[6:7]
	global_load_ushort v163, v4, s[8:9]
	global_load_ushort v164, v4, s[10:11]
	global_load_ushort v165, v4, s[12:13]
	v_add_u32_e32 v3, 0xc00, v3
	v_add_u32_e32 v4, 0x400, v4
	s_waitcnt vmcnt(21)
	v_lshlrev_b32_e32 v27, 16, v167
	v_sub_f32_e32 v29, v7, v27
	v_fma_f32 v29, v29, v10, v27
	v_mov_b32_e32 v7, v27
	v_lshlrev_b32_e32 v26, 16, v166
	v_sub_f32_e32 v28, v6, v26
	v_fma_f32 v28, v28, v9, v26
	v_mov_b32_e32 v6, v26
	v_lshlrev_b32_e32 v30, 16, v169
	v_mul_f32_e32 v30, 0xbfb8aa3b, v30
	v_exp_f32_e32 v30, v30
	v_lshlrev_b32_e32 v31, 16, v170
	v_mul_f32_e32 v192, v29, v11
	v_add_f32_e32 v193, -1.0, v31
	v_fma_f32 v193, v193, v12, 1.0
	v_mul_f32_e32 v193, v29, v193
	v_mul_f32_e32 v194, v192, v192
	v_mul_f32_e32 v195, v28, v193
	v_mul_f32_e32 v195, v195, v13
	v_lshlrev_b32_e32 v23, 16, v171
	v_lshlrev_b32_e32 v21, 16, v168
	s_nop 1
	v_permlane32_swap_b32 v194, v195
	s_nop 0
	v_add_f32_e32 v194, v194, v195
	s_nop 1
	v_add_f32_dpp v194, v194, v194 quad_perm:[1,0,3,2] row_mask:0xf bank_mask:0xf
	s_nop 1
	v_add_f32_dpp v194, v194, v194 quad_perm:[2,3,0,1] row_mask:0xf bank_mask:0xf
	s_nop 1
	v_add_f32_dpp v194, v194, v194 row_half_mirror row_mask:0xf bank_mask:0xf
	s_nop 1
	v_add_f32_dpp v194, v194, v194 row_mirror row_mask:0xf bank_mask:0xf
	s_nop 1
	v_add_f32_dpp v194, v194, v194 row_bcast:15 row_mask:0xa bank_mask:0xf
	s_nop 1
	v_readlane_b32 s28, v194, 31
	v_readlane_b32 s31, v194, 63
	s_nop 1
	v_mov_b32_e32 v196, s28
	v_max_f32_e32 v196, 0x179abe15, v196
	v_rsq_f32_e32 v196, v196
	v_mov_b32_e32 v19, v21
	v_mul_f32_e32 v192, v192, v196
	v_mul_f32_e64 v24, -v192, v8
	v_mul_f32_e32 v197, v192, v31
	v_mul_f32_e32 v8, v8, v30
	v_rcp_f32_e32 v198, v8
	v_mul_f32_e32 v25, v8, v28
	v_mul_f32_e32 v16, v197, v198
	v_mul_f32_e32 v17, v193, v198
	s_nop 1
	v_permlane32_swap_b32 v16, v17
	ds_write_b32 v1, v24
	ds_write_b32 v1, v25 offset:512
	ds_read_b128 v[32:35], v2 offset:0
	ds_read_b128 v[128:131], v2 offset:256
	ds_read_b128 v[36:39], v2 offset:32
	ds_read_b128 v[132:135], v2 offset:288
	ds_read_b128 v[40:43], v2 offset:64
	ds_read_b128 v[136:139], v2 offset:320
	ds_read_b128 v[44:47], v2 offset:96
	ds_read_b128 v[140:143], v2 offset:352
	ds_read_b128 v[48:51], v2 offset:128
	ds_read_b128 v[144:147], v2 offset:384
	ds_read_b128 v[52:55], v2 offset:160
	ds_read_b128 v[148:151], v2 offset:416
	ds_read_b128 v[56:59], v2 offset:192
	ds_read_b128 v[152:155], v2 offset:448
	ds_read_b128 v[60:63], v2 offset:224
	ds_read_b128 v[156:159], v2 offset:480
	s_waitcnt lgkmcnt(14)
	v_pk_mul_f32 v[184:185], v[64:65], v[32:33]
	v_pk_mul_f32 v[188:189], v[64:65], v[128:129]
	v_pk_mul_f32 v[186:187], v[80:81], v[32:33]
	v_pk_mul_f32 v[190:191], v[80:81], v[128:129]
	v_pk_fma_f32 v[184:185], v[66:67], v[34:35], v[184:185]
	v_pk_fma_f32 v[188:189], v[66:67], v[130:131], v[188:189]
	v_pk_fma_f32 v[186:187], v[82:83], v[34:35], v[186:187]
	v_pk_fma_f32 v[190:191], v[82:83], v[130:131], v[190:191]
	s_waitcnt lgkmcnt(12)
	v_pk_fma_f32 v[184:185], v[68:69], v[36:37], v[184:185]
	v_pk_fma_f32 v[188:189], v[68:69], v[132:133], v[188:189]
	v_pk_fma_f32 v[186:187], v[84:85], v[36:37], v[186:187]
	v_pk_fma_f32 v[190:191], v[84:85], v[132:133], v[190:191]
	v_pk_fma_f32 v[184:185], v[70:71], v[38:39], v[184:185]
	v_pk_fma_f32 v[188:189], v[70:71], v[134:135], v[188:189]
	v_pk_fma_f32 v[186:187], v[86:87], v[38:39], v[186:187]
	v_pk_fma_f32 v[190:191], v[86:87], v[134:135], v[190:191]
	s_waitcnt lgkmcnt(10)
	v_pk_fma_f32 v[184:185], v[72:73], v[40:41], v[184:185]
	v_pk_fma_f32 v[188:189], v[72:73], v[136:137], v[188:189]
	v_pk_fma_f32 v[186:187], v[88:89], v[40:41], v[186:187]
	v_pk_fma_f32 v[190:191], v[88:89], v[136:137], v[190:191]
	v_pk_fma_f32 v[184:185], v[74:75], v[42:43], v[184:185]
	v_pk_fma_f32 v[188:189], v[74:75], v[138:139], v[188:189]
	v_pk_fma_f32 v[186:187], v[90:91], v[42:43], v[186:187]
	v_pk_fma_f32 v[190:191], v[90:91], v[138:139], v[190:191]
	s_waitcnt lgkmcnt(8)
	v_pk_fma_f32 v[184:185], v[76:77], v[44:45], v[184:185]
	v_pk_fma_f32 v[188:189], v[76:77], v[140:141], v[188:189]
	v_pk_fma_f32 v[186:187], v[92:93], v[44:45], v[186:187]
	v_pk_fma_f32 v[190:191], v[92:93], v[140:141], v[190:191]
	v_pk_fma_f32 v[184:185], v[78:79], v[46:47], v[184:185]
	v_pk_fma_f32 v[188:189], v[78:79], v[142:143], v[188:189]
	v_pk_fma_f32 v[186:187], v[94:95], v[46:47], v[186:187]
	v_pk_fma_f32 v[190:191], v[94:95], v[142:143], v[190:191]
	s_waitcnt lgkmcnt(6)
	v_pk_fma_f32 v[184:185], v[96:97], v[48:49], v[184:185]
	v_pk_fma_f32 v[188:189], v[96:97], v[144:145], v[188:189]
	v_pk_fma_f32 v[186:187], v[112:113], v[48:49], v[186:187]
	v_pk_fma_f32 v[190:191], v[112:113], v[144:145], v[190:191]
	v_pk_fma_f32 v[184:185], v[98:99], v[50:51], v[184:185]
	v_pk_fma_f32 v[188:189], v[98:99], v[146:147], v[188:189]
	v_pk_fma_f32 v[186:187], v[114:115], v[50:51], v[186:187]
	v_pk_fma_f32 v[190:191], v[114:115], v[146:147], v[190:191]
	s_waitcnt lgkmcnt(4)
	v_pk_fma_f32 v[184:185], v[100:101], v[52:53], v[184:185]
	v_pk_fma_f32 v[188:189], v[100:101], v[148:149], v[188:189]
	v_pk_fma_f32 v[186:187], v[116:117], v[52:53], v[186:187]
	v_pk_fma_f32 v[190:191], v[116:117], v[148:149], v[190:191]
	v_pk_fma_f32 v[184:185], v[102:103], v[54:55], v[184:185]
	v_pk_fma_f32 v[188:189], v[102:103], v[150:151], v[188:189]
	v_pk_fma_f32 v[186:187], v[118:119], v[54:55], v[186:187]
	v_pk_fma_f32 v[190:191], v[118:119], v[150:151], v[190:191]
	s_waitcnt lgkmcnt(2)
; DI bf16_t f2bf(float x) { unsigned u = __float_as_uint(x); u += 0x7fffu + ((u >> 16) & 1u); return (bf16_t)(u >> 16); }
; DI float rl(float x, int l) { return __int_as_float(__builtin_amdgcn_readlane(__float_as_int(x), l)); }
; template <bool PASS2>
; DI void rwkv_item(const Params& p, int l, int item, int lane, const bf16_t* rkv, const bf16_t* lo2, float* rwst) {
;     ...
;     float y0 = 0.f, y1 = 0.f;
; #pragma unroll
;     for (int j = 0; j < 64; j += 2) {
;       const float w0 = rl(wdec, j), b0 = rl(bv, j), k0 = rl(kf, j);
;       const float w1 = rl(wdec, j + 1), b1 = rl(bv, j + 1), k1 = rl(kf, j + 1);
;       S[j] = S[j] * w0 + sa * b0 + v * k0;
;       S[j + 1] = S[j + 1] * w1 + sa * b1 + v * k1;
;       if (!PASS2) {
;         P[j] = P[j] * w0 + pa * b0;
;         P[j + 1] = P[j + 1] * w1 + pa * b1;
;       } else {
;         y0 += S[j] * rl(rr, j); y1 += S[j + 1] * rl(rr, j + 1);
;       }
;     }
;     if (PASS2) {
;       const float y = y0 + y1;
;       float s1 = y, s2 = y * y, s3 = rr * kf * rkw;
; #pragma unroll
;       for (int off = 32; off >= 1; off >>= 1) {
;         const float t1 = __shfl_xor(s1, off), t2 = __shfl_xor(s2, off), t3 = __shfl_xor(s3, off);
;         s1 += t1; s2 += t2; s3 += t3;
;       }
;       const float mean = s1 * (1.f / 64.f);
;       const float var = fmaxf(s2 * (1.f / 64.f) - mean * mean, 0.f);
;       const float yn = (y - mean) * rsqrtf(var + 64e-5f) * gnw + gnb;
;       const float bs = s3;
;       p.yc[(tok0 + t) * 512 + ch] = f2bf((yn + bs * v) * gg);
	v_pk_fma_f32 v[184:185], v[104:105], v[56:57], v[184:185]
	v_pk_fma_f32 v[188:189], v[104:105], v[152:153], v[188:189]
	v_pk_fma_f32 v[186:187], v[120:121], v[56:57], v[186:187]
	v_pk_fma_f32 v[190:191], v[120:121], v[152:153], v[190:191]
	v_pk_fma_f32 v[184:185], v[106:107], v[58:59], v[184:185]
	v_pk_fma_f32 v[188:189], v[106:107], v[154:155], v[188:189]
	v_pk_fma_f32 v[186:187], v[122:123], v[58:59], v[186:187]
	v_pk_fma_f32 v[190:191], v[122:123], v[154:155], v[190:191]
	s_waitcnt lgkmcnt(0)
	v_pk_fma_f32 v[184:185], v[108:109], v[60:61], v[184:185]
	v_pk_fma_f32 v[188:189], v[108:109], v[156:157], v[188:189]
	v_pk_fma_f32 v[186:187], v[124:125], v[60:61], v[186:187]
	v_pk_fma_f32 v[190:191], v[124:125], v[156:157], v[190:191]
	v_pk_fma_f32 v[184:185], v[110:111], v[62:63], v[184:185]
	v_pk_fma_f32 v[188:189], v[110:111], v[158:159], v[188:189]
	v_pk_fma_f32 v[186:187], v[126:127], v[62:63], v[186:187]
	v_pk_fma_f32 v[190:191], v[126:127], v[158:159], v[190:191]
	v_add_f32_e32 v18, v184, v185
	v_add_f32_e32 v200, v186, v187
	s_nop 1
	v_permlane32_swap_b32 v18, v200
	s_nop 0
	v_add_f32_e32 v18, v18, v200
	v_add_f32_e32 v201, v188, v189
	v_add_f32_e32 v202, v190, v191
	s_nop 1
	v_permlane32_swap_b32 v201, v202
	s_nop 0
	v_add_f32_e32 v201, v201, v202
	v_mul_f32_e32 v203, v201, v201
	v_mov_b32_e32 v204, v201
	s_nop 1
	v_permlane32_swap_b32 v204, v203
	s_nop 0
	v_add_f32_e32 v204, v204, v203
	s_nop 1
	v_add_f32_dpp v204, v204, v204 quad_perm:[1,0,3,2] row_mask:0xf bank_mask:0xf
	s_nop 1
	v_add_f32_dpp v204, v204, v204 quad_perm:[2,3,0,1] row_mask:0xf bank_mask:0xf
	s_nop 1
	v_add_f32_dpp v204, v204, v204 row_half_mirror row_mask:0xf bank_mask:0xf
	s_nop 1
	v_add_f32_dpp v204, v204, v204 row_mirror row_mask:0xf bank_mask:0xf
	s_nop 1
	v_add_f32_dpp v204, v204, v204 row_bcast:15 row_mask:0xa bank_mask:0xf
	s_nop 1
	v_readlane_b32 s34, v204, 31
	v_readlane_b32 s35, v204, 63
	s_nop 1
	v_mul_f32_e32 v205, s34, v207
	v_mul_f32_e32 v206, s35, v207
	v_fma_f32 v206, -v205, v205, v206
	v_max_f32_e32 v206, 0, v206
	v_add_f32_e32 v206, 0x3a27c5ac, v206
	v_rsq_f32_e32 v206, v206
	v_sub_f32_e32 v205, v201, v205
	v_mul_f32_e32 v205, v205, v206
	v_fma_f32 v205, v205, v14, v15
	v_fma_f32 v205, s30, v20, v205
	v_mul_f32_e32 v205, v205, v22
	v_bfe_u32 v206, v205, 16, 1
	v_add3_u32 v205, v205, v206, s36
	global_store_short_d16_hi v5, v205, s[14:15]
	v_add_u32_e32 v5, 0x400, v5
	s_nop 1
	v_permlane32_swap_b32 v18, v19
	s_nop 1
	v_mfma_f32_32x32x2_f32 v[64:79], v16, v18, v[64:79]
	v_mfma_f32_32x32x2_f32 v[80:95], v16, v19, v[80:95]
	v_mfma_f32_32x32x2_f32 v[96:111], v17, v18, v[96:111]
	v_mfma_f32_32x32x2_f32 v[112:127], v17, v19, v[112:127]
	global_load_ushort v166, v3, s[4:5]
	global_load_ushort v167, v3, s[4:5] offset:1024
	global_load_ushort v168, v4, s[6:7]
	global_load_ushort v169, v4, s[8:9]
	global_load_ushort v170, v4, s[10:11]
	global_load_ushort v171, v4, s[12:13]
	v_add_u32_e32 v3, 0xc00, v3
	v_add_u32_e32 v4, 0x400, v4
	s_waitcnt vmcnt(21)
	v_lshlrev_b32_e32 v27, 16, v173
	v_sub_f32_e32 v29, v7, v27
	v_fma_f32 v29, v29, v10, v27
	v_mov_b32_e32 v7, v27
	v_lshlrev_b32_e32 v26, 16, v172
	v_sub_f32_e32 v28, v6, v26
	v_fma_f32 v28, v28, v9, v26
	v_mov_b32_e32 v6, v26
	v_lshlrev_b32_e32 v30, 16, v175
	v_mul_f32_e32 v30, 0xbfb8aa3b, v30
	v_exp_f32_e32 v30, v30
	v_lshlrev_b32_e32 v31, 16, v176
	v_mul_f32_e32 v192, v29, v11
	v_add_f32_e32 v193, -1.0, v31
	v_fma_f32 v193, v193, v12, 1.0
	v_mul_f32_e32 v193, v29, v193
	v_mul_f32_e32 v194, v192, v192
	v_mul_f32_e32 v195, v28, v193
	v_mul_f32_e32 v195, v195, v13
	v_lshlrev_b32_e32 v22, 16, v177
	v_lshlrev_b32_e32 v20, 16, v174
	s_nop 1
	v_permlane32_swap_b32 v194, v195
	s_nop 0
	v_add_f32_e32 v194, v194, v195
	s_nop 1
	v_add_f32_dpp v194, v194, v194 quad_perm:[1,0,3,2] row_mask:0xf bank_mask:0xf
	s_nop 1
	v_add_f32_dpp v194, v194, v194 quad_perm:[2,3,0,1] row_mask:0xf bank_mask:0xf
	s_nop 1
	v_add_f32_dpp v194, v194, v194 row_half_mirror row_mask:0xf bank_mask:0xf
	s_nop 1
	v_add_f32_dpp v194, v194, v194 row_mirror row_mask:0xf bank_mask:0xf
	s_nop 1
	v_add_f32_dpp v194, v194, v194 row_bcast:15 row_mask:0xa bank_mask:0xf
	s_nop 1
	v_readlane_b32 s28, v194, 31
	v_readlane_b32 s30, v194, 63
	s_nop 1
	v_mov_b32_e32 v196, s28
	v_max_f32_e32 v196, 0x179abe15, v196
	v_rsq_f32_e32 v196, v196
	v_mov_b32_e32 v19, v20
	v_mul_f32_e32 v192, v192, v196
	v_mul_f32_e64 v24, -v192, v8
	v_mul_f32_e32 v197, v192, v31
	v_mul_f32_e32 v8, v8, v30
	v_rcp_f32_e32 v198, v8
	v_mul_f32_e32 v25, v8, v28
	v_mul_f32_e32 v16, v197, v198
	v_mul_f32_e32 v17, v193, v198
	s_nop 1
	v_permlane32_swap_b32 v16, v17
	ds_write_b32 v1, v24
	ds_write_b32 v1, v25 offset:256
	ds_read_b128 v[32:35], v2 offset:0
	ds_read_b128 v[128:131], v2 offset:512
	ds_read_b128 v[36:39], v2 offset:32
	ds_read_b128 v[132:135], v2 offset:544
	ds_read_b128 v[40:43], v2 offset:64
	ds_read_b128 v[136:139], v2 offset:576
	ds_read_b128 v[44:47], v2 offset:96
	ds_read_b128 v[140:143], v2 offset:608
	ds_read_b128 v[48:51], v2 offset:128
	ds_read_b128 v[144:147], v2 offset:640
	ds_read_b128 v[52:55], v2 offset:160
	ds_read_b128 v[148:151], v2 offset:672
	ds_read_b128 v[56:59], v2 offset:192
	ds_read_b128 v[152:155], v2 offset:704
	ds_read_b128 v[60:63], v2 offset:224
	ds_read_b128 v[156:159], v2 offset:736
	s_waitcnt lgkmcnt(14)
	v_pk_mul_f32 v[184:185], v[64:65], v[32:33]
	v_pk_mul_f32 v[188:189], v[64:65], v[128:129]
	v_pk_mul_f32 v[186:187], v[80:81], v[32:33]
	v_pk_mul_f32 v[190:191], v[80:81], v[128:129]
	v_pk_fma_f32 v[184:185], v[66:67], v[34:35], v[184:185]
	v_pk_fma_f32 v[188:189], v[66:67], v[130:131], v[188:189]
	v_pk_fma_f32 v[186:187], v[82:83], v[34:35], v[186:187]
	v_pk_fma_f32 v[190:191], v[82:83], v[130:131], v[190:191]
	s_waitcnt lgkmcnt(12)
; DI bf16_t f2bf(float x) { unsigned u = __float_as_uint(x); u += 0x7fffu + ((u >> 16) & 1u); return (bf16_t)(u >> 16); }
; DI float bf2f(bf16_t b) { return __uint_as_float(((unsigned)b) << 16); }
; DI float rl(float x, int l) { return __int_as_float(__builtin_amdgcn_readlane(__float_as_int(x), l)); }
; template <bool PASS2>
; DI void rwkv_item(const Params& p, int l, int item, int lane, const bf16_t* rkv, const bf16_t* lo2, float* rwst) {
;     ...
; #pragma unroll
;     for (int j = 0; j < 64; j += 2) {
;       const float a0 = rl(av, j), a1 = rl(av, j + 1);
;       sa0 += S[j] * a0; sa1 += S[j + 1] * a1;
;       if (!PASS2) { pa0 += P[j] * a0; pa1 += P[j + 1] * a1; }
;     }
;     const float sa = sa0 + sa1, pa = pa0 + pa1;
;     float y0 = 0.f, y1 = 0.f;
; #pragma unroll
;     for (int j = 0; j < 64; j += 2) {
;       const float w0 = rl(wdec, j), b0 = rl(bv, j), k0 = rl(kf, j);
;       const float w1 = rl(wdec, j + 1), b1 = rl(bv, j + 1), k1 = rl(kf, j + 1);
;       S[j] = S[j] * w0 + sa * b0 + v * k0;
;       S[j + 1] = S[j + 1] * w1 + sa * b1 + v * k1;
;       if (!PASS2) {
;         P[j] = P[j] * w0 + pa * b0;
;         P[j + 1] = P[j + 1] * w1 + pa * b1;
;       } else {
;         y0 += S[j] * rl(rr, j); y1 += S[j + 1] * rl(rr, j + 1);
;       }
;     }
;     if (PASS2) {
;       const float y = y0 + y1;
;       float s1 = y, s2 = y * y, s3 = rr * kf * rkw;
; #pragma unroll
;       for (int off = 32; off >= 1; off >>= 1) {
;         const float t1 = __shfl_xor(s1, off), t2 = __shfl_xor(s2, off), t3 = __shfl_xor(s3, off);
;         s1 += t1; s2 += t2; s3 += t3;
;       }
;       const float mean = s1 * (1.f / 64.f);
;       const float var = fmaxf(s2 * (1.f / 64.f) - mean * mean, 0.f);
;       const float yn = (y - mean) * rsqrtf(var + 64e-5f) * gnw + gnb;
;       const float bs = s3;
;       p.yc[(tok0 + t) * 512 + ch] = f2bf((yn + bs * v) * gg);
;     }
;     rpA = bf2f(rawB.rp); kpA = bf2f(rawB.kp); rawB = rawC; cur = nxt;
	v_pk_fma_f32 v[184:185], v[68:69], v[36:37], v[184:185]
	v_pk_fma_f32 v[188:189], v[68:69], v[132:133], v[188:189]
	v_pk_fma_f32 v[186:187], v[84:85], v[36:37], v[186:187]
	v_pk_fma_f32 v[190:191], v[84:85], v[132:133], v[190:191]
	v_pk_fma_f32 v[184:185], v[70:71], v[38:39], v[184:185]
	v_pk_fma_f32 v[188:189], v[70:71], v[134:135], v[188:189]
	v_pk_fma_f32 v[186:187], v[86:87], v[38:39], v[186:187]
	v_pk_fma_f32 v[190:191], v[86:87], v[134:135], v[190:191]
	s_waitcnt lgkmcnt(10)
	v_pk_fma_f32 v[184:185], v[72:73], v[40:41], v[184:185]
	v_pk_fma_f32 v[188:189], v[72:73], v[136:137], v[188:189]
	v_pk_fma_f32 v[186:187], v[88:89], v[40:41], v[186:187]
	v_pk_fma_f32 v[190:191], v[88:89], v[136:137], v[190:191]
	v_pk_fma_f32 v[184:185], v[74:75], v[42:43], v[184:185]
	v_pk_fma_f32 v[188:189], v[74:75], v[138:139], v[188:189]
	v_pk_fma_f32 v[186:187], v[90:91], v[42:43], v[186:187]
	v_pk_fma_f32 v[190:191], v[90:91], v[138:139], v[190:191]
	s_waitcnt lgkmcnt(8)
	v_pk_fma_f32 v[184:185], v[76:77], v[44:45], v[184:185]
	v_pk_fma_f32 v[188:189], v[76:77], v[140:141], v[188:189]
	v_pk_fma_f32 v[186:187], v[92:93], v[44:45], v[186:187]
	v_pk_fma_f32 v[190:191], v[92:93], v[140:141], v[190:191]
	v_pk_fma_f32 v[184:185], v[78:79], v[46:47], v[184:185]
	v_pk_fma_f32 v[188:189], v[78:79], v[142:143], v[188:189]
	v_pk_fma_f32 v[186:187], v[94:95], v[46:47], v[186:187]
	v_pk_fma_f32 v[190:191], v[94:95], v[142:143], v[190:191]
	s_waitcnt lgkmcnt(6)
	v_pk_fma_f32 v[184:185], v[96:97], v[48:49], v[184:185]
	v_pk_fma_f32 v[188:189], v[96:97], v[144:145], v[188:189]
	v_pk_fma_f32 v[186:187], v[112:113], v[48:49], v[186:187]
	v_pk_fma_f32 v[190:191], v[112:113], v[144:145], v[190:191]
	v_pk_fma_f32 v[184:185], v[98:99], v[50:51], v[184:185]
	v_pk_fma_f32 v[188:189], v[98:99], v[146:147], v[188:189]
	v_pk_fma_f32 v[186:187], v[114:115], v[50:51], v[186:187]
	v_pk_fma_f32 v[190:191], v[114:115], v[146:147], v[190:191]
	s_waitcnt lgkmcnt(4)
	v_pk_fma_f32 v[184:185], v[100:101], v[52:53], v[184:185]
	v_pk_fma_f32 v[188:189], v[100:101], v[148:149], v[188:189]
	v_pk_fma_f32 v[186:187], v[116:117], v[52:53], v[186:187]
	v_pk_fma_f32 v[190:191], v[116:117], v[148:149], v[190:191]
	v_pk_fma_f32 v[184:185], v[102:103], v[54:55], v[184:185]
	v_pk_fma_f32 v[188:189], v[102:103], v[150:151], v[188:189]
	v_pk_fma_f32 v[186:187], v[118:119], v[54:55], v[186:187]
	v_pk_fma_f32 v[190:191], v[118:119], v[150:151], v[190:191]
	s_waitcnt lgkmcnt(2)
	v_pk_fma_f32 v[184:185], v[104:105], v[56:57], v[184:185]
	v_pk_fma_f32 v[188:189], v[104:105], v[152:153], v[188:189]
	v_pk_fma_f32 v[186:187], v[120:121], v[56:57], v[186:187]
	v_pk_fma_f32 v[190:191], v[120:121], v[152:153], v[190:191]
	v_pk_fma_f32 v[184:185], v[106:107], v[58:59], v[184:185]
	v_pk_fma_f32 v[188:189], v[106:107], v[154:155], v[188:189]
	v_pk_fma_f32 v[186:187], v[122:123], v[58:59], v[186:187]
	v_pk_fma_f32 v[190:191], v[122:123], v[154:155], v[190:191]
	s_waitcnt lgkmcnt(0)
	v_pk_fma_f32 v[184:185], v[108:109], v[60:61], v[184:185]
	v_pk_fma_f32 v[188:189], v[108:109], v[156:157], v[188:189]
	v_pk_fma_f32 v[186:187], v[124:125], v[60:61], v[186:187]
	v_pk_fma_f32 v[190:191], v[124:125], v[156:157], v[190:191]
	v_pk_fma_f32 v[184:185], v[110:111], v[62:63], v[184:185]
	v_pk_fma_f32 v[188:189], v[110:111], v[158:159], v[188:189]
	v_pk_fma_f32 v[186:187], v[126:127], v[62:63], v[186:187]
	v_pk_fma_f32 v[190:191], v[126:127], v[158:159], v[190:191]
	v_add_f32_e32 v18, v184, v185
	v_add_f32_e32 v200, v186, v187
	s_nop 1
	v_permlane32_swap_b32 v18, v200
	s_nop 0
	v_add_f32_e32 v18, v18, v200
	v_add_f32_e32 v201, v188, v189
	v_add_f32_e32 v202, v190, v191
	s_nop 1
	v_permlane32_swap_b32 v201, v202
	s_nop 0
	v_add_f32_e32 v201, v201, v202
	v_mul_f32_e32 v203, v201, v201
	v_mov_b32_e32 v204, v201
	s_nop 1
	v_permlane32_swap_b32 v204, v203
	s_nop 0
	v_add_f32_e32 v204, v204, v203
	s_nop 1
	v_add_f32_dpp v204, v204, v204 quad_perm:[1,0,3,2] row_mask:0xf bank_mask:0xf
	s_nop 1
	v_add_f32_dpp v204, v204, v204 quad_perm:[2,3,0,1] row_mask:0xf bank_mask:0xf
	s_nop 1
	v_add_f32_dpp v204, v204, v204 row_half_mirror row_mask:0xf bank_mask:0xf
	s_nop 1
	v_add_f32_dpp v204, v204, v204 row_mirror row_mask:0xf bank_mask:0xf
	s_nop 1
	v_add_f32_dpp v204, v204, v204 row_bcast:15 row_mask:0xa bank_mask:0xf
	s_nop 1
	v_readlane_b32 s34, v204, 31
	v_readlane_b32 s35, v204, 63
	s_nop 1
	v_mul_f32_e32 v205, s34, v207
	v_mul_f32_e32 v206, s35, v207
	v_fma_f32 v206, -v205, v205, v206
	v_max_f32_e32 v206, 0, v206
	v_add_f32_e32 v206, 0x3a27c5ac, v206
	v_rsq_f32_e32 v206, v206
	v_sub_f32_e32 v205, v201, v205
	v_mul_f32_e32 v205, v205, v206
	v_fma_f32 v205, v205, v14, v15
	v_fma_f32 v205, s31, v21, v205
	v_mul_f32_e32 v205, v205, v23
	v_bfe_u32 v206, v205, 16, 1
	v_add3_u32 v205, v205, v206, s36
	global_store_short_d16_hi v5, v205, s[14:15]
	v_add_u32_e32 v5, 0x400, v5
	s_nop 1
	v_permlane32_swap_b32 v18, v19
	s_nop 1
	v_mfma_f32_32x32x2_f32 v[64:79], v16, v18, v[64:79]
	v_mfma_f32_32x32x2_f32 v[80:95], v16, v19, v[80:95]
	v_mfma_f32_32x32x2_f32 v[96:111], v17, v18, v[96:111]
	v_mfma_f32_32x32x2_f32 v[112:127], v17, v19, v[112:127]
	global_load_ushort v172, v3, s[4:5]
	global_load_ushort v173, v3, s[4:5] offset:1024
	global_load_ushort v174, v4, s[6:7]
	global_load_ushort v175, v4, s[8:9]
	global_load_ushort v176, v4, s[10:11]
	global_load_ushort v177, v4, s[12:13]
	v_add_u32_e32 v3, 0xc00, v3
	v_add_u32_e32 v4, 0x400, v4
	s_waitcnt vmcnt(21)
; DI float bf2f(bf16_t b) { return __uint_as_float(((unsigned)b) << 16); }
; DI float rl(float x, int l) { return __int_as_float(__builtin_amdgcn_readlane(__float_as_int(x), l)); }
; template <bool PASS2>
; DI void rwkv_item(const Params& p, int l, int item, int lane, const bf16_t* rkv, const bf16_t* lo2, float* rwst) {
;     ...
;   auto derive = [&](const Raw& x, float rpp, float kpp) __attribute__((always_inline)) {
;     Der d;
;     const float rp = bf2f(x.rp), kp = bf2f(x.kp), a = bf2f(x.a);
;     d.rr = rp + (rpp - rp) * mu_r;
;     const float k = kp + (kpp - kp) * mu_k;
;     d.wdec = __expf(-bf2f(x.ew));
;     float kkv = k * kkw;
;     const float nrm = wave_sum(kkv * kkv);
;     kkv *= rsqrtf(fmaxf(nrm, 1e-24f));
;     d.kf = k * (1.f + (a - 1.f) * kaw);
;     d.av = -kkv; d.bv = kkv * a;
;     d.v = bf2f(x.v); d.gg = bf2f(x.g);
;     return d;
;   };
;     ...
; #pragma unroll
;     for (int j = 0; j < 64; j += 2) {
;       const float a0 = rl(av, j), a1 = rl(av, j + 1);
;       sa0 += S[j] * a0; sa1 += S[j + 1] * a1;
;       if (!PASS2) { pa0 += P[j] * a0; pa1 += P[j + 1] * a1; }
;     }
;     const float sa = sa0 + sa1, pa = pa0 + pa1;
	v_lshlrev_b32_e32 v27, 16, v179
	v_sub_f32_e32 v29, v7, v27
	v_fma_f32 v29, v29, v10, v27
	v_mov_b32_e32 v7, v27
	v_lshlrev_b32_e32 v26, 16, v178
	v_sub_f32_e32 v28, v6, v26
	v_fma_f32 v28, v28, v9, v26
	v_mov_b32_e32 v6, v26
	v_lshlrev_b32_e32 v30, 16, v181
	v_mul_f32_e32 v30, 0xbfb8aa3b, v30
	v_exp_f32_e32 v30, v30
	v_lshlrev_b32_e32 v31, 16, v182
	v_mul_f32_e32 v192, v29, v11
	v_add_f32_e32 v193, -1.0, v31
	v_fma_f32 v193, v193, v12, 1.0
	v_mul_f32_e32 v193, v29, v193
	v_mul_f32_e32 v194, v192, v192
	v_mul_f32_e32 v195, v28, v193
	v_mul_f32_e32 v195, v195, v13
	v_lshlrev_b32_e32 v23, 16, v183
	v_lshlrev_b32_e32 v21, 16, v180
	s_nop 1
	v_permlane32_swap_b32 v194, v195
	s_nop 0
	v_add_f32_e32 v194, v194, v195
	s_nop 1
	v_add_f32_dpp v194, v194, v194 quad_perm:[1,0,3,2] row_mask:0xf bank_mask:0xf
	s_nop 1
	v_add_f32_dpp v194, v194, v194 quad_perm:[2,3,0,1] row_mask:0xf bank_mask:0xf
	s_nop 1
	v_add_f32_dpp v194, v194, v194 row_half_mirror row_mask:0xf bank_mask:0xf
	s_nop 1
	v_add_f32_dpp v194, v194, v194 row_mirror row_mask:0xf bank_mask:0xf
	s_nop 1
	v_add_f32_dpp v194, v194, v194 row_bcast:15 row_mask:0xa bank_mask:0xf
	s_nop 1
	v_readlane_b32 s28, v194, 31
	v_readlane_b32 s31, v194, 63
	s_nop 1
	v_mov_b32_e32 v196, s28
	v_max_f32_e32 v196, 0x179abe15, v196
	v_rsq_f32_e32 v196, v196
	v_mov_b32_e32 v19, v21
	v_mul_f32_e32 v192, v192, v196
	v_mul_f32_e64 v24, -v192, v8
	v_mul_f32_e32 v197, v192, v31
	v_mul_f32_e32 v8, v8, v30
	v_rcp_f32_e32 v198, v8
	v_mul_f32_e32 v25, v8, v28
	v_mul_f32_e32 v16, v197, v198
	v_mul_f32_e32 v17, v193, v198
	s_nop 1
	v_permlane32_swap_b32 v16, v17
	ds_write_b32 v1, v24
	ds_write_b32 v1, v25 offset:512
	ds_read_b128 v[32:35], v2 offset:0
	ds_read_b128 v[128:131], v2 offset:256
	ds_read_b128 v[36:39], v2 offset:32
	ds_read_b128 v[132:135], v2 offset:288
	ds_read_b128 v[40:43], v2 offset:64
	ds_read_b128 v[136:139], v2 offset:320
	ds_read_b128 v[44:47], v2 offset:96
	ds_read_b128 v[140:143], v2 offset:352
	ds_read_b128 v[48:51], v2 offset:128
	ds_read_b128 v[144:147], v2 offset:384
	ds_read_b128 v[52:55], v2 offset:160
	ds_read_b128 v[148:151], v2 offset:416
	ds_read_b128 v[56:59], v2 offset:192
	ds_read_b128 v[152:155], v2 offset:448
	ds_read_b128 v[60:63], v2 offset:224
	ds_read_b128 v[156:159], v2 offset:480
	s_waitcnt lgkmcnt(14)
	v_pk_mul_f32 v[184:185], v[64:65], v[32:33]
	v_pk_mul_f32 v[188:189], v[64:65], v[128:129]
	v_pk_mul_f32 v[186:187], v[80:81], v[32:33]
	v_pk_mul_f32 v[190:191], v[80:81], v[128:129]
	v_pk_fma_f32 v[184:185], v[66:67], v[34:35], v[184:185]
	v_pk_fma_f32 v[188:189], v[66:67], v[130:131], v[188:189]
	v_pk_fma_f32 v[186:187], v[82:83], v[34:35], v[186:187]
	v_pk_fma_f32 v[190:191], v[82:83], v[130:131], v[190:191]
	s_waitcnt lgkmcnt(12)
	v_pk_fma_f32 v[184:185], v[68:69], v[36:37], v[184:185]
	v_pk_fma_f32 v[188:189], v[68:69], v[132:133], v[188:189]
	v_pk_fma_f32 v[186:187], v[84:85], v[36:37], v[186:187]
	v_pk_fma_f32 v[190:191], v[84:85], v[132:133], v[190:191]
	v_pk_fma_f32 v[184:185], v[70:71], v[38:39], v[184:185]
	v_pk_fma_f32 v[188:189], v[70:71], v[134:135], v[188:189]
	v_pk_fma_f32 v[186:187], v[86:87], v[38:39], v[186:187]
	v_pk_fma_f32 v[190:191], v[86:87], v[134:135], v[190:191]
	s_waitcnt lgkmcnt(10)
	v_pk_fma_f32 v[184:185], v[72:73], v[40:41], v[184:185]
	v_pk_fma_f32 v[188:189], v[72:73], v[136:137], v[188:189]
	v_pk_fma_f32 v[186:187], v[88:89], v[40:41], v[186:187]
	v_pk_fma_f32 v[190:191], v[88:89], v[136:137], v[190:191]
	v_pk_fma_f32 v[184:185], v[74:75], v[42:43], v[184:185]
	v_pk_fma_f32 v[188:189], v[74:75], v[138:139], v[188:189]
	v_pk_fma_f32 v[186:187], v[90:91], v[42:43], v[186:187]
	v_pk_fma_f32 v[190:191], v[90:91], v[138:139], v[190:191]
	s_waitcnt lgkmcnt(8)
	v_pk_fma_f32 v[184:185], v[76:77], v[44:45], v[184:185]
	v_pk_fma_f32 v[188:189], v[76:77], v[140:141], v[188:189]
	v_pk_fma_f32 v[186:187], v[92:93], v[44:45], v[186:187]
	v_pk_fma_f32 v[190:191], v[92:93], v[140:141], v[190:191]
	v_pk_fma_f32 v[184:185], v[78:79], v[46:47], v[184:185]
	v_pk_fma_f32 v[188:189], v[78:79], v[142:143], v[188:189]
	v_pk_fma_f32 v[186:187], v[94:95], v[46:47], v[186:187]
	v_pk_fma_f32 v[190:191], v[94:95], v[142:143], v[190:191]
	s_waitcnt lgkmcnt(6)
	v_pk_fma_f32 v[184:185], v[96:97], v[48:49], v[184:185]
	v_pk_fma_f32 v[188:189], v[96:97], v[144:145], v[188:189]
	v_pk_fma_f32 v[186:187], v[112:113], v[48:49], v[186:187]
	v_pk_fma_f32 v[190:191], v[112:113], v[144:145], v[190:191]
	v_pk_fma_f32 v[184:185], v[98:99], v[50:51], v[184:185]
	v_pk_fma_f32 v[188:189], v[98:99], v[146:147], v[188:189]
	v_pk_fma_f32 v[186:187], v[114:115], v[50:51], v[186:187]
	v_pk_fma_f32 v[190:191], v[114:115], v[146:147], v[190:191]
	s_waitcnt lgkmcnt(4)
	v_pk_fma_f32 v[184:185], v[100:101], v[52:53], v[184:185]
	v_pk_fma_f32 v[188:189], v[100:101], v[148:149], v[188:189]
	v_pk_fma_f32 v[186:187], v[116:117], v[52:53], v[186:187]
	v_pk_fma_f32 v[190:191], v[116:117], v[148:149], v[190:191]
	v_pk_fma_f32 v[184:185], v[102:103], v[54:55], v[184:185]
	v_pk_fma_f32 v[188:189], v[102:103], v[150:151], v[188:189]
	v_pk_fma_f32 v[186:187], v[118:119], v[54:55], v[186:187]
	v_pk_fma_f32 v[190:191], v[118:119], v[150:151], v[190:191]
	s_waitcnt lgkmcnt(2)
	v_pk_fma_f32 v[184:185], v[104:105], v[56:57], v[184:185]
	v_pk_fma_f32 v[188:189], v[104:105], v[152:153], v[188:189]
	v_pk_fma_f32 v[186:187], v[120:121], v[56:57], v[186:187]
	v_pk_fma_f32 v[190:191], v[120:121], v[152:153], v[190:191]
	v_pk_fma_f32 v[184:185], v[106:107], v[58:59], v[184:185]
	v_pk_fma_f32 v[188:189], v[106:107], v[154:155], v[188:189]
	v_pk_fma_f32 v[186:187], v[122:123], v[58:59], v[186:187]
	v_pk_fma_f32 v[190:191], v[122:123], v[154:155], v[190:191]
	s_waitcnt lgkmcnt(0)
; DI bf16_t f2bf(float x) { unsigned u = __float_as_uint(x); u += 0x7fffu + ((u >> 16) & 1u); return (bf16_t)(u >> 16); }
; DI float bf2f(bf16_t b) { return __uint_as_float(((unsigned)b) << 16); }
; template <bool PASS2>
; DI void rwkv_item(const Params& p, int l, int item, int lane, const bf16_t* rkv, const bf16_t* lo2, float* rwst) {
;     ...
;   auto derive = [&](const Raw& x, float rpp, float kpp) __attribute__((always_inline)) {
;     Der d;
;     const float rp = bf2f(x.rp), kp = bf2f(x.kp), a = bf2f(x.a);
;     d.rr = rp + (rpp - rp) * mu_r;
;     const float k = kp + (kpp - kp) * mu_k;
;     d.wdec = __expf(-bf2f(x.ew));
;     float kkv = k * kkw;
;     const float nrm = wave_sum(kkv * kkv);
;     kkv *= rsqrtf(fmaxf(nrm, 1e-24f));
;     d.kf = k * (1.f + (a - 1.f) * kaw);
;     d.av = -kkv; d.bv = kkv * a;
;     d.v = bf2f(x.v); d.gg = bf2f(x.g);
;     return d;
;   };
;     ...
; #pragma unroll
;     for (int j = 0; j < 64; j += 2) {
;       const float a0 = rl(av, j), a1 = rl(av, j + 1);
;       sa0 += S[j] * a0; sa1 += S[j + 1] * a1;
;       if (!PASS2) { pa0 += P[j] * a0; pa1 += P[j + 1] * a1; }
;     }
;     const float sa = sa0 + sa1, pa = pa0 + pa1;
;     float y0 = 0.f, y1 = 0.f;
; #pragma unroll
;     for (int j = 0; j < 64; j += 2) {
;       const float w0 = rl(wdec, j), b0 = rl(bv, j), k0 = rl(kf, j);
;       const float w1 = rl(wdec, j + 1), b1 = rl(bv, j + 1), k1 = rl(kf, j + 1);
;       S[j] = S[j] * w0 + sa * b0 + v * k0;
;       S[j + 1] = S[j + 1] * w1 + sa * b1 + v * k1;
;       if (!PASS2) {
;         P[j] = P[j] * w0 + pa * b0;
;         P[j + 1] = P[j + 1] * w1 + pa * b1;
;       } else {
;         y0 += S[j] * rl(rr, j); y1 += S[j + 1] * rl(rr, j + 1);
;       }
;     }
;     if (PASS2) {
;       const float y = y0 + y1;
;       float s1 = y, s2 = y * y, s3 = rr * kf * rkw;
; #pragma unroll
;       for (int off = 32; off >= 1; off >>= 1) {
;         const float t1 = __shfl_xor(s1, off), t2 = __shfl_xor(s2, off), t3 = __shfl_xor(s3, off);
;         s1 += t1; s2 += t2; s3 += t3;
;       }
;       const float mean = s1 * (1.f / 64.f);
;       const float var = fmaxf(s2 * (1.f / 64.f) - mean * mean, 0.f);
;       const float yn = (y - mean) * rsqrtf(var + 64e-5f) * gnw + gnb;
;       const float bs = s3;
;       p.yc[(tok0 + t) * 512 + ch] = f2bf((yn + bs * v) * gg);
;     }
;     rpA = bf2f(rawB.rp); kpA = bf2f(rawB.kp); rawB = rawC; cur = nxt;
	v_pk_fma_f32 v[184:185], v[108:109], v[60:61], v[184:185]
	v_pk_fma_f32 v[188:189], v[108:109], v[156:157], v[188:189]
	v_pk_fma_f32 v[186:187], v[124:125], v[60:61], v[186:187]
	v_pk_fma_f32 v[190:191], v[124:125], v[156:157], v[190:191]
	v_pk_fma_f32 v[184:185], v[110:111], v[62:63], v[184:185]
	v_pk_fma_f32 v[188:189], v[110:111], v[158:159], v[188:189]
	v_pk_fma_f32 v[186:187], v[126:127], v[62:63], v[186:187]
	v_pk_fma_f32 v[190:191], v[126:127], v[158:159], v[190:191]
	v_add_f32_e32 v18, v184, v185
	v_add_f32_e32 v200, v186, v187
	s_nop 1
	v_permlane32_swap_b32 v18, v200
	s_nop 0
	v_add_f32_e32 v18, v18, v200
	v_add_f32_e32 v201, v188, v189
	v_add_f32_e32 v202, v190, v191
	s_nop 1
	v_permlane32_swap_b32 v201, v202
	s_nop 0
	v_add_f32_e32 v201, v201, v202
	v_mul_f32_e32 v203, v201, v201
	v_mov_b32_e32 v204, v201
	s_nop 1
	v_permlane32_swap_b32 v204, v203
	s_nop 0
	v_add_f32_e32 v204, v204, v203
	s_nop 1
	v_add_f32_dpp v204, v204, v204 quad_perm:[1,0,3,2] row_mask:0xf bank_mask:0xf
	s_nop 1
	v_add_f32_dpp v204, v204, v204 quad_perm:[2,3,0,1] row_mask:0xf bank_mask:0xf
	s_nop 1
	v_add_f32_dpp v204, v204, v204 row_half_mirror row_mask:0xf bank_mask:0xf
	s_nop 1
	v_add_f32_dpp v204, v204, v204 row_mirror row_mask:0xf bank_mask:0xf
	s_nop 1
	v_add_f32_dpp v204, v204, v204 row_bcast:15 row_mask:0xa bank_mask:0xf
	s_nop 1
	v_readlane_b32 s34, v204, 31
	v_readlane_b32 s35, v204, 63
	s_nop 1
	v_mul_f32_e32 v205, s34, v207
	v_mul_f32_e32 v206, s35, v207
	v_fma_f32 v206, -v205, v205, v206
	v_max_f32_e32 v206, 0, v206
	v_add_f32_e32 v206, 0x3a27c5ac, v206
	v_rsq_f32_e32 v206, v206
	v_sub_f32_e32 v205, v201, v205
	v_mul_f32_e32 v205, v205, v206
	v_fma_f32 v205, v205, v14, v15
	v_fma_f32 v205, s30, v20, v205
	v_mul_f32_e32 v205, v205, v22
	v_bfe_u32 v206, v205, 16, 1
	v_add3_u32 v205, v205, v206, s36
	global_store_short_d16_hi v5, v205, s[14:15]
	v_add_u32_e32 v5, 0x400, v5
	s_nop 1
	v_permlane32_swap_b32 v18, v19
	s_nop 1
	v_mfma_f32_32x32x2_f32 v[64:79], v16, v18, v[64:79]
	v_mfma_f32_32x32x2_f32 v[80:95], v16, v19, v[80:95]
	v_mfma_f32_32x32x2_f32 v[96:111], v17, v18, v[96:111]
	v_mfma_f32_32x32x2_f32 v[112:127], v17, v19, v[112:127]
	global_load_ushort v178, v3, s[4:5]
	global_load_ushort v179, v3, s[4:5] offset:1024
	global_load_ushort v180, v4, s[6:7]
	global_load_ushort v181, v4, s[8:9]
	global_load_ushort v182, v4, s[10:11]
	global_load_ushort v183, v4, s[12:13]
	v_add_u32_e32 v3, 0xc00, v3
	v_add_u32_e32 v4, 0x400, v4
	s_waitcnt vmcnt(21)
	v_lshlrev_b32_e32 v27, 16, v161
	v_sub_f32_e32 v29, v7, v27
	v_fma_f32 v29, v29, v10, v27
	v_mov_b32_e32 v7, v27
	v_lshlrev_b32_e32 v26, 16, v160
	v_sub_f32_e32 v28, v6, v26
	v_fma_f32 v28, v28, v9, v26
	v_mov_b32_e32 v6, v26
	v_lshlrev_b32_e32 v30, 16, v163
	v_mul_f32_e32 v30, 0xbfb8aa3b, v30
	v_exp_f32_e32 v30, v30
	v_lshlrev_b32_e32 v31, 16, v164
	v_mul_f32_e32 v192, v29, v11
	v_add_f32_e32 v193, -1.0, v31
	v_fma_f32 v193, v193, v12, 1.0
	v_mul_f32_e32 v193, v29, v193
	v_mul_f32_e32 v194, v192, v192
	v_mul_f32_e32 v195, v28, v193
	v_mul_f32_e32 v195, v195, v13
	v_lshlrev_b32_e32 v22, 16, v165
	v_lshlrev_b32_e32 v20, 16, v162
	s_nop 1
	v_permlane32_swap_b32 v194, v195
	s_nop 0
	v_add_f32_e32 v194, v194, v195
	s_nop 1
	v_add_f32_dpp v194, v194, v194 quad_perm:[1,0,3,2] row_mask:0xf bank_mask:0xf
	s_nop 1
	v_add_f32_dpp v194, v194, v194 quad_perm:[2,3,0,1] row_mask:0xf bank_mask:0xf
	s_nop 1
	v_add_f32_dpp v194, v194, v194 row_half_mirror row_mask:0xf bank_mask:0xf
	s_nop 1
	v_add_f32_dpp v194, v194, v194 row_mirror row_mask:0xf bank_mask:0xf
	s_nop 1
	v_add_f32_dpp v194, v194, v194 row_bcast:15 row_mask:0xa bank_mask:0xf
	s_nop 1
	v_readlane_b32 s28, v194, 31
	v_readlane_b32 s30, v194, 63
	s_nop 1
	v_mov_b32_e32 v196, s28
	v_max_f32_e32 v196, 0x179abe15, v196
	v_rsq_f32_e32 v196, v196
	v_mov_b32_e32 v19, v20
	v_mul_f32_e32 v192, v192, v196
	v_mul_f32_e64 v24, -v192, v8
	v_mul_f32_e32 v197, v192, v31
	v_mul_f32_e32 v8, v8, v30
	v_rcp_f32_e32 v198, v8
	v_mul_f32_e32 v25, v8, v28
	v_mul_f32_e32 v16, v197, v198
	v_mul_f32_e32 v17, v193, v198
	s_nop 1
	v_permlane32_swap_b32 v16, v17
	ds_write_b32 v1, v24
	ds_write_b32 v1, v25 offset:256
	ds_read_b128 v[32:35], v2 offset:0
	ds_read_b128 v[128:131], v2 offset:512
	ds_read_b128 v[36:39], v2 offset:32
	ds_read_b128 v[132:135], v2 offset:544
	ds_read_b128 v[40:43], v2 offset:64
	ds_read_b128 v[136:139], v2 offset:576
	ds_read_b128 v[44:47], v2 offset:96
	ds_read_b128 v[140:143], v2 offset:608
	ds_read_b128 v[48:51], v2 offset:128
	ds_read_b128 v[144:147], v2 offset:640
	ds_read_b128 v[52:55], v2 offset:160
	ds_read_b128 v[148:151], v2 offset:672
	ds_read_b128 v[56:59], v2 offset:192
	ds_read_b128 v[152:155], v2 offset:704
	ds_read_b128 v[60:63], v2 offset:224
	ds_read_b128 v[156:159], v2 offset:736
	s_waitcnt lgkmcnt(14)
	v_pk_mul_f32 v[184:185], v[64:65], v[32:33]
	v_pk_mul_f32 v[188:189], v[64:65], v[128:129]
	v_pk_mul_f32 v[186:187], v[80:81], v[32:33]
	v_pk_mul_f32 v[190:191], v[80:81], v[128:129]
	v_pk_fma_f32 v[184:185], v[66:67], v[34:35], v[184:185]
	v_pk_fma_f32 v[188:189], v[66:67], v[130:131], v[188:189]
	v_pk_fma_f32 v[186:187], v[82:83], v[34:35], v[186:187]
	v_pk_fma_f32 v[190:191], v[82:83], v[130:131], v[190:191]
	s_waitcnt lgkmcnt(12)
; DI bf16_t f2bf(float x) { unsigned u = __float_as_uint(x); u += 0x7fffu + ((u >> 16) & 1u); return (bf16_t)(u >> 16); }
; DI float bf2f(bf16_t b) { return __uint_as_float(((unsigned)b) << 16); }
; DI float rl(float x, int l) { return __int_as_float(__builtin_amdgcn_readlane(__float_as_int(x), l)); }
; template <bool PASS2>
; DI void rwkv_item(const Params& p, int l, int item, int lane, const bf16_t* rkv, const bf16_t* lo2, float* rwst) {
;     ...
; #pragma unroll
;     for (int j = 0; j < 64; j += 2) {
;       const float a0 = rl(av, j), a1 = rl(av, j + 1);
;       sa0 += S[j] * a0; sa1 += S[j + 1] * a1;
;       if (!PASS2) { pa0 += P[j] * a0; pa1 += P[j + 1] * a1; }
;     }
;     const float sa = sa0 + sa1, pa = pa0 + pa1;
;     float y0 = 0.f, y1 = 0.f;
; #pragma unroll
;     for (int j = 0; j < 64; j += 2) {
;       const float w0 = rl(wdec, j), b0 = rl(bv, j), k0 = rl(kf, j);
;       const float w1 = rl(wdec, j + 1), b1 = rl(bv, j + 1), k1 = rl(kf, j + 1);
;       S[j] = S[j] * w0 + sa * b0 + v * k0;
;       S[j + 1] = S[j + 1] * w1 + sa * b1 + v * k1;
;       if (!PASS2) {
;         P[j] = P[j] * w0 + pa * b0;
;         P[j + 1] = P[j + 1] * w1 + pa * b1;
;       } else {
;         y0 += S[j] * rl(rr, j); y1 += S[j + 1] * rl(rr, j + 1);
;       }
;     }
;     if (PASS2) {
;       const float y = y0 + y1;
;       float s1 = y, s2 = y * y, s3 = rr * kf * rkw;
; #pragma unroll
;       for (int off = 32; off >= 1; off >>= 1) {
;         const float t1 = __shfl_xor(s1, off), t2 = __shfl_xor(s2, off), t3 = __shfl_xor(s3, off);
;         s1 += t1; s2 += t2; s3 += t3;
;       }
;       const float mean = s1 * (1.f / 64.f);
;       const float var = fmaxf(s2 * (1.f / 64.f) - mean * mean, 0.f);
;       const float yn = (y - mean) * rsqrtf(var + 64e-5f) * gnw + gnb;
;       const float bs = s3;
;       p.yc[(tok0 + t) * 512 + ch] = f2bf((yn + bs * v) * gg);
;     }
;     rpA = bf2f(rawB.rp); kpA = bf2f(rawB.kp); rawB = rawC; cur = nxt;
	v_pk_fma_f32 v[184:185], v[68:69], v[36:37], v[184:185]
	v_pk_fma_f32 v[188:189], v[68:69], v[132:133], v[188:189]
	v_pk_fma_f32 v[186:187], v[84:85], v[36:37], v[186:187]
	v_pk_fma_f32 v[190:191], v[84:85], v[132:133], v[190:191]
	v_pk_fma_f32 v[184:185], v[70:71], v[38:39], v[184:185]
	v_pk_fma_f32 v[188:189], v[70:71], v[134:135], v[188:189]
	v_pk_fma_f32 v[186:187], v[86:87], v[38:39], v[186:187]
	v_pk_fma_f32 v[190:191], v[86:87], v[134:135], v[190:191]
	s_waitcnt lgkmcnt(10)
	v_pk_fma_f32 v[184:185], v[72:73], v[40:41], v[184:185]
	v_pk_fma_f32 v[188:189], v[72:73], v[136:137], v[188:189]
	v_pk_fma_f32 v[186:187], v[88:89], v[40:41], v[186:187]
	v_pk_fma_f32 v[190:191], v[88:89], v[136:137], v[190:191]
	v_pk_fma_f32 v[184:185], v[74:75], v[42:43], v[184:185]
	v_pk_fma_f32 v[188:189], v[74:75], v[138:139], v[188:189]
	v_pk_fma_f32 v[186:187], v[90:91], v[42:43], v[186:187]
	v_pk_fma_f32 v[190:191], v[90:91], v[138:139], v[190:191]
	s_waitcnt lgkmcnt(8)
	v_pk_fma_f32 v[184:185], v[76:77], v[44:45], v[184:185]
	v_pk_fma_f32 v[188:189], v[76:77], v[140:141], v[188:189]
	v_pk_fma_f32 v[186:187], v[92:93], v[44:45], v[186:187]
	v_pk_fma_f32 v[190:191], v[92:93], v[140:141], v[190:191]
	v_pk_fma_f32 v[184:185], v[78:79], v[46:47], v[184:185]
	v_pk_fma_f32 v[188:189], v[78:79], v[142:143], v[188:189]
	v_pk_fma_f32 v[186:187], v[94:95], v[46:47], v[186:187]
	v_pk_fma_f32 v[190:191], v[94:95], v[142:143], v[190:191]
	s_waitcnt lgkmcnt(6)
	v_pk_fma_f32 v[184:185], v[96:97], v[48:49], v[184:185]
	v_pk_fma_f32 v[188:189], v[96:97], v[144:145], v[188:189]
	v_pk_fma_f32 v[186:187], v[112:113], v[48:49], v[186:187]
	v_pk_fma_f32 v[190:191], v[112:113], v[144:145], v[190:191]
	v_pk_fma_f32 v[184:185], v[98:99], v[50:51], v[184:185]
	v_pk_fma_f32 v[188:189], v[98:99], v[146:147], v[188:189]
	v_pk_fma_f32 v[186:187], v[114:115], v[50:51], v[186:187]
	v_pk_fma_f32 v[190:191], v[114:115], v[146:147], v[190:191]
	s_waitcnt lgkmcnt(4)
	v_pk_fma_f32 v[184:185], v[100:101], v[52:53], v[184:185]
	v_pk_fma_f32 v[188:189], v[100:101], v[148:149], v[188:189]
	v_pk_fma_f32 v[186:187], v[116:117], v[52:53], v[186:187]
	v_pk_fma_f32 v[190:191], v[116:117], v[148:149], v[190:191]
	v_pk_fma_f32 v[184:185], v[102:103], v[54:55], v[184:185]
	v_pk_fma_f32 v[188:189], v[102:103], v[150:151], v[188:189]
	v_pk_fma_f32 v[186:187], v[118:119], v[54:55], v[186:187]
	v_pk_fma_f32 v[190:191], v[118:119], v[150:151], v[190:191]
	s_waitcnt lgkmcnt(2)
	v_pk_fma_f32 v[184:185], v[104:105], v[56:57], v[184:185]
	v_pk_fma_f32 v[188:189], v[104:105], v[152:153], v[188:189]
	v_pk_fma_f32 v[186:187], v[120:121], v[56:57], v[186:187]
	v_pk_fma_f32 v[190:191], v[120:121], v[152:153], v[190:191]
	v_pk_fma_f32 v[184:185], v[106:107], v[58:59], v[184:185]
	v_pk_fma_f32 v[188:189], v[106:107], v[154:155], v[188:189]
	v_pk_fma_f32 v[186:187], v[122:123], v[58:59], v[186:187]
	v_pk_fma_f32 v[190:191], v[122:123], v[154:155], v[190:191]
	s_waitcnt lgkmcnt(0)
	v_pk_fma_f32 v[184:185], v[108:109], v[60:61], v[184:185]
	v_pk_fma_f32 v[188:189], v[108:109], v[156:157], v[188:189]
	v_pk_fma_f32 v[186:187], v[124:125], v[60:61], v[186:187]
	v_pk_fma_f32 v[190:191], v[124:125], v[156:157], v[190:191]
	v_pk_fma_f32 v[184:185], v[110:111], v[62:63], v[184:185]
	v_pk_fma_f32 v[188:189], v[110:111], v[158:159], v[188:189]
	v_pk_fma_f32 v[186:187], v[126:127], v[62:63], v[186:187]
	v_pk_fma_f32 v[190:191], v[126:127], v[158:159], v[190:191]
	v_add_f32_e32 v18, v184, v185
	v_add_f32_e32 v200, v186, v187
	s_nop 1
	v_permlane32_swap_b32 v18, v200
	s_nop 0
	v_add_f32_e32 v18, v18, v200
	v_add_f32_e32 v201, v188, v189
	v_add_f32_e32 v202, v190, v191
	s_nop 1
	v_permlane32_swap_b32 v201, v202
	s_nop 0
	v_add_f32_e32 v201, v201, v202
	v_mul_f32_e32 v203, v201, v201
	v_mov_b32_e32 v204, v201
	s_nop 1
	v_permlane32_swap_b32 v204, v203
	s_nop 0
	v_add_f32_e32 v204, v204, v203
	s_nop 1
	v_add_f32_dpp v204, v204, v204 quad_perm:[1,0,3,2] row_mask:0xf bank_mask:0xf
	s_nop 1
	v_add_f32_dpp v204, v204, v204 quad_perm:[2,3,0,1] row_mask:0xf bank_mask:0xf
	s_nop 1
	v_add_f32_dpp v204, v204, v204 row_half_mirror row_mask:0xf bank_mask:0xf
	s_nop 1
	v_add_f32_dpp v204, v204, v204 row_mirror row_mask:0xf bank_mask:0xf
	s_nop 1
	v_add_f32_dpp v204, v204, v204 row_bcast:15 row_mask:0xa bank_mask:0xf
	s_nop 1
	v_readlane_b32 s34, v204, 31
	v_readlane_b32 s35, v204, 63
	s_nop 1
	v_mul_f32_e32 v205, s34, v207
	v_mul_f32_e32 v206, s35, v207
	v_fma_f32 v206, -v205, v205, v206
	v_max_f32_e32 v206, 0, v206
	v_add_f32_e32 v206, 0x3a27c5ac, v206
	v_rsq_f32_e32 v206, v206
	v_sub_f32_e32 v205, v201, v205
	v_mul_f32_e32 v205, v205, v206
	v_fma_f32 v205, v205, v14, v15
	v_fma_f32 v205, s31, v21, v205
	v_mul_f32_e32 v205, v205, v23
	v_bfe_u32 v206, v205, 16, 1
	v_add3_u32 v205, v205, v206, s36
	global_store_short_d16_hi v5, v205, s[14:15]
	v_add_u32_e32 v5, 0x400, v5
	s_add_u32 s18, s18, 4
	s_cmp_lt_u32 s18, 128
	s_cbranch_scc1 .Lrwp2a_loop
	s_waitcnt vmcnt(0)
	s_add_u32 s16, s16, s17
	s_cmpk_lt_i32 s16, 0x800
	s_cbranch_scc1 .Lrwp2a_item
	v_readlane_b32 s50, v253, 19
	v_readlane_b32 s51, v253, 20
	v_readlane_b32 s52, v253, 21
	v_readlane_b32 s53, v253, 22
	v_readlane_b32 s54, v253, 23
	v_readlane_b32 s55, v253, 24
	v_readlane_b32 s56, v253, 25
	v_readlane_b32 s57, v253, 26
	v_readlane_b32 s58, v253, 27
	v_readlane_b32 s59, v253, 28

; #define XT4_LOOP(NTN, BASE) \
;   for (int pos_ = first_item((BASE), (int)(blockIdx.x >> 3), (int)(gridDim.x >> 3)); pos_ < 16 * (NTN); pos_ += (int)(gridDim.x >> 3))
; DI void phase_gemm_qkv(const Params& p, bf16_t* sm) {
;     ...
;   XT4_LOOP(12, 0) {
;     int mt_, nt_; xt4_decode(pos_, 12, mt_, nt_);
;     const int row0 = mt_ * 256, n0 = nt_ * 128;
.LBB0_2064:
	s_add_i32 s13, s13, s33
	s_add_i32 s6, s6, s33
	s_cmpk_lt_u32 s13, 0xc0
	s_cbranch_scc0 .LBB0_2201

; DI bf16_t f2bf(float x) { unsigned u = __float_as_uint(x); u += 0x7fffu + ((u >> 16) & 1u); return (bf16_t)(u >> 16); }
; DI void phase_gemm_qkv(const Params& p, bf16_t* sm) {
;     ...
; #pragma unroll
;     for (int mi = 0; mi < 4; mi++)
; #pragma unroll
;       for (int i = 0; i < 16; i++) {
;         const int row = EPI_ROW4(mi, i);
;         const int col = n0 + ewn * 64 + er;
;         float x1 = acc[mi][0][i], x2 = acc[mi][1][i];
;         if (n0 < 1024) {
;           int pos = row & (SEQ - 1);
;           float c = p.ropeC[pos * 32 + er], s = p.ropeS[pos * 32 + er];
;           float o1 = x1 * c - x2 * s, o2 = x2 * c + x1 * s;
;           if (n0 < 512) { o1 *= 0.125f; o2 *= 0.125f; }
;           x1 = o1; x2 = o2;
;         }
;         qkv[(size_t)row * 1536 + col] = f2bf(x1);
;         qkv[(size_t)row * 1536 + col + 32] = f2bf(x2);
;       }
.LBB0_2073:
	v_or_b32_e32 v245, s2, v203
	v_or_b32_e32 v246, s14, v204
	v_readlane_b32 s10, v254, 44
	v_readlane_b32 s11, v254, 45
	v_mul_u32_u24_e32 v247, 0xc00, v246
	v_lshl_add_u32 v247, v245, 1, v247
	s_cmp_gt_i32 s3, 7
	s_cbranch_scc1 .Lqkv1_store
	s_cmp_lt_i32 s3, 4
	s_cselect_b32 s2, 0x3e000000, 1.0
	v_readlane_b32 s4, v254, 38
	v_readlane_b32 s5, v254, 39
	v_readlane_b32 s8, v254, 40
	v_readlane_b32 s9, v254, 41
	v_and_b32_e32 v244, 0x3fff, v246
	v_lshlrev_b32_e32 v244, 7, v244
	v_lshl_add_u32 v244, v202, 2, v244
	s_nop 4
	global_load_dword v128, v244, s[4:5] offset:0
	global_load_dword v144, v244, s[8:9] offset:0
	global_load_dword v129, v244, s[4:5] offset:128
	global_load_dword v145, v244, s[8:9] offset:128
	global_load_dword v130, v244, s[4:5] offset:256
	global_load_dword v146, v244, s[8:9] offset:256
	global_load_dword v131, v244, s[4:5] offset:384
	global_load_dword v147, v244, s[8:9] offset:384
	global_load_dword v132, v244, s[4:5] offset:1024
	global_load_dword v148, v244, s[8:9] offset:1024
	global_load_dword v133, v244, s[4:5] offset:1152
	global_load_dword v149, v244, s[8:9] offset:1152
	global_load_dword v134, v244, s[4:5] offset:1280
	global_load_dword v150, v244, s[8:9] offset:1280
	global_load_dword v135, v244, s[4:5] offset:1408
	global_load_dword v151, v244, s[8:9] offset:1408
	global_load_dword v136, v244, s[4:5] offset:2048
	global_load_dword v152, v244, s[8:9] offset:2048
	global_load_dword v137, v244, s[4:5] offset:2176
	global_load_dword v153, v244, s[8:9] offset:2176
	global_load_dword v138, v244, s[4:5] offset:2304
	global_load_dword v154, v244, s[8:9] offset:2304
	global_load_dword v139, v244, s[4:5] offset:2432
	global_load_dword v155, v244, s[8:9] offset:2432
	global_load_dword v140, v244, s[4:5] offset:3072
	global_load_dword v156, v244, s[8:9] offset:3072
	global_load_dword v141, v244, s[4:5] offset:3200
	global_load_dword v157, v244, s[8:9] offset:3200
	global_load_dword v142, v244, s[4:5] offset:3328
	global_load_dword v158, v244, s[8:9] offset:3328
	global_load_dword v143, v244, s[4:5] offset:3456
	global_load_dword v159, v244, s[8:9] offset:3456
	s_add_u32 s4, s4, 0x1000
	s_addc_u32 s5, s5, 0
	s_add_u32 s8, s8, 0x1000
	s_addc_u32 s9, s9, 0
	global_load_dword v160, v244, s[4:5] offset:0
	global_load_dword v190, v244, s[8:9] offset:0
	global_load_dword v161, v244, s[4:5] offset:128
	global_load_dword v191, v244, s[8:9] offset:128
	global_load_dword v162, v244, s[4:5] offset:256
	global_load_dword v192, v244, s[8:9] offset:256
	global_load_dword v163, v244, s[4:5] offset:384
	global_load_dword v193, v244, s[8:9] offset:384
	global_load_dword v164, v244, s[4:5] offset:1024
	global_load_dword v194, v244, s[8:9] offset:1024
	global_load_dword v165, v244, s[4:5] offset:1152
	global_load_dword v195, v244, s[8:9] offset:1152
	global_load_dword v166, v244, s[4:5] offset:1280
	global_load_dword v196, v244, s[8:9] offset:1280
	global_load_dword v167, v244, s[4:5] offset:1408
	global_load_dword v197, v244, s[8:9] offset:1408
	global_load_dword v168, v244, s[4:5] offset:2048
	global_load_dword v198, v244, s[8:9] offset:2048
	global_load_dword v169, v244, s[4:5] offset:2176
	global_load_dword v199, v244, s[8:9] offset:2176
	global_load_dword v170, v244, s[4:5] offset:2304
	global_load_dword v200, v244, s[8:9] offset:2304
	global_load_dword v171, v244, s[4:5] offset:2432
	global_load_dword v201, v244, s[8:9] offset:2432
	global_load_dword v172, v244, s[4:5] offset:3072
	global_load_dword v206, v244, s[8:9] offset:3072
	global_load_dword v173, v244, s[4:5] offset:3200
	global_load_dword v207, v244, s[8:9] offset:3200
	global_load_dword v174, v244, s[4:5] offset:3328
	global_load_dword v208, v244, s[8:9] offset:3328
	global_load_dword v175, v244, s[4:5] offset:3456
	global_load_dword v209, v244, s[8:9] offset:3456
	s_add_u32 s4, s4, 0x1000
	s_addc_u32 s5, s5, 0
	s_add_u32 s8, s8, 0x1000
	s_addc_u32 s9, s9, 0
	s_waitcnt vmcnt(32)
	v_mul_f32_e32 v128, s2, v128
	v_mul_f32_e32 v144, s2, v144
	v_mul_f32_e32 v248, v96, v144
	v_mul_f32_e32 v249, v112, v144
	v_fma_f32 v112, v112, v128, -v248
	v_fma_f32 v96, v96, v128, v249
	v_mul_f32_e32 v129, s2, v129
	v_mul_f32_e32 v145, s2, v145
	v_mul_f32_e32 v250, v97, v145
	v_mul_f32_e32 v251, v113, v145
	v_fma_f32 v113, v113, v129, -v250
	v_fma_f32 v97, v97, v129, v251
	v_mul_f32_e32 v130, s2, v130
	v_mul_f32_e32 v146, s2, v146
	v_mul_f32_e32 v248, v98, v146
	v_mul_f32_e32 v249, v114, v146
	v_fma_f32 v114, v114, v130, -v248
	v_fma_f32 v98, v98, v130, v249
	v_mul_f32_e32 v131, s2, v131
	v_mul_f32_e32 v147, s2, v147
	v_mul_f32_e32 v250, v99, v147
	v_mul_f32_e32 v251, v115, v147
	v_fma_f32 v115, v115, v131, -v250
	v_fma_f32 v99, v99, v131, v251
	v_mul_f32_e32 v132, s2, v132
	v_mul_f32_e32 v148, s2, v148
	v_mul_f32_e32 v248, v100, v148
	v_mul_f32_e32 v249, v116, v148
	v_fma_f32 v116, v116, v132, -v248
	v_fma_f32 v100, v100, v132, v249
	v_mul_f32_e32 v133, s2, v133
	v_mul_f32_e32 v149, s2, v149
	v_mul_f32_e32 v250, v101, v149
	v_mul_f32_e32 v251, v117, v149
	v_fma_f32 v117, v117, v133, -v250
	v_fma_f32 v101, v101, v133, v251
	v_mul_f32_e32 v134, s2, v134
	v_mul_f32_e32 v150, s2, v150
	v_mul_f32_e32 v248, v102, v150
	v_mul_f32_e32 v249, v118, v150
	v_fma_f32 v118, v118, v134, -v248
	v_fma_f32 v102, v102, v134, v249
	v_mul_f32_e32 v135, s2, v135
	v_mul_f32_e32 v151, s2, v151
	v_mul_f32_e32 v250, v103, v151
	v_mul_f32_e32 v251, v119, v151
	v_fma_f32 v119, v119, v135, -v250
	v_fma_f32 v103, v103, v135, v251
	v_mul_f32_e32 v136, s2, v136
	v_mul_f32_e32 v152, s2, v152
	v_mul_f32_e32 v248, v104, v152
	v_mul_f32_e32 v249, v120, v152
	v_fma_f32 v120, v120, v136, -v248
	v_fma_f32 v104, v104, v136, v249
; DI bf16_t f2bf(float x) { unsigned u = __float_as_uint(x); u += 0x7fffu + ((u >> 16) & 1u); return (bf16_t)(u >> 16); }
; DI void phase_gemm_qkv(const Params& p, bf16_t* sm) {
;     ...
; #pragma unroll
;     for (int mi = 0; mi < 4; mi++)
; #pragma unroll
;       for (int i = 0; i < 16; i++) {
;         const int row = EPI_ROW4(mi, i);
;         const int col = n0 + ewn * 64 + er;
;         float x1 = acc[mi][0][i], x2 = acc[mi][1][i];
;         if (n0 < 1024) {
;           int pos = row & (SEQ - 1);
;           float c = p.ropeC[pos * 32 + er], s = p.ropeS[pos * 32 + er];
;           float o1 = x1 * c - x2 * s, o2 = x2 * c + x1 * s;
;           if (n0 < 512) { o1 *= 0.125f; o2 *= 0.125f; }
;           x1 = o1; x2 = o2;
;         }
;         qkv[(size_t)row * 1536 + col] = f2bf(x1);
;         qkv[(size_t)row * 1536 + col + 32] = f2bf(x2);
;       }
	v_mul_f32_e32 v137, s2, v137
	v_mul_f32_e32 v153, s2, v153
	v_mul_f32_e32 v250, v105, v153
	v_mul_f32_e32 v251, v121, v153
	v_fma_f32 v121, v121, v137, -v250
	v_fma_f32 v105, v105, v137, v251
	v_mul_f32_e32 v138, s2, v138
	v_mul_f32_e32 v154, s2, v154
	v_mul_f32_e32 v248, v106, v154
	v_mul_f32_e32 v249, v122, v154
	v_fma_f32 v122, v122, v138, -v248
	v_fma_f32 v106, v106, v138, v249
	v_mul_f32_e32 v139, s2, v139
	v_mul_f32_e32 v155, s2, v155
	v_mul_f32_e32 v250, v107, v155
	v_mul_f32_e32 v251, v123, v155
	v_fma_f32 v123, v123, v139, -v250
	v_fma_f32 v107, v107, v139, v251
	v_mul_f32_e32 v140, s2, v140
	v_mul_f32_e32 v156, s2, v156
	v_mul_f32_e32 v248, v108, v156
	v_mul_f32_e32 v249, v124, v156
	v_fma_f32 v124, v124, v140, -v248
	v_fma_f32 v108, v108, v140, v249
	v_mul_f32_e32 v141, s2, v141
	v_mul_f32_e32 v157, s2, v157
	v_mul_f32_e32 v250, v109, v157
	v_mul_f32_e32 v251, v125, v157
	v_fma_f32 v125, v125, v141, -v250
	v_fma_f32 v109, v109, v141, v251
	v_mul_f32_e32 v142, s2, v142
	v_mul_f32_e32 v158, s2, v158
	v_mul_f32_e32 v248, v110, v158
	v_mul_f32_e32 v249, v126, v158
	v_fma_f32 v126, v126, v142, -v248
	v_fma_f32 v110, v110, v142, v249
	v_mul_f32_e32 v143, s2, v143
	v_mul_f32_e32 v159, s2, v159
	v_mul_f32_e32 v250, v111, v159
	v_mul_f32_e32 v251, v127, v159
	v_fma_f32 v127, v127, v143, -v250
	v_fma_f32 v111, v111, v143, v251
	global_load_dword v128, v244, s[4:5] offset:0
	global_load_dword v144, v244, s[8:9] offset:0
	global_load_dword v129, v244, s[4:5] offset:128
	global_load_dword v145, v244, s[8:9] offset:128
	global_load_dword v130, v244, s[4:5] offset:256
	global_load_dword v146, v244, s[8:9] offset:256
	global_load_dword v131, v244, s[4:5] offset:384
	global_load_dword v147, v244, s[8:9] offset:384
	global_load_dword v132, v244, s[4:5] offset:1024
	global_load_dword v148, v244, s[8:9] offset:1024
	global_load_dword v133, v244, s[4:5] offset:1152
	global_load_dword v149, v244, s[8:9] offset:1152
	global_load_dword v134, v244, s[4:5] offset:1280
	global_load_dword v150, v244, s[8:9] offset:1280
	global_load_dword v135, v244, s[4:5] offset:1408
	global_load_dword v151, v244, s[8:9] offset:1408
	global_load_dword v136, v244, s[4:5] offset:2048
	global_load_dword v152, v244, s[8:9] offset:2048
	global_load_dword v137, v244, s[4:5] offset:2176
	global_load_dword v153, v244, s[8:9] offset:2176
	global_load_dword v138, v244, s[4:5] offset:2304
	global_load_dword v154, v244, s[8:9] offset:2304
	global_load_dword v139, v244, s[4:5] offset:2432
	global_load_dword v155, v244, s[8:9] offset:2432
	global_load_dword v140, v244, s[4:5] offset:3072
	global_load_dword v156, v244, s[8:9] offset:3072
	global_load_dword v141, v244, s[4:5] offset:3200
	global_load_dword v157, v244, s[8:9] offset:3200
	global_load_dword v142, v244, s[4:5] offset:3328
	global_load_dword v158, v244, s[8:9] offset:3328
	global_load_dword v143, v244, s[4:5] offset:3456
	global_load_dword v159, v244, s[8:9] offset:3456
	s_add_u32 s4, s4, 0x1000
	s_addc_u32 s5, s5, 0
	s_add_u32 s8, s8, 0x1000
	s_addc_u32 s9, s9, 0
	s_waitcnt vmcnt(32)
	v_mul_f32_e32 v160, s2, v160
	v_mul_f32_e32 v190, s2, v190
	v_mul_f32_e32 v248, v64, v190
	v_mul_f32_e32 v249, v80, v190
	v_fma_f32 v80, v80, v160, -v248
	v_fma_f32 v64, v64, v160, v249
	v_mul_f32_e32 v161, s2, v161
	v_mul_f32_e32 v191, s2, v191
	v_mul_f32_e32 v250, v65, v191
	v_mul_f32_e32 v251, v81, v191
	v_fma_f32 v81, v81, v161, -v250
	v_fma_f32 v65, v65, v161, v251
	v_mul_f32_e32 v162, s2, v162
	v_mul_f32_e32 v192, s2, v192
	v_mul_f32_e32 v248, v66, v192
	v_mul_f32_e32 v249, v82, v192
	v_fma_f32 v82, v82, v162, -v248
	v_fma_f32 v66, v66, v162, v249
	v_mul_f32_e32 v163, s2, v163
	v_mul_f32_e32 v193, s2, v193
	v_mul_f32_e32 v250, v67, v193
	v_mul_f32_e32 v251, v83, v193
	v_fma_f32 v83, v83, v163, -v250
	v_fma_f32 v67, v67, v163, v251
	v_mul_f32_e32 v164, s2, v164
	v_mul_f32_e32 v194, s2, v194
	v_mul_f32_e32 v248, v68, v194
	v_mul_f32_e32 v249, v84, v194
	v_fma_f32 v84, v84, v164, -v248
	v_fma_f32 v68, v68, v164, v249
	v_mul_f32_e32 v165, s2, v165
	v_mul_f32_e32 v195, s2, v195
	v_mul_f32_e32 v250, v69, v195
	v_mul_f32_e32 v251, v85, v195
	v_fma_f32 v85, v85, v165, -v250
	v_fma_f32 v69, v69, v165, v251
	v_mul_f32_e32 v166, s2, v166
	v_mul_f32_e32 v196, s2, v196
	v_mul_f32_e32 v248, v70, v196
	v_mul_f32_e32 v249, v86, v196
	v_fma_f32 v86, v86, v166, -v248
	v_fma_f32 v70, v70, v166, v249
	v_mul_f32_e32 v167, s2, v167
	v_mul_f32_e32 v197, s2, v197
	v_mul_f32_e32 v250, v71, v197
	v_mul_f32_e32 v251, v87, v197
	v_fma_f32 v87, v87, v167, -v250
	v_fma_f32 v71, v71, v167, v251
	v_mul_f32_e32 v168, s2, v168
	v_mul_f32_e32 v198, s2, v198
	v_mul_f32_e32 v248, v72, v198
	v_mul_f32_e32 v249, v88, v198
	v_fma_f32 v88, v88, v168, -v248
	v_fma_f32 v72, v72, v168, v249
	v_mul_f32_e32 v169, s2, v169
	v_mul_f32_e32 v199, s2, v199
	v_mul_f32_e32 v250, v73, v199
	v_mul_f32_e32 v251, v89, v199
	v_fma_f32 v89, v89, v169, -v250
	v_fma_f32 v73, v73, v169, v251
	v_mul_f32_e32 v170, s2, v170
	v_mul_f32_e32 v200, s2, v200
	v_mul_f32_e32 v248, v74, v200
	v_mul_f32_e32 v249, v90, v200
	v_fma_f32 v90, v90, v170, -v248
	v_fma_f32 v74, v74, v170, v249
	v_mul_f32_e32 v171, s2, v171
	v_mul_f32_e32 v201, s2, v201
	v_mul_f32_e32 v250, v75, v201
	v_mul_f32_e32 v251, v91, v201
	v_fma_f32 v91, v91, v171, -v250
	v_fma_f32 v75, v75, v171, v251
	v_mul_f32_e32 v172, s2, v172
	v_mul_f32_e32 v206, s2, v206
	v_mul_f32_e32 v248, v76, v206
	v_mul_f32_e32 v249, v92, v206
	v_fma_f32 v92, v92, v172, -v248
	v_fma_f32 v76, v76, v172, v249
	v_mul_f32_e32 v173, s2, v173
	v_mul_f32_e32 v207, s2, v207
	v_mul_f32_e32 v250, v77, v207
	v_mul_f32_e32 v251, v93, v207
	v_fma_f32 v93, v93, v173, -v250
; DI bf16_t f2bf(float x) { unsigned u = __float_as_uint(x); u += 0x7fffu + ((u >> 16) & 1u); return (bf16_t)(u >> 16); }
; DI void phase_gemm_qkv(const Params& p, bf16_t* sm) {
;     ...
; #pragma unroll
;     for (int mi = 0; mi < 4; mi++)
; #pragma unroll
;       for (int i = 0; i < 16; i++) {
;         const int row = EPI_ROW4(mi, i);
;         const int col = n0 + ewn * 64 + er;
;         float x1 = acc[mi][0][i], x2 = acc[mi][1][i];
;         if (n0 < 1024) {
;           int pos = row & (SEQ - 1);
;           float c = p.ropeC[pos * 32 + er], s = p.ropeS[pos * 32 + er];
;           float o1 = x1 * c - x2 * s, o2 = x2 * c + x1 * s;
;           if (n0 < 512) { o1 *= 0.125f; o2 *= 0.125f; }
;           x1 = o1; x2 = o2;
;         }
;         qkv[(size_t)row * 1536 + col] = f2bf(x1);
;         qkv[(size_t)row * 1536 + col + 32] = f2bf(x2);
;       }
	v_fma_f32 v77, v77, v173, v251
	v_mul_f32_e32 v174, s2, v174
	v_mul_f32_e32 v208, s2, v208
	v_mul_f32_e32 v248, v78, v208
	v_mul_f32_e32 v249, v94, v208
	v_fma_f32 v94, v94, v174, -v248
	v_fma_f32 v78, v78, v174, v249
	v_mul_f32_e32 v175, s2, v175
	v_mul_f32_e32 v209, s2, v209
	v_mul_f32_e32 v250, v79, v209
	v_mul_f32_e32 v251, v95, v209
	v_fma_f32 v95, v95, v175, -v250
	v_fma_f32 v79, v79, v175, v251
	global_load_dword v160, v244, s[4:5] offset:0
	global_load_dword v190, v244, s[8:9] offset:0
	global_load_dword v161, v244, s[4:5] offset:128
	global_load_dword v191, v244, s[8:9] offset:128
	global_load_dword v162, v244, s[4:5] offset:256
	global_load_dword v192, v244, s[8:9] offset:256
	global_load_dword v163, v244, s[4:5] offset:384
	global_load_dword v193, v244, s[8:9] offset:384
	global_load_dword v164, v244, s[4:5] offset:1024
	global_load_dword v194, v244, s[8:9] offset:1024
	global_load_dword v165, v244, s[4:5] offset:1152
	global_load_dword v195, v244, s[8:9] offset:1152
	global_load_dword v166, v244, s[4:5] offset:1280
	global_load_dword v196, v244, s[8:9] offset:1280
	global_load_dword v167, v244, s[4:5] offset:1408
	global_load_dword v197, v244, s[8:9] offset:1408
	global_load_dword v168, v244, s[4:5] offset:2048
	global_load_dword v198, v244, s[8:9] offset:2048
	global_load_dword v169, v244, s[4:5] offset:2176
	global_load_dword v199, v244, s[8:9] offset:2176
	global_load_dword v170, v244, s[4:5] offset:2304
	global_load_dword v200, v244, s[8:9] offset:2304
	global_load_dword v171, v244, s[4:5] offset:2432
	global_load_dword v201, v244, s[8:9] offset:2432
	global_load_dword v172, v244, s[4:5] offset:3072
	global_load_dword v206, v244, s[8:9] offset:3072
	global_load_dword v173, v244, s[4:5] offset:3200
	global_load_dword v207, v244, s[8:9] offset:3200
	global_load_dword v174, v244, s[4:5] offset:3328
	global_load_dword v208, v244, s[8:9] offset:3328
	global_load_dword v175, v244, s[4:5] offset:3456
	global_load_dword v209, v244, s[8:9] offset:3456
	s_add_u32 s4, s4, 0x1000
	s_addc_u32 s5, s5, 0
	s_add_u32 s8, s8, 0x1000
	s_addc_u32 s9, s9, 0
	s_waitcnt vmcnt(32)
	v_mul_f32_e32 v128, s2, v128
	v_mul_f32_e32 v144, s2, v144
	v_mul_f32_e32 v248, v32, v144
	v_mul_f32_e32 v249, v48, v144
	v_fma_f32 v48, v48, v128, -v248
	v_fma_f32 v32, v32, v128, v249
	v_mul_f32_e32 v129, s2, v129
	v_mul_f32_e32 v145, s2, v145
	v_mul_f32_e32 v250, v33, v145
	v_mul_f32_e32 v251, v49, v145
	v_fma_f32 v49, v49, v129, -v250
	v_fma_f32 v33, v33, v129, v251
	v_mul_f32_e32 v130, s2, v130
	v_mul_f32_e32 v146, s2, v146
	v_mul_f32_e32 v248, v34, v146
	v_mul_f32_e32 v249, v50, v146
	v_fma_f32 v50, v50, v130, -v248
	v_fma_f32 v34, v34, v130, v249
	v_mul_f32_e32 v131, s2, v131
	v_mul_f32_e32 v147, s2, v147
	v_mul_f32_e32 v250, v35, v147
	v_mul_f32_e32 v251, v51, v147
	v_fma_f32 v51, v51, v131, -v250
	v_fma_f32 v35, v35, v131, v251
	v_mul_f32_e32 v132, s2, v132
	v_mul_f32_e32 v148, s2, v148
	v_mul_f32_e32 v248, v36, v148
	v_mul_f32_e32 v249, v52, v148
	v_fma_f32 v52, v52, v132, -v248
	v_fma_f32 v36, v36, v132, v249
	v_mul_f32_e32 v133, s2, v133
	v_mul_f32_e32 v149, s2, v149
	v_mul_f32_e32 v250, v37, v149
	v_mul_f32_e32 v251, v53, v149
	v_fma_f32 v53, v53, v133, -v250
	v_fma_f32 v37, v37, v133, v251
	v_mul_f32_e32 v134, s2, v134
	v_mul_f32_e32 v150, s2, v150
	v_mul_f32_e32 v248, v38, v150
	v_mul_f32_e32 v249, v54, v150
	v_fma_f32 v54, v54, v134, -v248
	v_fma_f32 v38, v38, v134, v249
	v_mul_f32_e32 v135, s2, v135
	v_mul_f32_e32 v151, s2, v151
	v_mul_f32_e32 v250, v39, v151
	v_mul_f32_e32 v251, v55, v151
	v_fma_f32 v55, v55, v135, -v250
	v_fma_f32 v39, v39, v135, v251
	v_mul_f32_e32 v136, s2, v136
	v_mul_f32_e32 v152, s2, v152
	v_mul_f32_e32 v248, v40, v152
	v_mul_f32_e32 v249, v56, v152
	v_fma_f32 v56, v56, v136, -v248
	v_fma_f32 v40, v40, v136, v249
	v_mul_f32_e32 v137, s2, v137
	v_mul_f32_e32 v153, s2, v153
	v_mul_f32_e32 v250, v41, v153
	v_mul_f32_e32 v251, v57, v153
	v_fma_f32 v57, v57, v137, -v250
	v_fma_f32 v41, v41, v137, v251
	v_mul_f32_e32 v138, s2, v138
	v_mul_f32_e32 v154, s2, v154
	v_mul_f32_e32 v248, v42, v154
	v_mul_f32_e32 v249, v58, v154
	v_fma_f32 v58, v58, v138, -v248
	v_fma_f32 v42, v42, v138, v249
	v_mul_f32_e32 v139, s2, v139
	v_mul_f32_e32 v155, s2, v155
	v_mul_f32_e32 v250, v43, v155
	v_mul_f32_e32 v251, v59, v155
	v_fma_f32 v59, v59, v139, -v250
	v_fma_f32 v43, v43, v139, v251
	v_mul_f32_e32 v140, s2, v140
	v_mul_f32_e32 v156, s2, v156
	v_mul_f32_e32 v248, v44, v156
	v_mul_f32_e32 v249, v60, v156
	v_fma_f32 v60, v60, v140, -v248
	v_fma_f32 v44, v44, v140, v249
	v_mul_f32_e32 v141, s2, v141
	v_mul_f32_e32 v157, s2, v157
	v_mul_f32_e32 v250, v45, v157
	v_mul_f32_e32 v251, v61, v157
	v_fma_f32 v61, v61, v141, -v250
	v_fma_f32 v45, v45, v141, v251
	v_mul_f32_e32 v142, s2, v142
	v_mul_f32_e32 v158, s2, v158
	v_mul_f32_e32 v248, v46, v158
	v_mul_f32_e32 v249, v62, v158
	v_fma_f32 v62, v62, v142, -v248
	v_fma_f32 v46, v46, v142, v249
	v_mul_f32_e32 v143, s2, v143
	v_mul_f32_e32 v159, s2, v159
	v_mul_f32_e32 v250, v47, v159
	v_mul_f32_e32 v251, v63, v159
	v_fma_f32 v63, v63, v143, -v250
	v_fma_f32 v47, v47, v143, v251
	s_waitcnt vmcnt(0)
; DI bf16_t f2bf(float x) { unsigned u = __float_as_uint(x); u += 0x7fffu + ((u >> 16) & 1u); return (bf16_t)(u >> 16); }
; DI void phase_gemm_qkv(const Params& p, bf16_t* sm) {
;     ...
;         const int row = EPI_ROW4(mi, i);
;         const int col = n0 + ewn * 64 + er;
;         float x1 = acc[mi][0][i], x2 = acc[mi][1][i];
;         if (n0 < 1024) {
;           int pos = row & (SEQ - 1);
;           float c = p.ropeC[pos * 32 + er], s = p.ropeS[pos * 32 + er];
;           float o1 = x1 * c - x2 * s, o2 = x2 * c + x1 * s;
;           if (n0 < 512) { o1 *= 0.125f; o2 *= 0.125f; }
;           x1 = o1; x2 = o2;
;         }
;         qkv[(size_t)row * 1536 + col] = f2bf(x1);
;         qkv[(size_t)row * 1536 + col + 32] = f2bf(x2);
	v_mul_f32_e32 v160, s2, v160
	v_mul_f32_e32 v190, s2, v190
	v_mul_f32_e32 v248, v0, v190
	v_mul_f32_e32 v249, v16, v190
	v_fma_f32 v16, v16, v160, -v248
	v_fma_f32 v0, v0, v160, v249
	v_mul_f32_e32 v161, s2, v161
	v_mul_f32_e32 v191, s2, v191
	v_mul_f32_e32 v250, v1, v191
	v_mul_f32_e32 v251, v17, v191
	v_fma_f32 v17, v17, v161, -v250
	v_fma_f32 v1, v1, v161, v251
	v_mul_f32_e32 v162, s2, v162
	v_mul_f32_e32 v192, s2, v192
	v_mul_f32_e32 v248, v2, v192
	v_mul_f32_e32 v249, v18, v192
	v_fma_f32 v18, v18, v162, -v248
	v_fma_f32 v2, v2, v162, v249
	v_mul_f32_e32 v163, s2, v163
	v_mul_f32_e32 v193, s2, v193
	v_mul_f32_e32 v250, v3, v193
	v_mul_f32_e32 v251, v19, v193
	v_fma_f32 v19, v19, v163, -v250
	v_fma_f32 v3, v3, v163, v251
	v_mul_f32_e32 v164, s2, v164
	v_mul_f32_e32 v194, s2, v194
	v_mul_f32_e32 v248, v4, v194
	v_mul_f32_e32 v249, v20, v194
	v_fma_f32 v20, v20, v164, -v248
	v_fma_f32 v4, v4, v164, v249
	v_mul_f32_e32 v165, s2, v165
	v_mul_f32_e32 v195, s2, v195
	v_mul_f32_e32 v250, v5, v195
	v_mul_f32_e32 v251, v21, v195
	v_fma_f32 v21, v21, v165, -v250
	v_fma_f32 v5, v5, v165, v251
	v_mul_f32_e32 v166, s2, v166
	v_mul_f32_e32 v196, s2, v196
	v_mul_f32_e32 v248, v6, v196
	v_mul_f32_e32 v249, v22, v196
	v_fma_f32 v22, v22, v166, -v248
	v_fma_f32 v6, v6, v166, v249
	v_mul_f32_e32 v167, s2, v167
	v_mul_f32_e32 v197, s2, v197
	v_mul_f32_e32 v250, v7, v197
	v_mul_f32_e32 v251, v23, v197
	v_fma_f32 v23, v23, v167, -v250
	v_fma_f32 v7, v7, v167, v251
	v_mul_f32_e32 v168, s2, v168
	v_mul_f32_e32 v198, s2, v198
	v_mul_f32_e32 v248, v8, v198
	v_mul_f32_e32 v249, v24, v198
	v_fma_f32 v24, v24, v168, -v248
	v_fma_f32 v8, v8, v168, v249
	v_mul_f32_e32 v169, s2, v169
	v_mul_f32_e32 v199, s2, v199
	v_mul_f32_e32 v250, v9, v199
	v_mul_f32_e32 v251, v25, v199
	v_fma_f32 v25, v25, v169, -v250
	v_fma_f32 v9, v9, v169, v251
	v_mul_f32_e32 v170, s2, v170
	v_mul_f32_e32 v200, s2, v200
	v_mul_f32_e32 v248, v10, v200
	v_mul_f32_e32 v249, v26, v200
	v_fma_f32 v26, v26, v170, -v248
	v_fma_f32 v10, v10, v170, v249
	v_mul_f32_e32 v171, s2, v171
	v_mul_f32_e32 v201, s2, v201
	v_mul_f32_e32 v250, v11, v201
	v_mul_f32_e32 v251, v27, v201
	v_fma_f32 v27, v27, v171, -v250
	v_fma_f32 v11, v11, v171, v251
	v_mul_f32_e32 v172, s2, v172
	v_mul_f32_e32 v206, s2, v206
	v_mul_f32_e32 v248, v12, v206
	v_mul_f32_e32 v249, v28, v206
	v_fma_f32 v28, v28, v172, -v248
	v_fma_f32 v12, v12, v172, v249
	v_mul_f32_e32 v173, s2, v173
	v_mul_f32_e32 v207, s2, v207
	v_mul_f32_e32 v250, v13, v207
	v_mul_f32_e32 v251, v29, v207
	v_fma_f32 v29, v29, v173, -v250
	v_fma_f32 v13, v13, v173, v251
	v_mul_f32_e32 v174, s2, v174
	v_mul_f32_e32 v208, s2, v208
	v_mul_f32_e32 v248, v14, v208
	v_mul_f32_e32 v249, v30, v208
	v_fma_f32 v30, v30, v174, -v248
	v_fma_f32 v14, v14, v174, v249
	v_mul_f32_e32 v175, s2, v175
	v_mul_f32_e32 v209, s2, v209
	v_mul_f32_e32 v250, v15, v209
	v_mul_f32_e32 v251, v31, v209
	v_fma_f32 v31, v31, v175, -v250
	v_fma_f32 v15, v15, v175, v251
.Lqkv1_store:
	s_nop 1
	v_bfe_u32 v248, v112, 16, 1
	v_bfe_u32 v249, v96, 16, 1
	v_add3_u32 v248, v112, v248, s12
	v_add3_u32 v249, v96, v249, s12
	global_store_short_d16_hi v247, v248, s[10:11]
	global_store_short_d16_hi v247, v249, s[10:11] offset:64
	v_add_u32_e32 v247, 0xc00, v247
	v_bfe_u32 v250, v113, 16, 1
	v_bfe_u32 v251, v97, 16, 1
	v_add3_u32 v250, v113, v250, s12
	v_add3_u32 v251, v97, v251, s12
	global_store_short_d16_hi v247, v250, s[10:11]
	global_store_short_d16_hi v247, v251, s[10:11] offset:64
	v_add_u32_e32 v247, 0xc00, v247
	v_bfe_u32 v248, v114, 16, 1
	v_bfe_u32 v249, v98, 16, 1
	v_add3_u32 v248, v114, v248, s12
	v_add3_u32 v249, v98, v249, s12
	global_store_short_d16_hi v247, v248, s[10:11]
	global_store_short_d16_hi v247, v249, s[10:11] offset:64
	v_add_u32_e32 v247, 0xc00, v247
	v_bfe_u32 v250, v115, 16, 1
	v_bfe_u32 v251, v99, 16, 1
	v_add3_u32 v250, v115, v250, s12
	v_add3_u32 v251, v99, v251, s12
	global_store_short_d16_hi v247, v250, s[10:11]
	global_store_short_d16_hi v247, v251, s[10:11] offset:64
	v_add_u32_e32 v247, 0x3c00, v247
	v_bfe_u32 v248, v116, 16, 1
	v_bfe_u32 v249, v100, 16, 1
	v_add3_u32 v248, v116, v248, s12
	v_add3_u32 v249, v100, v249, s12
	global_store_short_d16_hi v247, v248, s[10:11]
	global_store_short_d16_hi v247, v249, s[10:11] offset:64
	v_add_u32_e32 v247, 0xc00, v247
	v_bfe_u32 v250, v117, 16, 1
	v_bfe_u32 v251, v101, 16, 1
	v_add3_u32 v250, v117, v250, s12
	v_add3_u32 v251, v101, v251, s12
	global_store_short_d16_hi v247, v250, s[10:11]
	global_store_short_d16_hi v247, v251, s[10:11] offset:64
	v_add_u32_e32 v247, 0xc00, v247
	v_bfe_u32 v248, v118, 16, 1
	v_bfe_u32 v249, v102, 16, 1
	v_add3_u32 v248, v118, v248, s12
	v_add3_u32 v249, v102, v249, s12
	global_store_short_d16_hi v247, v248, s[10:11]
	global_store_short_d16_hi v247, v249, s[10:11] offset:64
	v_add_u32_e32 v247, 0xc00, v247
	v_bfe_u32 v250, v119, 16, 1
	v_bfe_u32 v251, v103, 16, 1
	v_add3_u32 v250, v119, v250, s12
	v_add3_u32 v251, v103, v251, s12
	global_store_short_d16_hi v247, v250, s[10:11]
	global_store_short_d16_hi v247, v251, s[10:11] offset:64
	v_add_u32_e32 v247, 0x3c00, v247
	v_bfe_u32 v248, v120, 16, 1
	v_bfe_u32 v249, v104, 16, 1
	v_add3_u32 v248, v120, v248, s12
	v_add3_u32 v249, v104, v249, s12
	global_store_short_d16_hi v247, v248, s[10:11]
	global_store_short_d16_hi v247, v249, s[10:11] offset:64
	v_add_u32_e32 v247, 0xc00, v247
	v_bfe_u32 v250, v121, 16, 1
	v_bfe_u32 v251, v105, 16, 1
	v_add3_u32 v250, v121, v250, s12
	v_add3_u32 v251, v105, v251, s12
	global_store_short_d16_hi v247, v250, s[10:11]
	global_store_short_d16_hi v247, v251, s[10:11] offset:64
	v_add_u32_e32 v247, 0xc00, v247
; DI bf16_t f2bf(float x) { unsigned u = __float_as_uint(x); u += 0x7fffu + ((u >> 16) & 1u); return (bf16_t)(u >> 16); }
; DI void phase_gemm_qkv(const Params& p, bf16_t* sm) {
;     ...
;         const int row = EPI_ROW4(mi, i);
;         const int col = n0 + ewn * 64 + er;
;         float x1 = acc[mi][0][i], x2 = acc[mi][1][i];
;         if (n0 < 1024) {
;           int pos = row & (SEQ - 1);
;           float c = p.ropeC[pos * 32 + er], s = p.ropeS[pos * 32 + er];
;           float o1 = x1 * c - x2 * s, o2 = x2 * c + x1 * s;
;           if (n0 < 512) { o1 *= 0.125f; o2 *= 0.125f; }
;           x1 = o1; x2 = o2;
;         }
;         qkv[(size_t)row * 1536 + col] = f2bf(x1);
;         qkv[(size_t)row * 1536 + col + 32] = f2bf(x2);
	v_bfe_u32 v248, v122, 16, 1
	v_bfe_u32 v249, v106, 16, 1
	v_add3_u32 v248, v122, v248, s12
	v_add3_u32 v249, v106, v249, s12
	global_store_short_d16_hi v247, v248, s[10:11]
	global_store_short_d16_hi v247, v249, s[10:11] offset:64
	v_add_u32_e32 v247, 0xc00, v247
	v_bfe_u32 v250, v123, 16, 1
	v_bfe_u32 v251, v107, 16, 1
	v_add3_u32 v250, v123, v250, s12
	v_add3_u32 v251, v107, v251, s12
	global_store_short_d16_hi v247, v250, s[10:11]
	global_store_short_d16_hi v247, v251, s[10:11] offset:64
	v_add_u32_e32 v247, 0x3c00, v247
	v_bfe_u32 v248, v124, 16, 1
	v_bfe_u32 v249, v108, 16, 1
	v_add3_u32 v248, v124, v248, s12
	v_add3_u32 v249, v108, v249, s12
	global_store_short_d16_hi v247, v248, s[10:11]
	global_store_short_d16_hi v247, v249, s[10:11] offset:64
	v_add_u32_e32 v247, 0xc00, v247
	v_bfe_u32 v250, v125, 16, 1
	v_bfe_u32 v251, v109, 16, 1
	v_add3_u32 v250, v125, v250, s12
	v_add3_u32 v251, v109, v251, s12
	global_store_short_d16_hi v247, v250, s[10:11]
	global_store_short_d16_hi v247, v251, s[10:11] offset:64
	v_add_u32_e32 v247, 0xc00, v247
	v_bfe_u32 v248, v126, 16, 1
	v_bfe_u32 v249, v110, 16, 1
	v_add3_u32 v248, v126, v248, s12
	v_add3_u32 v249, v110, v249, s12
	global_store_short_d16_hi v247, v248, s[10:11]
	global_store_short_d16_hi v247, v249, s[10:11] offset:64
	v_add_u32_e32 v247, 0xc00, v247
	v_bfe_u32 v250, v127, 16, 1
	v_bfe_u32 v251, v111, 16, 1
	v_add3_u32 v250, v127, v250, s12
	v_add3_u32 v251, v111, v251, s12
	global_store_short_d16_hi v247, v250, s[10:11]
	global_store_short_d16_hi v247, v251, s[10:11] offset:64
	v_add_u32_e32 v247, 0x3c00, v247
	v_bfe_u32 v248, v80, 16, 1
	v_bfe_u32 v249, v64, 16, 1
	v_add3_u32 v248, v80, v248, s12
	v_add3_u32 v249, v64, v249, s12
	global_store_short_d16_hi v247, v248, s[10:11]
	global_store_short_d16_hi v247, v249, s[10:11] offset:64
	v_add_u32_e32 v247, 0xc00, v247
	v_bfe_u32 v250, v81, 16, 1
	v_bfe_u32 v251, v65, 16, 1
	v_add3_u32 v250, v81, v250, s12
	v_add3_u32 v251, v65, v251, s12
	global_store_short_d16_hi v247, v250, s[10:11]
	global_store_short_d16_hi v247, v251, s[10:11] offset:64
	v_add_u32_e32 v247, 0xc00, v247
	v_bfe_u32 v248, v82, 16, 1
	v_bfe_u32 v249, v66, 16, 1
	v_add3_u32 v248, v82, v248, s12
	v_add3_u32 v249, v66, v249, s12
	global_store_short_d16_hi v247, v248, s[10:11]
	global_store_short_d16_hi v247, v249, s[10:11] offset:64
	v_add_u32_e32 v247, 0xc00, v247
	v_bfe_u32 v250, v83, 16, 1
	v_bfe_u32 v251, v67, 16, 1
	v_add3_u32 v250, v83, v250, s12
	v_add3_u32 v251, v67, v251, s12
	global_store_short_d16_hi v247, v250, s[10:11]
	global_store_short_d16_hi v247, v251, s[10:11] offset:64
	v_add_u32_e32 v247, 0x3c00, v247
	v_bfe_u32 v248, v84, 16, 1
	v_bfe_u32 v249, v68, 16, 1
	v_add3_u32 v248, v84, v248, s12
	v_add3_u32 v249, v68, v249, s12
	global_store_short_d16_hi v247, v248, s[10:11]
	global_store_short_d16_hi v247, v249, s[10:11] offset:64
	v_add_u32_e32 v247, 0xc00, v247
	v_bfe_u32 v250, v85, 16, 1
	v_bfe_u32 v251, v69, 16, 1
	v_add3_u32 v250, v85, v250, s12
	v_add3_u32 v251, v69, v251, s12
	global_store_short_d16_hi v247, v250, s[10:11]
	global_store_short_d16_hi v247, v251, s[10:11] offset:64
	v_add_u32_e32 v247, 0xc00, v247
	v_bfe_u32 v248, v86, 16, 1
	v_bfe_u32 v249, v70, 16, 1
	v_add3_u32 v248, v86, v248, s12
	v_add3_u32 v249, v70, v249, s12
	global_store_short_d16_hi v247, v248, s[10:11]
	global_store_short_d16_hi v247, v249, s[10:11] offset:64
	v_add_u32_e32 v247, 0xc00, v247
	v_bfe_u32 v250, v87, 16, 1
	v_bfe_u32 v251, v71, 16, 1
	v_add3_u32 v250, v87, v250, s12
	v_add3_u32 v251, v71, v251, s12
	global_store_short_d16_hi v247, v250, s[10:11]
	global_store_short_d16_hi v247, v251, s[10:11] offset:64
	v_add_u32_e32 v247, 0x3c00, v247
	v_bfe_u32 v248, v88, 16, 1
	v_bfe_u32 v249, v72, 16, 1
	v_add3_u32 v248, v88, v248, s12
	v_add3_u32 v249, v72, v249, s12
	global_store_short_d16_hi v247, v248, s[10:11]
	global_store_short_d16_hi v247, v249, s[10:11] offset:64
	v_add_u32_e32 v247, 0xc00, v247
	v_bfe_u32 v250, v89, 16, 1
	v_bfe_u32 v251, v73, 16, 1
	v_add3_u32 v250, v89, v250, s12
	v_add3_u32 v251, v73, v251, s12
	global_store_short_d16_hi v247, v250, s[10:11]
	global_store_short_d16_hi v247, v251, s[10:11] offset:64
	v_add_u32_e32 v247, 0xc00, v247
	v_bfe_u32 v248, v90, 16, 1
	v_bfe_u32 v249, v74, 16, 1
	v_add3_u32 v248, v90, v248, s12
	v_add3_u32 v249, v74, v249, s12
	global_store_short_d16_hi v247, v248, s[10:11]
	global_store_short_d16_hi v247, v249, s[10:11] offset:64
	v_add_u32_e32 v247, 0xc00, v247
	v_bfe_u32 v250, v91, 16, 1
	v_bfe_u32 v251, v75, 16, 1
	v_add3_u32 v250, v91, v250, s12
	v_add3_u32 v251, v75, v251, s12
	global_store_short_d16_hi v247, v250, s[10:11]
	global_store_short_d16_hi v247, v251, s[10:11] offset:64
	v_add_u32_e32 v247, 0x3c00, v247
	v_bfe_u32 v248, v92, 16, 1
	v_bfe_u32 v249, v76, 16, 1
	v_add3_u32 v248, v92, v248, s12
	v_add3_u32 v249, v76, v249, s12
	global_store_short_d16_hi v247, v248, s[10:11]
	global_store_short_d16_hi v247, v249, s[10:11] offset:64
	v_add_u32_e32 v247, 0xc00, v247
	v_bfe_u32 v250, v93, 16, 1
	v_bfe_u32 v251, v77, 16, 1
	v_add3_u32 v250, v93, v250, s12
	v_add3_u32 v251, v77, v251, s12
	global_store_short_d16_hi v247, v250, s[10:11]
	global_store_short_d16_hi v247, v251, s[10:11] offset:64
	v_add_u32_e32 v247, 0xc00, v247
	v_bfe_u32 v248, v94, 16, 1
	v_bfe_u32 v249, v78, 16, 1
	v_add3_u32 v248, v94, v248, s12
	v_add3_u32 v249, v78, v249, s12
	global_store_short_d16_hi v247, v248, s[10:11]
	global_store_short_d16_hi v247, v249, s[10:11] offset:64
	v_add_u32_e32 v247, 0xc00, v247
	v_bfe_u32 v250, v95, 16, 1
	v_bfe_u32 v251, v79, 16, 1
	v_add3_u32 v250, v95, v250, s12
	v_add3_u32 v251, v79, v251, s12
; DI bf16_t f2bf(float x) { unsigned u = __float_as_uint(x); u += 0x7fffu + ((u >> 16) & 1u); return (bf16_t)(u >> 16); }
; DI void phase_gemm_qkv(const Params& p, bf16_t* sm) {
;     ...
;         const int row = EPI_ROW4(mi, i);
;         const int col = n0 + ewn * 64 + er;
;         float x1 = acc[mi][0][i], x2 = acc[mi][1][i];
;         if (n0 < 1024) {
;           int pos = row & (SEQ - 1);
;           float c = p.ropeC[pos * 32 + er], s = p.ropeS[pos * 32 + er];
;           float o1 = x1 * c - x2 * s, o2 = x2 * c + x1 * s;
;           if (n0 < 512) { o1 *= 0.125f; o2 *= 0.125f; }
;           x1 = o1; x2 = o2;
;         }
;         qkv[(size_t)row * 1536 + col] = f2bf(x1);
;         qkv[(size_t)row * 1536 + col + 32] = f2bf(x2);
	global_store_short_d16_hi v247, v250, s[10:11]
	global_store_short_d16_hi v247, v251, s[10:11] offset:64
	v_add_u32_e32 v247, 0x3c00, v247
	v_bfe_u32 v248, v48, 16, 1
	v_bfe_u32 v249, v32, 16, 1
	v_add3_u32 v248, v48, v248, s12
	v_add3_u32 v249, v32, v249, s12
	global_store_short_d16_hi v247, v248, s[10:11]
	global_store_short_d16_hi v247, v249, s[10:11] offset:64
	v_add_u32_e32 v247, 0xc00, v247
	v_bfe_u32 v250, v49, 16, 1
	v_bfe_u32 v251, v33, 16, 1
	v_add3_u32 v250, v49, v250, s12
	v_add3_u32 v251, v33, v251, s12
	global_store_short_d16_hi v247, v250, s[10:11]
	global_store_short_d16_hi v247, v251, s[10:11] offset:64
	v_add_u32_e32 v247, 0xc00, v247
	v_bfe_u32 v248, v50, 16, 1
	v_bfe_u32 v249, v34, 16, 1
	v_add3_u32 v248, v50, v248, s12
	v_add3_u32 v249, v34, v249, s12
	global_store_short_d16_hi v247, v248, s[10:11]
	global_store_short_d16_hi v247, v249, s[10:11] offset:64
	v_add_u32_e32 v247, 0xc00, v247
	v_bfe_u32 v250, v51, 16, 1
	v_bfe_u32 v251, v35, 16, 1
	v_add3_u32 v250, v51, v250, s12
	v_add3_u32 v251, v35, v251, s12
	global_store_short_d16_hi v247, v250, s[10:11]
	global_store_short_d16_hi v247, v251, s[10:11] offset:64
	v_add_u32_e32 v247, 0x3c00, v247
	v_bfe_u32 v248, v52, 16, 1
	v_bfe_u32 v249, v36, 16, 1
	v_add3_u32 v248, v52, v248, s12
	v_add3_u32 v249, v36, v249, s12
	global_store_short_d16_hi v247, v248, s[10:11]
	global_store_short_d16_hi v247, v249, s[10:11] offset:64
	v_add_u32_e32 v247, 0xc00, v247
	v_bfe_u32 v250, v53, 16, 1
	v_bfe_u32 v251, v37, 16, 1
	v_add3_u32 v250, v53, v250, s12
	v_add3_u32 v251, v37, v251, s12
	global_store_short_d16_hi v247, v250, s[10:11]
	global_store_short_d16_hi v247, v251, s[10:11] offset:64
	v_add_u32_e32 v247, 0xc00, v247
	v_bfe_u32 v248, v54, 16, 1
	v_bfe_u32 v249, v38, 16, 1
	v_add3_u32 v248, v54, v248, s12
	v_add3_u32 v249, v38, v249, s12
	global_store_short_d16_hi v247, v248, s[10:11]
	global_store_short_d16_hi v247, v249, s[10:11] offset:64
	v_add_u32_e32 v247, 0xc00, v247
	v_bfe_u32 v250, v55, 16, 1
	v_bfe_u32 v251, v39, 16, 1
	v_add3_u32 v250, v55, v250, s12
	v_add3_u32 v251, v39, v251, s12
	global_store_short_d16_hi v247, v250, s[10:11]
	global_store_short_d16_hi v247, v251, s[10:11] offset:64
	v_add_u32_e32 v247, 0x3c00, v247
	v_bfe_u32 v248, v56, 16, 1
	v_bfe_u32 v249, v40, 16, 1
	v_add3_u32 v248, v56, v248, s12
	v_add3_u32 v249, v40, v249, s12
	global_store_short_d16_hi v247, v248, s[10:11]
	global_store_short_d16_hi v247, v249, s[10:11] offset:64
	v_add_u32_e32 v247, 0xc00, v247
	v_bfe_u32 v250, v57, 16, 1
	v_bfe_u32 v251, v41, 16, 1
	v_add3_u32 v250, v57, v250, s12
	v_add3_u32 v251, v41, v251, s12
	global_store_short_d16_hi v247, v250, s[10:11]
	global_store_short_d16_hi v247, v251, s[10:11] offset:64
	v_add_u32_e32 v247, 0xc00, v247
	v_bfe_u32 v248, v58, 16, 1
	v_bfe_u32 v249, v42, 16, 1
	v_add3_u32 v248, v58, v248, s12
	v_add3_u32 v249, v42, v249, s12
	global_store_short_d16_hi v247, v248, s[10:11]
	global_store_short_d16_hi v247, v249, s[10:11] offset:64
	v_add_u32_e32 v247, 0xc00, v247
	v_bfe_u32 v250, v59, 16, 1
	v_bfe_u32 v251, v43, 16, 1
	v_add3_u32 v250, v59, v250, s12
	v_add3_u32 v251, v43, v251, s12
	global_store_short_d16_hi v247, v250, s[10:11]
	global_store_short_d16_hi v247, v251, s[10:11] offset:64
	v_add_u32_e32 v247, 0x3c00, v247
	v_bfe_u32 v248, v60, 16, 1
	v_bfe_u32 v249, v44, 16, 1
	v_add3_u32 v248, v60, v248, s12
	v_add3_u32 v249, v44, v249, s12
	global_store_short_d16_hi v247, v248, s[10:11]
	global_store_short_d16_hi v247, v249, s[10:11] offset:64
	v_add_u32_e32 v247, 0xc00, v247
	v_bfe_u32 v250, v61, 16, 1
	v_bfe_u32 v251, v45, 16, 1
	v_add3_u32 v250, v61, v250, s12
	v_add3_u32 v251, v45, v251, s12
	global_store_short_d16_hi v247, v250, s[10:11]
	global_store_short_d16_hi v247, v251, s[10:11] offset:64
	v_add_u32_e32 v247, 0xc00, v247
	v_bfe_u32 v248, v62, 16, 1
	v_bfe_u32 v249, v46, 16, 1
	v_add3_u32 v248, v62, v248, s12
	v_add3_u32 v249, v46, v249, s12
	global_store_short_d16_hi v247, v248, s[10:11]
	global_store_short_d16_hi v247, v249, s[10:11] offset:64
	v_add_u32_e32 v247, 0xc00, v247
	v_bfe_u32 v250, v63, 16, 1
	v_bfe_u32 v251, v47, 16, 1
	v_add3_u32 v250, v63, v250, s12
	v_add3_u32 v251, v47, v251, s12
	global_store_short_d16_hi v247, v250, s[10:11]
; DI bf16_t f2bf(float x) { unsigned u = __float_as_uint(x); u += 0x7fffu + ((u >> 16) & 1u); return (bf16_t)(u >> 16); }
; DI void phase_gemm_qkv(const Params& p, bf16_t* sm) {
;     ...
;         const int row = EPI_ROW4(mi, i);
;         const int col = n0 + ewn * 64 + er;
;         float x1 = acc[mi][0][i], x2 = acc[mi][1][i];
;         if (n0 < 1024) {
;           int pos = row & (SEQ - 1);
;           float c = p.ropeC[pos * 32 + er], s = p.ropeS[pos * 32 + er];
;           float o1 = x1 * c - x2 * s, o2 = x2 * c + x1 * s;
;           if (n0 < 512) { o1 *= 0.125f; o2 *= 0.125f; }
;           x1 = o1; x2 = o2;
;         }
;         qkv[(size_t)row * 1536 + col] = f2bf(x1);
;         qkv[(size_t)row * 1536 + col + 32] = f2bf(x2);
	global_store_short_d16_hi v247, v251, s[10:11] offset:64
	v_add_u32_e32 v247, 0x3c00, v247
	v_bfe_u32 v248, v16, 16, 1
	v_bfe_u32 v249, v0, 16, 1
	v_add3_u32 v248, v16, v248, s12
	v_add3_u32 v249, v0, v249, s12
	global_store_short_d16_hi v247, v248, s[10:11]
	global_store_short_d16_hi v247, v249, s[10:11] offset:64
	v_add_u32_e32 v247, 0xc00, v247
	v_bfe_u32 v250, v17, 16, 1
	v_bfe_u32 v251, v1, 16, 1
	v_add3_u32 v250, v17, v250, s12
	v_add3_u32 v251, v1, v251, s12
	global_store_short_d16_hi v247, v250, s[10:11]
	global_store_short_d16_hi v247, v251, s[10:11] offset:64
	v_add_u32_e32 v247, 0xc00, v247
	v_bfe_u32 v248, v18, 16, 1
	v_bfe_u32 v249, v2, 16, 1
	v_add3_u32 v248, v18, v248, s12
	v_add3_u32 v249, v2, v249, s12
	global_store_short_d16_hi v247, v248, s[10:11]
	global_store_short_d16_hi v247, v249, s[10:11] offset:64
	v_add_u32_e32 v247, 0xc00, v247
	v_bfe_u32 v250, v19, 16, 1
	v_bfe_u32 v251, v3, 16, 1
	v_add3_u32 v250, v19, v250, s12
	v_add3_u32 v251, v3, v251, s12
	global_store_short_d16_hi v247, v250, s[10:11]
	global_store_short_d16_hi v247, v251, s[10:11] offset:64
	v_add_u32_e32 v247, 0x3c00, v247
	v_bfe_u32 v248, v20, 16, 1
	v_bfe_u32 v249, v4, 16, 1
	v_add3_u32 v248, v20, v248, s12
	v_add3_u32 v249, v4, v249, s12
	global_store_short_d16_hi v247, v248, s[10:11]
	global_store_short_d16_hi v247, v249, s[10:11] offset:64
	v_add_u32_e32 v247, 0xc00, v247
	v_bfe_u32 v250, v21, 16, 1
	v_bfe_u32 v251, v5, 16, 1
	v_add3_u32 v250, v21, v250, s12
	v_add3_u32 v251, v5, v251, s12
	global_store_short_d16_hi v247, v250, s[10:11]
	global_store_short_d16_hi v247, v251, s[10:11] offset:64
	v_add_u32_e32 v247, 0xc00, v247
	v_bfe_u32 v248, v22, 16, 1
	v_bfe_u32 v249, v6, 16, 1
	v_add3_u32 v248, v22, v248, s12
	v_add3_u32 v249, v6, v249, s12
	global_store_short_d16_hi v247, v248, s[10:11]
	global_store_short_d16_hi v247, v249, s[10:11] offset:64
	v_add_u32_e32 v247, 0xc00, v247
	v_bfe_u32 v250, v23, 16, 1
	v_bfe_u32 v251, v7, 16, 1
	v_add3_u32 v250, v23, v250, s12
	v_add3_u32 v251, v7, v251, s12
	global_store_short_d16_hi v247, v250, s[10:11]
	global_store_short_d16_hi v247, v251, s[10:11] offset:64
	v_add_u32_e32 v247, 0x3c00, v247
	v_bfe_u32 v248, v24, 16, 1
	v_bfe_u32 v249, v8, 16, 1
	v_add3_u32 v248, v24, v248, s12
	v_add3_u32 v249, v8, v249, s12
	global_store_short_d16_hi v247, v248, s[10:11]
	global_store_short_d16_hi v247, v249, s[10:11] offset:64
	v_add_u32_e32 v247, 0xc00, v247
	v_bfe_u32 v250, v25, 16, 1
	v_bfe_u32 v251, v9, 16, 1
	v_add3_u32 v250, v25, v250, s12
	v_add3_u32 v251, v9, v251, s12
	global_store_short_d16_hi v247, v250, s[10:11]
	global_store_short_d16_hi v247, v251, s[10:11] offset:64
	v_add_u32_e32 v247, 0xc00, v247
	v_bfe_u32 v248, v26, 16, 1
	v_bfe_u32 v249, v10, 16, 1
	v_add3_u32 v248, v26, v248, s12
	v_add3_u32 v249, v10, v249, s12
	global_store_short_d16_hi v247, v248, s[10:11]
	global_store_short_d16_hi v247, v249, s[10:11] offset:64
	v_add_u32_e32 v247, 0xc00, v247
	v_bfe_u32 v250, v27, 16, 1
	v_bfe_u32 v251, v11, 16, 1
	v_add3_u32 v250, v27, v250, s12
	v_add3_u32 v251, v11, v251, s12
	global_store_short_d16_hi v247, v250, s[10:11]
	global_store_short_d16_hi v247, v251, s[10:11] offset:64
	v_add_u32_e32 v247, 0x3c00, v247
	v_bfe_u32 v248, v28, 16, 1
	v_bfe_u32 v249, v12, 16, 1
	v_add3_u32 v248, v28, v248, s12
	v_add3_u32 v249, v12, v249, s12
	global_store_short_d16_hi v247, v248, s[10:11]
	global_store_short_d16_hi v247, v249, s[10:11] offset:64
	v_add_u32_e32 v247, 0xc00, v247
	v_bfe_u32 v250, v29, 16, 1
	v_bfe_u32 v251, v13, 16, 1
	v_add3_u32 v250, v29, v250, s12
	v_add3_u32 v251, v13, v251, s12
	global_store_short_d16_hi v247, v250, s[10:11]
	global_store_short_d16_hi v247, v251, s[10:11] offset:64
	v_add_u32_e32 v247, 0xc00, v247
	v_bfe_u32 v248, v30, 16, 1
	v_bfe_u32 v249, v14, 16, 1
	v_add3_u32 v248, v30, v248, s12
	v_add3_u32 v249, v14, v249, s12
	global_store_short_d16_hi v247, v248, s[10:11]
	global_store_short_d16_hi v247, v249, s[10:11] offset:64
	v_add_u32_e32 v247, 0xc00, v247
	v_bfe_u32 v250, v31, 16, 1
	v_bfe_u32 v251, v15, 16, 1
	v_add3_u32 v250, v31, v250, s12
	v_add3_u32 v251, v15, v251, s12
	global_store_short_d16_hi v247, v250, s[10:11]
	global_store_short_d16_hi v247, v251, s[10:11] offset:64
	s_branch .LBB0_2064

; DI float bf2f(bf16_t b) { return __uint_as_float(((unsigned)b) << 16); }
; template <bool PASS2>
; DI void rwkv_item(const Params& p, int l, int item, int lane, const bf16_t* rkv, const bf16_t* lo2, float* rwst) {
;   const int b = item / (8 * NCHR), head = (item / NCHR) % 8, c = item % NCHR;
;   const int ch = head * 64 + lane;
;   const float mu_r = p.in[I_RW_MU_RKV][(size_t)l * 1536 + ch], mu_k = p.in[I_RW_MU_RKV][(size_t)l * 1536 + 512 + ch];
;   const float kkw = p.in[I_RW_K_K][l * 512 + ch], kaw = p.in[I_RW_K_A][l * 512 + ch];
;   const float rkw = p.in[I_RW_R_K][l * 512 + ch];
;   const float gnw = p.in[I_RW_GN_W][l * 512 + ch], gnb = p.in[I_RW_GN_B][l * 512 + ch];
;   const size_t tok0 = (size_t)b * SEQ + (size_t)c * LCR;
;   float* stS = rwst + ((size_t)((b * 8 + head) * NCHR + c)) * 4096;
;   float* stP = (float*)p.yc + ((size_t)((b * 8 + head) * NCHR + c)) * 4096;
;   float S[64], P[64];
; #pragma unroll
;   for (int j = 0; j < 64; j++) { S[j] = 0.f; P[j] = (j == lane) ? 1.f : 0.f; }
;   if (PASS2 && c > 0) {
;     const float4* sp = (const float4*)(stS - 4096 + lane * 64);
; #pragma unroll
;     for (int j = 0; j < 16; j++) { float4 v = sp[j]; S[4 * j] = v.x; S[4 * j + 1] = v.y; S[4 * j + 2] = v.z; S[4 * j + 3] = v.w; }
;   }
;   float rp_prev = 0.f, kp_prev = 0.f;
;   if (c > 0) { rp_prev = bf2f(rkv[(tok0 - 1) * 1536 + ch]); kp_prev = bf2f(rkv[(tok0 - 1) * 1536 + 512 + ch]); }
;   const bf16_t* ewb = lo2; const bf16_t* ab = lo2 + (size_t)TOK * 512; const bf16_t* gb = lo2 + (size_t)2 * TOK * 512;
.LBB0_3030:
	s_or_b64 exec, exec, s[0:1]
	s_waitcnt lgkmcnt(0)
	v_mov_b32_e32 v0, v210
	v_mov_b32_e32 v1, v210
	s_barrier
	v_readlane_b32 s0, v252, 1
	v_bfe_u32 v1, v1, 6, 2
	v_readlane_b32 s1, v252, 2
	v_mul_lo_u32 v1, v1, s0
	v_readlane_b32 s0, v252, 26
	s_nop 1
	v_add_u32_e32 v201, s0, v1
	s_movk_i32 s0, 0x800
	v_cmp_gt_i32_e32 vcc, s0, v201
	s_and_saveexec_b64 s[0:1], vcc
	s_cbranch_execz .LBB0_3041
	v_and_b32_e32 v0, 63, v210
	v_lshrrev_b32_e32 v1, 6, v210
	v_and_b32_e32 v1, 3, v1
	v_lshlrev_b32_e32 v1, 10, v1
	v_lshrrev_b32_e32 v2, 5, v0
	v_lshl_add_u32 v2, v2, 4, v1
	v_lshl_add_u32 v1, v0, 2, v1
	v_readlane_b32 s36, v252, 3
	v_readlane_b32 s37, v252, 4
	v_readlane_b32 s17, v252, 1
	v_readfirstlane_b32 s16, v201
	s_sub_u32 s36, s36, 0x180
	s_subb_u32 s37, s37, 0
	s_lshl_b32 s17, s17, 2
	s_load_dwordx2 s[2:3], s[36:37], 0x170
	s_load_dwordx2 s[12:13], s[36:37], 0x68
	s_load_dwordx2 s[14:15], s[36:37], 0xb8
	s_load_dwordx2 s[34:35], s[36:37], 0xc0
	s_waitcnt lgkmcnt(0)
.Lrwp1b_item:
	s_lshr_b32 s19, s16, 10
	s_bfe_u32 s20, s16, 0x30007
	s_and_b32 s21, s16, 127
	s_lshl_b32 s22, s19, 14
	s_lshl_b32 s23, s21, 7
	s_add_u32 s22, s22, s23
	v_lshl_add_u32 v3, s20, 6, v0
	v_lshlrev_b32_e32 v4, 2, v3
	v_lshlrev_b32_e32 v232, 1, v3
	s_add_u32 s28, s12, 0x2000
	s_addc_u32 s29, s13, 0
	global_load_dword v10, v4, s[28:29]
	s_add_u32 s28, s14, 0x800
	s_addc_u32 s29, s15, 0
	global_load_dword v11, v4, s[28:29]
	s_add_u32 s28, s34, 0x800
	s_addc_u32 s29, s35, 0
	global_load_dword v12, v4, s[28:29]
	s_add_u32 s4, s2, 0x17558000
	s_addc_u32 s5, s3, 0
	s_add_u32 s6, s2, 0x3558000
	s_addc_u32 s7, s3, 0
	s_add_u32 s8, s2, 0x11558000
	s_addc_u32 s9, s3, 0
	s_add_u32 s10, s2, 0x13558000
	s_addc_u32 s11, s3, 0
	s_lshl_b32 s23, s19, 3
	s_add_u32 s23, s23, s20
	s_lshl_b32 s23, s23, 7
	s_add_u32 s23, s23, s21
	s_lshr_b32 s25, s23, 18
	s_lshl_b32 s24, s23, 14
	s_add_u32 s24, s24, s2
	s_addc_u32 s25, s25, s3
	s_add_u32 s24, s24, 0x1d558000
	s_addc_u32 s25, s25, 0
	s_add_u32 s26, s24, 0x2000
	s_addc_u32 s27, s25, 0
	s_lshr_b32 s41, s23, 18
	s_lshl_b32 s40, s23, 14
	s_add_u32 s40, s40, s2
	s_addc_u32 s41, s41, s3
	s_add_u32 s40, s40, 0xd558000
	s_addc_u32 s41, s41, 0
	s_add_u32 s38, s40, 0x2000
	s_addc_u32 s39, s41, 0
	v_and_b32_e32 v5, 63, v210
	v_and_b32_e32 v6, 31, v5
	v_lshrrev_b32_e32 v7, 5, v5
	v_lshlrev_b32_e32 v26, 8, v6
	v_lshl_add_u32 v26, v7, 4, v26
	s_mul_i32 s28, s22, 0xc00
	s_lshl_b32 s29, s22, 10
	s_waitcnt vmcnt(0)
	v_lshlrev_b32_e32 v27, 2, v7
	v_sub_u32_e32 v27, v6, v27
	v_add_u32_e32 v3, s28, v232
	v_add_u32_e32 v4, s29, v232
	v_mov_b32_e32 v6, 0
	v_mov_b32_e32 v7, 0
	s_cmp_eq_u32 s21, 0
	s_cbranch_scc1 .Lrwp1b_noprev
	global_load_ushort v7, v3, s[4:5] offset:-2048

; DI float bf2f(bf16_t b) { return __uint_as_float(((unsigned)b) << 16); }
; template <bool PASS2>
; DI void rwkv_item(const Params& p, int l, int item, int lane, const bf16_t* rkv, const bf16_t* lo2, float* rwst) {
;   const int b = item / (8 * NCHR), head = (item / NCHR) % 8, c = item % NCHR;
;   const int ch = head * 64 + lane;
;   const float mu_r = p.in[I_RW_MU_RKV][(size_t)l * 1536 + ch], mu_k = p.in[I_RW_MU_RKV][(size_t)l * 1536 + 512 + ch];
;   const float kkw = p.in[I_RW_K_K][l * 512 + ch], kaw = p.in[I_RW_K_A][l * 512 + ch];
;   const float rkw = p.in[I_RW_R_K][l * 512 + ch];
;   const float gnw = p.in[I_RW_GN_W][l * 512 + ch], gnb = p.in[I_RW_GN_B][l * 512 + ch];
;   const size_t tok0 = (size_t)b * SEQ + (size_t)c * LCR;
;   float* stS = rwst + ((size_t)((b * 8 + head) * NCHR + c)) * 4096;
;   float* stP = (float*)p.yc + ((size_t)((b * 8 + head) * NCHR + c)) * 4096;
;   float S[64], P[64];
; #pragma unroll
;   for (int j = 0; j < 64; j++) { S[j] = 0.f; P[j] = (j == lane) ? 1.f : 0.f; }
;   if (PASS2 && c > 0) {
;     const float4* sp = (const float4*)(stS - 4096 + lane * 64);
; #pragma unroll
;     for (int j = 0; j < 16; j++) { float4 v = sp[j]; S[4 * j] = v.x; S[4 * j + 1] = v.y; S[4 * j + 2] = v.z; S[4 * j + 3] = v.w; }
;   }
;   float rp_prev = 0.f, kp_prev = 0.f;
;   if (c > 0) { rp_prev = bf2f(rkv[(tok0 - 1) * 1536 + ch]); kp_prev = bf2f(rkv[(tok0 - 1) * 1536 + 512 + ch]); }
;   const bf16_t* ewb = lo2; const bf16_t* ab = lo2 + (size_t)TOK * 512; const bf16_t* gb = lo2 + (size_t)2 * TOK * 512;
.LBB0_3297:
	s_or_b64 exec, exec, s[0:1]
	s_waitcnt lgkmcnt(0)
	v_mov_b32_e32 v0, v210
	v_mov_b32_e32 v1, v210
	s_barrier
	v_readlane_b32 s0, v252, 1
	v_bfe_u32 v1, v1, 6, 2
	v_readlane_b32 s1, v252, 2
	v_mul_lo_u32 v1, v1, s0
	v_readlane_b32 s0, v252, 26
	s_nop 1
	v_add_u32_e32 v80, s0, v1
	s_movk_i32 s0, 0x800
	v_cmp_gt_i32_e32 vcc, s0, v80
	s_and_saveexec_b64 s[0:1], vcc
	s_cbranch_execz .LBB0_3311
	v_and_b32_e32 v0, 63, v210
	v_lshrrev_b32_e32 v1, 6, v210
	v_and_b32_e32 v1, 3, v1
	v_lshlrev_b32_e32 v1, 10, v1
	v_lshrrev_b32_e32 v2, 5, v0
	v_lshl_add_u32 v2, v2, 4, v1
	v_lshl_add_u32 v1, v0, 2, v1
	v_readlane_b32 s56, v252, 3
	v_readlane_b32 s57, v252, 4
	v_readlane_b32 s17, v252, 1
	v_readfirstlane_b32 s16, v80
	s_sub_u32 s56, s56, 0x180
	s_subb_u32 s57, s57, 0
	s_lshl_b32 s17, s17, 2
	s_load_dwordx2 s[2:3], s[56:57], 0x170
	s_load_dwordx2 s[44:45], s[56:57], 0x68
	s_load_dwordx2 s[46:47], s[56:57], 0xb8
	s_load_dwordx2 s[58:59], s[56:57], 0xc0
	s_load_dwordx2 s[50:51], s[56:57], 0xc8
	s_load_dwordx2 s[52:53], s[56:57], 0xd0
	s_load_dwordx2 s[54:55], s[56:57], 0xd8
	s_waitcnt lgkmcnt(0)
.Lrwp2b_item:
	s_lshr_b32 s19, s16, 10
	s_bfe_u32 s20, s16, 0x30007
	s_and_b32 s21, s16, 127
	s_lshl_b32 s22, s19, 14
	s_lshl_b32 s23, s21, 7
	s_add_u32 s22, s22, s23
	v_lshl_add_u32 v3, s20, 6, v0
	v_lshlrev_b32_e32 v4, 2, v3
	v_lshlrev_b32_e32 v208, 1, v3
	s_add_u32 s28, s44, 0x1800
	s_addc_u32 s29, s45, 0
	global_load_dword v9, v4, s[28:29]
	s_add_u32 s28, s44, 0x2000
	s_addc_u32 s29, s45, 0
	global_load_dword v10, v4, s[28:29]
	s_add_u32 s28, s46, 0x800
	s_addc_u32 s29, s47, 0
	global_load_dword v11, v4, s[28:29]
	s_add_u32 s28, s58, 0x800
	s_addc_u32 s29, s59, 0
	global_load_dword v12, v4, s[28:29]
	s_add_u32 s28, s50, 0x800
	s_addc_u32 s29, s51, 0
	global_load_dword v13, v4, s[28:29]
	s_add_u32 s28, s52, 0x800
	s_addc_u32 s29, s53, 0
	global_load_dword v14, v4, s[28:29]
	s_add_u32 s28, s54, 0x800
	s_addc_u32 s29, s55, 0
	global_load_dword v15, v4, s[28:29]
	s_add_u32 s4, s2, 0x17558000
	s_addc_u32 s5, s3, 0
	s_add_u32 s6, s2, 0x3558000
	s_addc_u32 s7, s3, 0
	s_add_u32 s8, s2, 0x11558000
	s_addc_u32 s9, s3, 0
	s_add_u32 s10, s2, 0x13558000
	s_addc_u32 s11, s3, 0
	s_add_u32 s12, s2, 0x15558000
	s_addc_u32 s13, s3, 0
	s_add_u32 s14, s2, 0xd558000
	s_addc_u32 s15, s3, 0
	s_lshl_b32 s23, s19, 3
	s_add_u32 s23, s23, s20
	s_lshl_b32 s23, s23, 7
	s_add_u32 s23, s23, s21
	s_sub_u32 s23, s23, 1
	s_lshr_b32 s25, s23, 18
	s_lshl_b32 s24, s23, 14
	s_add_u32 s24, s24, s2
	s_addc_u32 s25, s25, s3
	s_add_u32 s24, s24, 0x1d558000
	s_addc_u32 s25, s25, 0
	s_add_u32 s26, s24, 0x2000
	s_addc_u32 s27, s25, 0
	v_and_b32_e32 v5, 63, v210
	v_and_b32_e32 v6, 31, v5
	v_lshrrev_b32_e32 v7, 5, v5
	v_lshlrev_b32_e32 v26, 8, v6
	v_lshl_add_u32 v26, v7, 4, v26
	s_mul_i32 s28, s22, 0xc00
	s_lshl_b32 s29, s22, 10
	s_waitcnt vmcnt(0)
	v_add_u32_e32 v3, s28, v208
	v_add_u32_e32 v4, s29, v208
	v_add_u32_e32 v5, s29, v208
	v_mov_b32_e32 v6, 0
	v_mov_b32_e32 v7, 0
	s_cmp_eq_u32 s21, 0
	s_cbranch_scc1 .Lrwp2b_noprev
	global_load_ushort v6, v3, s[4:5] offset:-3072
	global_load_ushort v7, v3, s[4:5] offset:-2048

; template <bool PASS2>
; DI void rwkv_item(const Params& p, int l, int item, int lane, const bf16_t* rkv, const bf16_t* lo2, float* rwst) {
;     ...
;   auto derive = [&](const Raw& x, float rpp, float kpp) __attribute__((always_inline)) {
;     Der d;
;     const float rp = bf2f(x.rp), kp = bf2f(x.kp), a = bf2f(x.a);
;     d.rr = rp + (rpp - rp) * mu_r;
;     const float k = kp + (kpp - kp) * mu_k;
;     d.wdec = __expf(-bf2f(x.ew));
;     float kkv = k * kkw;
;     const float nrm = wave_sum(kkv * kkv);
;     ...
;   for (int t = 0; t < LCR; t++) {
;     Raw rawC = rawB;
;     if (t + 2 < LCR) rawC = load_raw(tok0 + t + 2);
;     Der nxt = cur;
;     if (t + 1 < LCR) nxt = derive(rawB, rpA, kpA);
;     const float rr = cur.rr, wdec = cur.wdec, kf = cur.kf, av = cur.av, bv = cur.bv, v = cur.v, gg = cur.gg;
;     float sa0 = 0.f, sa1 = 0.f, pa0 = 0.f, pa1 = 0.f;
; #pragma unroll
;     for (int j = 0; j < 64; j += 2) {
;       const float a0 = rl(av, j), a1 = rl(av, j + 1);
;       sa0 += S[j] * a0; sa1 += S[j + 1] * a1;
;       if (!PASS2) { pa0 += P[j] * a0; pa1 += P[j + 1] * a1; }
;     }
;     const float sa = sa0 + sa1, pa = pa0 + pa1;
;     float y0 = 0.f, y1 = 0.f;
; #pragma unroll
;     for (int j = 0; j < 64; j += 2) {
;       const float w0 = rl(wdec, j), b0 = rl(bv, j), k0 = rl(kf, j);
;       const float w1 = rl(wdec, j + 1), b1 = rl(bv, j + 1), k1 = rl(kf, j + 1);
;       S[j] = S[j] * w0 + sa * b0 + v * k0;
;       S[j + 1] = S[j + 1] * w1 + sa * b1 + v * k1;
;       if (!PASS2) {
;         P[j] = P[j] * w0 + pa * b0;
;         P[j + 1] = P[j + 1] * w1 + pa * b1;
;       } else {
;         y0 += S[j] * rl(rr, j); y1 += S[j + 1] * rl(rr, j + 1);
;       }
;     }
;     if (PASS2) {
;       const float y = y0 + y1;
;       float s1 = y, s2 = y * y, s3 = rr * kf * rkw;
; #pragma unroll
;       for (int off = 32; off >= 1; off >>= 1) {
;         const float t1 = __shfl_xor(s1, off), t2 = __shfl_xor(s2, off), t3 = __shfl_xor(s3, off);
;         s1 += t1; s2 += t2; s3 += t3;
;       }
;       const float mean = s1 * (1.f / 64.f);
;       const float var = fmaxf(s2 * (1.f / 64.f) - mean * mean, 0.f);
;       const float yn = (y - mean) * rsqrtf(var + 64e-5f) * gnw + gnb;
;       const float bs = s3;
;       p.yc[(tok0 + t) * 512 + ch] = f2bf((yn + bs * v) * gg);
;     }
;     rpA = bf2f(rawB.rp); kpA = bf2f(rawB.kp); rawB = rawC; cur = nxt;
.Lrwp2b_loop:
	s_nop 1
	v_permlane32_swap_b32 v18, v19
	s_nop 1
	v_mfma_f32_32x32x2_f32 v[64:79], v16, v18, v[64:79]
	v_mfma_f32_32x32x2_f32 v[80:95], v16, v19, v[80:95]
	v_mfma_f32_32x32x2_f32 v[96:111], v17, v18, v[96:111]
	v_mfma_f32_32x32x2_f32 v[112:127], v17, v19, v[112:127]
	global_load_ushort v160, v3, s[4:5]
	global_load_ushort v161, v3, s[4:5] offset:1024
	global_load_ushort v162, v4, s[6:7]
	global_load_ushort v163, v4, s[8:9]
	global_load_ushort v164, v4, s[10:11]
	global_load_ushort v165, v4, s[12:13]
	v_add_u32_e32 v3, 0xc00, v3
	v_add_u32_e32 v4, 0x400, v4
	s_waitcnt vmcnt(21)
	v_lshlrev_b32_e32 v27, 16, v167
	v_sub_f32_e32 v29, v7, v27
	v_fma_f32 v29, v29, v10, v27
	v_mov_b32_e32 v7, v27
	v_lshlrev_b32_e32 v26, 16, v166
	v_sub_f32_e32 v28, v6, v26
	v_fma_f32 v28, v28, v9, v26
	v_mov_b32_e32 v6, v26
	v_lshlrev_b32_e32 v30, 16, v169
	v_mul_f32_e32 v30, 0xbfb8aa3b, v30
	v_exp_f32_e32 v30, v30
	v_lshlrev_b32_e32 v31, 16, v170
	v_mul_f32_e32 v192, v29, v11
	v_add_f32_e32 v193, -1.0, v31
	v_fma_f32 v193, v193, v12, 1.0
	v_mul_f32_e32 v193, v29, v193
	v_mul_f32_e32 v194, v192, v192
	v_mul_f32_e32 v195, v28, v193
	v_mul_f32_e32 v195, v195, v13
	v_lshlrev_b32_e32 v23, 16, v171
	v_lshlrev_b32_e32 v21, 16, v168
	s_nop 1
	v_permlane32_swap_b32 v194, v195
	s_nop 0
	v_add_f32_e32 v194, v194, v195
	s_nop 1
	v_add_f32_dpp v194, v194, v194 quad_perm:[1,0,3,2] row_mask:0xf bank_mask:0xf
	s_nop 1
	v_add_f32_dpp v194, v194, v194 quad_perm:[2,3,0,1] row_mask:0xf bank_mask:0xf
	s_nop 1
	v_add_f32_dpp v194, v194, v194 row_half_mirror row_mask:0xf bank_mask:0xf
	s_nop 1
	v_add_f32_dpp v194, v194, v194 row_mirror row_mask:0xf bank_mask:0xf
	s_nop 1
	v_add_f32_dpp v194, v194, v194 row_bcast:15 row_mask:0xa bank_mask:0xf
	s_nop 1
	v_readlane_b32 s28, v194, 31
	v_readlane_b32 s31, v194, 63
	s_nop 1
	v_mov_b32_e32 v196, s28
	v_max_f32_e32 v196, 0x179abe15, v196
	v_rsq_f32_e32 v196, v196
	v_mov_b32_e32 v19, v21
	v_mul_f32_e32 v192, v192, v196
	v_mul_f32_e64 v24, -v192, v8
	v_mul_f32_e32 v197, v192, v31
	v_mul_f32_e32 v8, v8, v30
	v_rcp_f32_e32 v198, v8
	v_mul_f32_e32 v25, v8, v28
	v_mul_f32_e32 v16, v197, v198
	v_mul_f32_e32 v17, v193, v198
	s_nop 1
	v_permlane32_swap_b32 v16, v17
	ds_write_b32 v1, v24
	ds_write_b32 v1, v25 offset:512
	ds_read_b128 v[32:35], v2 offset:0
	ds_read_b128 v[128:131], v2 offset:256
	ds_read_b128 v[36:39], v2 offset:32
	ds_read_b128 v[132:135], v2 offset:288
	ds_read_b128 v[40:43], v2 offset:64
	ds_read_b128 v[136:139], v2 offset:320
	ds_read_b128 v[44:47], v2 offset:96
	ds_read_b128 v[140:143], v2 offset:352
	ds_read_b128 v[48:51], v2 offset:128
	ds_read_b128 v[144:147], v2 offset:384
	ds_read_b128 v[52:55], v2 offset:160
	ds_read_b128 v[148:151], v2 offset:416
	ds_read_b128 v[56:59], v2 offset:192
	ds_read_b128 v[152:155], v2 offset:448
	ds_read_b128 v[60:63], v2 offset:224
	ds_read_b128 v[156:159], v2 offset:480
	s_waitcnt lgkmcnt(14)
	v_pk_mul_f32 v[184:185], v[64:65], v[32:33]
	v_pk_mul_f32 v[188:189], v[64:65], v[128:129]
	v_pk_mul_f32 v[186:187], v[80:81], v[32:33]
	v_pk_mul_f32 v[190:191], v[80:81], v[128:129]
	v_pk_fma_f32 v[184:185], v[66:67], v[34:35], v[184:185]
	v_pk_fma_f32 v[188:189], v[66:67], v[130:131], v[188:189]
	v_pk_fma_f32 v[186:187], v[82:83], v[34:35], v[186:187]
	v_pk_fma_f32 v[190:191], v[82:83], v[130:131], v[190:191]
	s_waitcnt lgkmcnt(12)
	v_pk_fma_f32 v[184:185], v[68:69], v[36:37], v[184:185]
	v_pk_fma_f32 v[188:189], v[68:69], v[132:133], v[188:189]
	v_pk_fma_f32 v[186:187], v[84:85], v[36:37], v[186:187]
	v_pk_fma_f32 v[190:191], v[84:85], v[132:133], v[190:191]
	v_pk_fma_f32 v[184:185], v[70:71], v[38:39], v[184:185]
	v_pk_fma_f32 v[188:189], v[70:71], v[134:135], v[188:189]
	v_pk_fma_f32 v[186:187], v[86:87], v[38:39], v[186:187]
	v_pk_fma_f32 v[190:191], v[86:87], v[134:135], v[190:191]
	s_waitcnt lgkmcnt(10)
	v_pk_fma_f32 v[184:185], v[72:73], v[40:41], v[184:185]
	v_pk_fma_f32 v[188:189], v[72:73], v[136:137], v[188:189]
	v_pk_fma_f32 v[186:187], v[88:89], v[40:41], v[186:187]
	v_pk_fma_f32 v[190:191], v[88:89], v[136:137], v[190:191]
	v_pk_fma_f32 v[184:185], v[74:75], v[42:43], v[184:185]
	v_pk_fma_f32 v[188:189], v[74:75], v[138:139], v[188:189]
	v_pk_fma_f32 v[186:187], v[90:91], v[42:43], v[186:187]
	v_pk_fma_f32 v[190:191], v[90:91], v[138:139], v[190:191]
	s_waitcnt lgkmcnt(8)
	v_pk_fma_f32 v[184:185], v[76:77], v[44:45], v[184:185]
	v_pk_fma_f32 v[188:189], v[76:77], v[140:141], v[188:189]
	v_pk_fma_f32 v[186:187], v[92:93], v[44:45], v[186:187]
	v_pk_fma_f32 v[190:191], v[92:93], v[140:141], v[190:191]
	v_pk_fma_f32 v[184:185], v[78:79], v[46:47], v[184:185]
	v_pk_fma_f32 v[188:189], v[78:79], v[142:143], v[188:189]
	v_pk_fma_f32 v[186:187], v[94:95], v[46:47], v[186:187]
	v_pk_fma_f32 v[190:191], v[94:95], v[142:143], v[190:191]
	s_waitcnt lgkmcnt(6)
	v_pk_fma_f32 v[184:185], v[96:97], v[48:49], v[184:185]
	v_pk_fma_f32 v[188:189], v[96:97], v[144:145], v[188:189]
	v_pk_fma_f32 v[186:187], v[112:113], v[48:49], v[186:187]
	v_pk_fma_f32 v[190:191], v[112:113], v[144:145], v[190:191]
	v_pk_fma_f32 v[184:185], v[98:99], v[50:51], v[184:185]
	v_pk_fma_f32 v[188:189], v[98:99], v[146:147], v[188:189]
	v_pk_fma_f32 v[186:187], v[114:115], v[50:51], v[186:187]
	v_pk_fma_f32 v[190:191], v[114:115], v[146:147], v[190:191]
	s_waitcnt lgkmcnt(4)
	v_pk_fma_f32 v[184:185], v[100:101], v[52:53], v[184:185]
	v_pk_fma_f32 v[188:189], v[100:101], v[148:149], v[188:189]
	v_pk_fma_f32 v[186:187], v[116:117], v[52:53], v[186:187]
	v_pk_fma_f32 v[190:191], v[116:117], v[148:149], v[190:191]
	v_pk_fma_f32 v[184:185], v[102:103], v[54:55], v[184:185]
	v_pk_fma_f32 v[188:189], v[102:103], v[150:151], v[188:189]
	v_pk_fma_f32 v[186:187], v[118:119], v[54:55], v[186:187]
	v_pk_fma_f32 v[190:191], v[118:119], v[150:151], v[190:191]
	s_waitcnt lgkmcnt(2)
; DI bf16_t f2bf(float x) { unsigned u = __float_as_uint(x); u += 0x7fffu + ((u >> 16) & 1u); return (bf16_t)(u >> 16); }
; DI float bf2f(bf16_t b) { return __uint_as_float(((unsigned)b) << 16); }
; template <bool PASS2>
; DI void rwkv_item(const Params& p, int l, int item, int lane, const bf16_t* rkv, const bf16_t* lo2, float* rwst) {
;     ...
;   auto derive = [&](const Raw& x, float rpp, float kpp) __attribute__((always_inline)) {
;     Der d;
;     const float rp = bf2f(x.rp), kp = bf2f(x.kp), a = bf2f(x.a);
;     d.rr = rp + (rpp - rp) * mu_r;
;     const float k = kp + (kpp - kp) * mu_k;
;     d.wdec = __expf(-bf2f(x.ew));
;     float kkv = k * kkw;
;     const float nrm = wave_sum(kkv * kkv);
;     kkv *= rsqrtf(fmaxf(nrm, 1e-24f));
;     d.kf = k * (1.f + (a - 1.f) * kaw);
;     d.av = -kkv; d.bv = kkv * a;
;     d.v = bf2f(x.v); d.gg = bf2f(x.g);
;     return d;
;   };
;     ...
; #pragma unroll
;     for (int j = 0; j < 64; j += 2) {
;       const float a0 = rl(av, j), a1 = rl(av, j + 1);
;       sa0 += S[j] * a0; sa1 += S[j + 1] * a1;
;       if (!PASS2) { pa0 += P[j] * a0; pa1 += P[j + 1] * a1; }
;     }
;     const float sa = sa0 + sa1, pa = pa0 + pa1;
;     float y0 = 0.f, y1 = 0.f;
; #pragma unroll
;     for (int j = 0; j < 64; j += 2) {
;       const float w0 = rl(wdec, j), b0 = rl(bv, j), k0 = rl(kf, j);
;       const float w1 = rl(wdec, j + 1), b1 = rl(bv, j + 1), k1 = rl(kf, j + 1);
;       S[j] = S[j] * w0 + sa * b0 + v * k0;
;       S[j + 1] = S[j + 1] * w1 + sa * b1 + v * k1;
;       if (!PASS2) {
;         P[j] = P[j] * w0 + pa * b0;
;         P[j + 1] = P[j + 1] * w1 + pa * b1;
;       } else {
;         y0 += S[j] * rl(rr, j); y1 += S[j + 1] * rl(rr, j + 1);
;       }
;     }
;     if (PASS2) {
;       const float y = y0 + y1;
;       float s1 = y, s2 = y * y, s3 = rr * kf * rkw;
; #pragma unroll
;       for (int off = 32; off >= 1; off >>= 1) {
;         const float t1 = __shfl_xor(s1, off), t2 = __shfl_xor(s2, off), t3 = __shfl_xor(s3, off);
;         s1 += t1; s2 += t2; s3 += t3;
;       }
;       const float mean = s1 * (1.f / 64.f);
;       const float var = fmaxf(s2 * (1.f / 64.f) - mean * mean, 0.f);
;       const float yn = (y - mean) * rsqrtf(var + 64e-5f) * gnw + gnb;
;       const float bs = s3;
;       p.yc[(tok0 + t) * 512 + ch] = f2bf((yn + bs * v) * gg);
;     }
;     rpA = bf2f(rawB.rp); kpA = bf2f(rawB.kp); rawB = rawC; cur = nxt;
	v_pk_fma_f32 v[184:185], v[104:105], v[56:57], v[184:185]
	v_pk_fma_f32 v[188:189], v[104:105], v[152:153], v[188:189]
	v_pk_fma_f32 v[186:187], v[120:121], v[56:57], v[186:187]
	v_pk_fma_f32 v[190:191], v[120:121], v[152:153], v[190:191]
	v_pk_fma_f32 v[184:185], v[106:107], v[58:59], v[184:185]
	v_pk_fma_f32 v[188:189], v[106:107], v[154:155], v[188:189]
	v_pk_fma_f32 v[186:187], v[122:123], v[58:59], v[186:187]
	v_pk_fma_f32 v[190:191], v[122:123], v[154:155], v[190:191]
	s_waitcnt lgkmcnt(0)
	v_pk_fma_f32 v[184:185], v[108:109], v[60:61], v[184:185]
	v_pk_fma_f32 v[188:189], v[108:109], v[156:157], v[188:189]
	v_pk_fma_f32 v[186:187], v[124:125], v[60:61], v[186:187]
	v_pk_fma_f32 v[190:191], v[124:125], v[156:157], v[190:191]
	v_pk_fma_f32 v[184:185], v[110:111], v[62:63], v[184:185]
	v_pk_fma_f32 v[188:189], v[110:111], v[158:159], v[188:189]
	v_pk_fma_f32 v[186:187], v[126:127], v[62:63], v[186:187]
	v_pk_fma_f32 v[190:191], v[126:127], v[158:159], v[190:191]
	v_add_f32_e32 v18, v184, v185
	v_add_f32_e32 v200, v186, v187
	s_nop 1
	v_permlane32_swap_b32 v18, v200
	s_nop 0
	v_add_f32_e32 v18, v18, v200
	v_add_f32_e32 v201, v188, v189
	v_add_f32_e32 v202, v190, v191
	s_nop 1
	v_permlane32_swap_b32 v201, v202
	s_nop 0
	v_add_f32_e32 v201, v201, v202
	v_mul_f32_e32 v203, v201, v201
	v_mov_b32_e32 v204, v201
	s_nop 1
	v_permlane32_swap_b32 v204, v203
	s_nop 0
	v_add_f32_e32 v204, v204, v203
	s_nop 1
	v_add_f32_dpp v204, v204, v204 quad_perm:[1,0,3,2] row_mask:0xf bank_mask:0xf
	s_nop 1
	v_add_f32_dpp v204, v204, v204 quad_perm:[2,3,0,1] row_mask:0xf bank_mask:0xf
	s_nop 1
	v_add_f32_dpp v204, v204, v204 row_half_mirror row_mask:0xf bank_mask:0xf
	s_nop 1
	v_add_f32_dpp v204, v204, v204 row_mirror row_mask:0xf bank_mask:0xf
	s_nop 1
	v_add_f32_dpp v204, v204, v204 row_bcast:15 row_mask:0xa bank_mask:0xf
	s_nop 1
	v_readlane_b32 s34, v204, 31
	v_readlane_b32 s35, v204, 63
	s_nop 1
	v_mul_f32_e32 v205, s34, v207
	v_mul_f32_e32 v206, s35, v207
	v_fma_f32 v206, -v205, v205, v206
	v_max_f32_e32 v206, 0, v206
	v_add_f32_e32 v206, 0x3a27c5ac, v206
	v_rsq_f32_e32 v206, v206
	v_sub_f32_e32 v205, v201, v205
	v_mul_f32_e32 v205, v205, v206
	v_fma_f32 v205, v205, v14, v15
	v_fma_f32 v205, s30, v20, v205
	v_mul_f32_e32 v205, v205, v22
	v_bfe_u32 v206, v205, 16, 1
	v_add3_u32 v205, v205, v206, s36
	global_store_short_d16_hi v5, v205, s[14:15]
	v_add_u32_e32 v5, 0x400, v5
	s_nop 1
	v_permlane32_swap_b32 v18, v19
	s_nop 1
	v_mfma_f32_32x32x2_f32 v[64:79], v16, v18, v[64:79]
	v_mfma_f32_32x32x2_f32 v[80:95], v16, v19, v[80:95]
	v_mfma_f32_32x32x2_f32 v[96:111], v17, v18, v[96:111]
	v_mfma_f32_32x32x2_f32 v[112:127], v17, v19, v[112:127]
	global_load_ushort v166, v3, s[4:5]
	global_load_ushort v167, v3, s[4:5] offset:1024
	global_load_ushort v168, v4, s[6:7]
	global_load_ushort v169, v4, s[8:9]
	global_load_ushort v170, v4, s[10:11]
	global_load_ushort v171, v4, s[12:13]
	v_add_u32_e32 v3, 0xc00, v3
	v_add_u32_e32 v4, 0x400, v4
	s_waitcnt vmcnt(21)
	v_lshlrev_b32_e32 v27, 16, v173
	v_sub_f32_e32 v29, v7, v27
	v_fma_f32 v29, v29, v10, v27
	v_mov_b32_e32 v7, v27
	v_lshlrev_b32_e32 v26, 16, v172
	v_sub_f32_e32 v28, v6, v26
	v_fma_f32 v28, v28, v9, v26
	v_mov_b32_e32 v6, v26
	v_lshlrev_b32_e32 v30, 16, v175
	v_mul_f32_e32 v30, 0xbfb8aa3b, v30
	v_exp_f32_e32 v30, v30
	v_lshlrev_b32_e32 v31, 16, v176
	v_mul_f32_e32 v192, v29, v11
	v_add_f32_e32 v193, -1.0, v31
	v_fma_f32 v193, v193, v12, 1.0
	v_mul_f32_e32 v193, v29, v193
	v_mul_f32_e32 v194, v192, v192
	v_mul_f32_e32 v195, v28, v193
	v_mul_f32_e32 v195, v195, v13
	v_lshlrev_b32_e32 v22, 16, v177
	v_lshlrev_b32_e32 v20, 16, v174
	s_nop 1
	v_permlane32_swap_b32 v194, v195
	s_nop 0
	v_add_f32_e32 v194, v194, v195
	s_nop 1
	v_add_f32_dpp v194, v194, v194 quad_perm:[1,0,3,2] row_mask:0xf bank_mask:0xf
	s_nop 1
	v_add_f32_dpp v194, v194, v194 quad_perm:[2,3,0,1] row_mask:0xf bank_mask:0xf
	s_nop 1
	v_add_f32_dpp v194, v194, v194 row_half_mirror row_mask:0xf bank_mask:0xf
	s_nop 1
	v_add_f32_dpp v194, v194, v194 row_mirror row_mask:0xf bank_mask:0xf
	s_nop 1
	v_add_f32_dpp v194, v194, v194 row_bcast:15 row_mask:0xa bank_mask:0xf
	s_nop 1
	v_readlane_b32 s28, v194, 31
	v_readlane_b32 s30, v194, 63
	s_nop 1
	v_mov_b32_e32 v196, s28
	v_max_f32_e32 v196, 0x179abe15, v196
	v_rsq_f32_e32 v196, v196
	v_mov_b32_e32 v19, v20
	v_mul_f32_e32 v192, v192, v196
	v_mul_f32_e64 v24, -v192, v8
	v_mul_f32_e32 v197, v192, v31
	v_mul_f32_e32 v8, v8, v30
	v_rcp_f32_e32 v198, v8
	v_mul_f32_e32 v25, v8, v28
	v_mul_f32_e32 v16, v197, v198
	v_mul_f32_e32 v17, v193, v198
	s_nop 1
	v_permlane32_swap_b32 v16, v17
	ds_write_b32 v1, v24
	ds_write_b32 v1, v25 offset:256
	ds_read_b128 v[32:35], v2 offset:0
	ds_read_b128 v[128:131], v2 offset:512
	ds_read_b128 v[36:39], v2 offset:32
	ds_read_b128 v[132:135], v2 offset:544
	ds_read_b128 v[40:43], v2 offset:64
	ds_read_b128 v[136:139], v2 offset:576
	ds_read_b128 v[44:47], v2 offset:96
	ds_read_b128 v[140:143], v2 offset:608
	ds_read_b128 v[48:51], v2 offset:128
	ds_read_b128 v[144:147], v2 offset:640
	ds_read_b128 v[52:55], v2 offset:160
	ds_read_b128 v[148:151], v2 offset:672
	ds_read_b128 v[56:59], v2 offset:192
	ds_read_b128 v[152:155], v2 offset:704
	ds_read_b128 v[60:63], v2 offset:224
	ds_read_b128 v[156:159], v2 offset:736
	s_waitcnt lgkmcnt(14)
	v_pk_mul_f32 v[184:185], v[64:65], v[32:33]
	v_pk_mul_f32 v[188:189], v[64:65], v[128:129]
	v_pk_mul_f32 v[186:187], v[80:81], v[32:33]
	v_pk_mul_f32 v[190:191], v[80:81], v[128:129]
	v_pk_fma_f32 v[184:185], v[66:67], v[34:35], v[184:185]
	v_pk_fma_f32 v[188:189], v[66:67], v[130:131], v[188:189]
	v_pk_fma_f32 v[186:187], v[82:83], v[34:35], v[186:187]
	v_pk_fma_f32 v[190:191], v[82:83], v[130:131], v[190:191]
	s_waitcnt lgkmcnt(12)
; DI bf16_t f2bf(float x) { unsigned u = __float_as_uint(x); u += 0x7fffu + ((u >> 16) & 1u); return (bf16_t)(u >> 16); }
; DI float bf2f(bf16_t b) { return __uint_as_float(((unsigned)b) << 16); }
; DI float rl(float x, int l) { return __int_as_float(__builtin_amdgcn_readlane(__float_as_int(x), l)); }
; template <bool PASS2>
; DI void rwkv_item(const Params& p, int l, int item, int lane, const bf16_t* rkv, const bf16_t* lo2, float* rwst) {
;     ...
; #pragma unroll
;     for (int j = 0; j < 64; j += 2) {
;       const float a0 = rl(av, j), a1 = rl(av, j + 1);
;       sa0 += S[j] * a0; sa1 += S[j + 1] * a1;
;       if (!PASS2) { pa0 += P[j] * a0; pa1 += P[j + 1] * a1; }
;     }
;     const float sa = sa0 + sa1, pa = pa0 + pa1;
;     float y0 = 0.f, y1 = 0.f;
; #pragma unroll
;     for (int j = 0; j < 64; j += 2) {
;       const float w0 = rl(wdec, j), b0 = rl(bv, j), k0 = rl(kf, j);
;       const float w1 = rl(wdec, j + 1), b1 = rl(bv, j + 1), k1 = rl(kf, j + 1);
;       S[j] = S[j] * w0 + sa * b0 + v * k0;
;       S[j + 1] = S[j + 1] * w1 + sa * b1 + v * k1;
;       if (!PASS2) {
;         P[j] = P[j] * w0 + pa * b0;
;         P[j + 1] = P[j + 1] * w1 + pa * b1;
;       } else {
;         y0 += S[j] * rl(rr, j); y1 += S[j + 1] * rl(rr, j + 1);
;       }
;     }
;     if (PASS2) {
;       const float y = y0 + y1;
;       float s1 = y, s2 = y * y, s3 = rr * kf * rkw;
; #pragma unroll
;       for (int off = 32; off >= 1; off >>= 1) {
;         const float t1 = __shfl_xor(s1, off), t2 = __shfl_xor(s2, off), t3 = __shfl_xor(s3, off);
;         s1 += t1; s2 += t2; s3 += t3;
;       }
;       const float mean = s1 * (1.f / 64.f);
;       const float var = fmaxf(s2 * (1.f / 64.f) - mean * mean, 0.f);
;       const float yn = (y - mean) * rsqrtf(var + 64e-5f) * gnw + gnb;
;       const float bs = s3;
;       p.yc[(tok0 + t) * 512 + ch] = f2bf((yn + bs * v) * gg);
;     }
;     rpA = bf2f(rawB.rp); kpA = bf2f(rawB.kp); rawB = rawC; cur = nxt;
	v_pk_fma_f32 v[184:185], v[68:69], v[36:37], v[184:185]
	v_pk_fma_f32 v[188:189], v[68:69], v[132:133], v[188:189]
	v_pk_fma_f32 v[186:187], v[84:85], v[36:37], v[186:187]
	v_pk_fma_f32 v[190:191], v[84:85], v[132:133], v[190:191]
	v_pk_fma_f32 v[184:185], v[70:71], v[38:39], v[184:185]
	v_pk_fma_f32 v[188:189], v[70:71], v[134:135], v[188:189]
	v_pk_fma_f32 v[186:187], v[86:87], v[38:39], v[186:187]
	v_pk_fma_f32 v[190:191], v[86:87], v[134:135], v[190:191]
	s_waitcnt lgkmcnt(10)
	v_pk_fma_f32 v[184:185], v[72:73], v[40:41], v[184:185]
	v_pk_fma_f32 v[188:189], v[72:73], v[136:137], v[188:189]
	v_pk_fma_f32 v[186:187], v[88:89], v[40:41], v[186:187]
	v_pk_fma_f32 v[190:191], v[88:89], v[136:137], v[190:191]
	v_pk_fma_f32 v[184:185], v[74:75], v[42:43], v[184:185]
	v_pk_fma_f32 v[188:189], v[74:75], v[138:139], v[188:189]
	v_pk_fma_f32 v[186:187], v[90:91], v[42:43], v[186:187]
	v_pk_fma_f32 v[190:191], v[90:91], v[138:139], v[190:191]
	s_waitcnt lgkmcnt(8)
	v_pk_fma_f32 v[184:185], v[76:77], v[44:45], v[184:185]
	v_pk_fma_f32 v[188:189], v[76:77], v[140:141], v[188:189]
	v_pk_fma_f32 v[186:187], v[92:93], v[44:45], v[186:187]
	v_pk_fma_f32 v[190:191], v[92:93], v[140:141], v[190:191]
	v_pk_fma_f32 v[184:185], v[78:79], v[46:47], v[184:185]
	v_pk_fma_f32 v[188:189], v[78:79], v[142:143], v[188:189]
	v_pk_fma_f32 v[186:187], v[94:95], v[46:47], v[186:187]
	v_pk_fma_f32 v[190:191], v[94:95], v[142:143], v[190:191]
	s_waitcnt lgkmcnt(6)
	v_pk_fma_f32 v[184:185], v[96:97], v[48:49], v[184:185]
	v_pk_fma_f32 v[188:189], v[96:97], v[144:145], v[188:189]
	v_pk_fma_f32 v[186:187], v[112:113], v[48:49], v[186:187]
	v_pk_fma_f32 v[190:191], v[112:113], v[144:145], v[190:191]
	v_pk_fma_f32 v[184:185], v[98:99], v[50:51], v[184:185]
	v_pk_fma_f32 v[188:189], v[98:99], v[146:147], v[188:189]
	v_pk_fma_f32 v[186:187], v[114:115], v[50:51], v[186:187]
	v_pk_fma_f32 v[190:191], v[114:115], v[146:147], v[190:191]
	s_waitcnt lgkmcnt(4)
	v_pk_fma_f32 v[184:185], v[100:101], v[52:53], v[184:185]
	v_pk_fma_f32 v[188:189], v[100:101], v[148:149], v[188:189]
	v_pk_fma_f32 v[186:187], v[116:117], v[52:53], v[186:187]
	v_pk_fma_f32 v[190:191], v[116:117], v[148:149], v[190:191]
	v_pk_fma_f32 v[184:185], v[102:103], v[54:55], v[184:185]
	v_pk_fma_f32 v[188:189], v[102:103], v[150:151], v[188:189]
	v_pk_fma_f32 v[186:187], v[118:119], v[54:55], v[186:187]
	v_pk_fma_f32 v[190:191], v[118:119], v[150:151], v[190:191]
	s_waitcnt lgkmcnt(2)
	v_pk_fma_f32 v[184:185], v[104:105], v[56:57], v[184:185]
	v_pk_fma_f32 v[188:189], v[104:105], v[152:153], v[188:189]
	v_pk_fma_f32 v[186:187], v[120:121], v[56:57], v[186:187]
	v_pk_fma_f32 v[190:191], v[120:121], v[152:153], v[190:191]
	v_pk_fma_f32 v[184:185], v[106:107], v[58:59], v[184:185]
	v_pk_fma_f32 v[188:189], v[106:107], v[154:155], v[188:189]
	v_pk_fma_f32 v[186:187], v[122:123], v[58:59], v[186:187]
	v_pk_fma_f32 v[190:191], v[122:123], v[154:155], v[190:191]
	s_waitcnt lgkmcnt(0)
	v_pk_fma_f32 v[184:185], v[108:109], v[60:61], v[184:185]
	v_pk_fma_f32 v[188:189], v[108:109], v[156:157], v[188:189]
	v_pk_fma_f32 v[186:187], v[124:125], v[60:61], v[186:187]
	v_pk_fma_f32 v[190:191], v[124:125], v[156:157], v[190:191]
	v_pk_fma_f32 v[184:185], v[110:111], v[62:63], v[184:185]
	v_pk_fma_f32 v[188:189], v[110:111], v[158:159], v[188:189]
	v_pk_fma_f32 v[186:187], v[126:127], v[62:63], v[186:187]
	v_pk_fma_f32 v[190:191], v[126:127], v[158:159], v[190:191]
	v_add_f32_e32 v18, v184, v185
	v_add_f32_e32 v200, v186, v187
	s_nop 1
	v_permlane32_swap_b32 v18, v200
	s_nop 0
	v_add_f32_e32 v18, v18, v200
	v_add_f32_e32 v201, v188, v189
	v_add_f32_e32 v202, v190, v191
	s_nop 1
	v_permlane32_swap_b32 v201, v202
	s_nop 0
	v_add_f32_e32 v201, v201, v202
	v_mul_f32_e32 v203, v201, v201
	v_mov_b32_e32 v204, v201
	s_nop 1
	v_permlane32_swap_b32 v204, v203
	s_nop 0
	v_add_f32_e32 v204, v204, v203
	s_nop 1
	v_add_f32_dpp v204, v204, v204 quad_perm:[1,0,3,2] row_mask:0xf bank_mask:0xf
	s_nop 1
	v_add_f32_dpp v204, v204, v204 quad_perm:[2,3,0,1] row_mask:0xf bank_mask:0xf
	s_nop 1
	v_add_f32_dpp v204, v204, v204 row_half_mirror row_mask:0xf bank_mask:0xf
	s_nop 1
	v_add_f32_dpp v204, v204, v204 row_mirror row_mask:0xf bank_mask:0xf
	s_nop 1
	v_add_f32_dpp v204, v204, v204 row_bcast:15 row_mask:0xa bank_mask:0xf
	s_nop 1
	v_readlane_b32 s34, v204, 31
	v_readlane_b32 s35, v204, 63
	s_nop 1
	v_mul_f32_e32 v205, s34, v207
	v_mul_f32_e32 v206, s35, v207
	v_fma_f32 v206, -v205, v205, v206
	v_max_f32_e32 v206, 0, v206
	v_add_f32_e32 v206, 0x3a27c5ac, v206
	v_rsq_f32_e32 v206, v206
	v_sub_f32_e32 v205, v201, v205
	v_mul_f32_e32 v205, v205, v206
	v_fma_f32 v205, v205, v14, v15
	v_fma_f32 v205, s31, v21, v205
	v_mul_f32_e32 v205, v205, v23
	v_bfe_u32 v206, v205, 16, 1
	v_add3_u32 v205, v205, v206, s36
	global_store_short_d16_hi v5, v205, s[14:15]
	v_add_u32_e32 v5, 0x400, v5
	s_nop 1
	v_permlane32_swap_b32 v18, v19
	s_nop 1
	v_mfma_f32_32x32x2_f32 v[64:79], v16, v18, v[64:79]
	v_mfma_f32_32x32x2_f32 v[80:95], v16, v19, v[80:95]
	v_mfma_f32_32x32x2_f32 v[96:111], v17, v18, v[96:111]
	v_mfma_f32_32x32x2_f32 v[112:127], v17, v19, v[112:127]
	global_load_ushort v172, v3, s[4:5]
	global_load_ushort v173, v3, s[4:5] offset:1024
	global_load_ushort v174, v4, s[6:7]
	global_load_ushort v175, v4, s[8:9]
	global_load_ushort v176, v4, s[10:11]
	global_load_ushort v177, v4, s[12:13]
	v_add_u32_e32 v3, 0xc00, v3
	v_add_u32_e32 v4, 0x400, v4
	s_waitcnt vmcnt(21)
; DI float bf2f(bf16_t b) { return __uint_as_float(((unsigned)b) << 16); }
; DI float rl(float x, int l) { return __int_as_float(__builtin_amdgcn_readlane(__float_as_int(x), l)); }
; template <bool PASS2>
; DI void rwkv_item(const Params& p, int l, int item, int lane, const bf16_t* rkv, const bf16_t* lo2, float* rwst) {
;     ...
;   auto derive = [&](const Raw& x, float rpp, float kpp) __attribute__((always_inline)) {
;     Der d;
;     const float rp = bf2f(x.rp), kp = bf2f(x.kp), a = bf2f(x.a);
;     d.rr = rp + (rpp - rp) * mu_r;
;     const float k = kp + (kpp - kp) * mu_k;
;     d.wdec = __expf(-bf2f(x.ew));
;     float kkv = k * kkw;
;     const float nrm = wave_sum(kkv * kkv);
;     kkv *= rsqrtf(fmaxf(nrm, 1e-24f));
;     d.kf = k * (1.f + (a - 1.f) * kaw);
;     d.av = -kkv; d.bv = kkv * a;
;     d.v = bf2f(x.v); d.gg = bf2f(x.g);
;     return d;
;   };
;     ...
; #pragma unroll
;     for (int j = 0; j < 64; j += 2) {
;       const float a0 = rl(av, j), a1 = rl(av, j + 1);
;       sa0 += S[j] * a0; sa1 += S[j + 1] * a1;
;       if (!PASS2) { pa0 += P[j] * a0; pa1 += P[j + 1] * a1; }
;     }
;     const float sa = sa0 + sa1, pa = pa0 + pa1;
	v_lshlrev_b32_e32 v27, 16, v179
	v_sub_f32_e32 v29, v7, v27
	v_fma_f32 v29, v29, v10, v27
	v_mov_b32_e32 v7, v27
	v_lshlrev_b32_e32 v26, 16, v178
	v_sub_f32_e32 v28, v6, v26
	v_fma_f32 v28, v28, v9, v26
	v_mov_b32_e32 v6, v26
	v_lshlrev_b32_e32 v30, 16, v181
	v_mul_f32_e32 v30, 0xbfb8aa3b, v30
	v_exp_f32_e32 v30, v30
	v_lshlrev_b32_e32 v31, 16, v182
	v_mul_f32_e32 v192, v29, v11
	v_add_f32_e32 v193, -1.0, v31
	v_fma_f32 v193, v193, v12, 1.0
	v_mul_f32_e32 v193, v29, v193
	v_mul_f32_e32 v194, v192, v192
	v_mul_f32_e32 v195, v28, v193
	v_mul_f32_e32 v195, v195, v13
	v_lshlrev_b32_e32 v23, 16, v183
	v_lshlrev_b32_e32 v21, 16, v180
	s_nop 1
	v_permlane32_swap_b32 v194, v195
	s_nop 0
	v_add_f32_e32 v194, v194, v195
	s_nop 1
	v_add_f32_dpp v194, v194, v194 quad_perm:[1,0,3,2] row_mask:0xf bank_mask:0xf
	s_nop 1
	v_add_f32_dpp v194, v194, v194 quad_perm:[2,3,0,1] row_mask:0xf bank_mask:0xf
	s_nop 1
	v_add_f32_dpp v194, v194, v194 row_half_mirror row_mask:0xf bank_mask:0xf
	s_nop 1
	v_add_f32_dpp v194, v194, v194 row_mirror row_mask:0xf bank_mask:0xf
	s_nop 1
	v_add_f32_dpp v194, v194, v194 row_bcast:15 row_mask:0xa bank_mask:0xf
	s_nop 1
	v_readlane_b32 s28, v194, 31
	v_readlane_b32 s31, v194, 63
	s_nop 1
	v_mov_b32_e32 v196, s28
	v_max_f32_e32 v196, 0x179abe15, v196
	v_rsq_f32_e32 v196, v196
	v_mov_b32_e32 v19, v21
	v_mul_f32_e32 v192, v192, v196
	v_mul_f32_e64 v24, -v192, v8
	v_mul_f32_e32 v197, v192, v31
	v_mul_f32_e32 v8, v8, v30
	v_rcp_f32_e32 v198, v8
	v_mul_f32_e32 v25, v8, v28
	v_mul_f32_e32 v16, v197, v198
	v_mul_f32_e32 v17, v193, v198
	s_nop 1
	v_permlane32_swap_b32 v16, v17
	ds_write_b32 v1, v24
	ds_write_b32 v1, v25 offset:512
	ds_read_b128 v[32:35], v2 offset:0
	ds_read_b128 v[128:131], v2 offset:256
	ds_read_b128 v[36:39], v2 offset:32
	ds_read_b128 v[132:135], v2 offset:288
	ds_read_b128 v[40:43], v2 offset:64
	ds_read_b128 v[136:139], v2 offset:320
	ds_read_b128 v[44:47], v2 offset:96
	ds_read_b128 v[140:143], v2 offset:352
	ds_read_b128 v[48:51], v2 offset:128
	ds_read_b128 v[144:147], v2 offset:384
	ds_read_b128 v[52:55], v2 offset:160
	ds_read_b128 v[148:151], v2 offset:416
	ds_read_b128 v[56:59], v2 offset:192
	ds_read_b128 v[152:155], v2 offset:448
	ds_read_b128 v[60:63], v2 offset:224
	ds_read_b128 v[156:159], v2 offset:480
	s_waitcnt lgkmcnt(14)
	v_pk_mul_f32 v[184:185], v[64:65], v[32:33]
	v_pk_mul_f32 v[188:189], v[64:65], v[128:129]
	v_pk_mul_f32 v[186:187], v[80:81], v[32:33]
	v_pk_mul_f32 v[190:191], v[80:81], v[128:129]
	v_pk_fma_f32 v[184:185], v[66:67], v[34:35], v[184:185]
	v_pk_fma_f32 v[188:189], v[66:67], v[130:131], v[188:189]
	v_pk_fma_f32 v[186:187], v[82:83], v[34:35], v[186:187]
	v_pk_fma_f32 v[190:191], v[82:83], v[130:131], v[190:191]
	s_waitcnt lgkmcnt(12)
	v_pk_fma_f32 v[184:185], v[68:69], v[36:37], v[184:185]
	v_pk_fma_f32 v[188:189], v[68:69], v[132:133], v[188:189]
	v_pk_fma_f32 v[186:187], v[84:85], v[36:37], v[186:187]
	v_pk_fma_f32 v[190:191], v[84:85], v[132:133], v[190:191]
	v_pk_fma_f32 v[184:185], v[70:71], v[38:39], v[184:185]
	v_pk_fma_f32 v[188:189], v[70:71], v[134:135], v[188:189]
	v_pk_fma_f32 v[186:187], v[86:87], v[38:39], v[186:187]
	v_pk_fma_f32 v[190:191], v[86:87], v[134:135], v[190:191]
	s_waitcnt lgkmcnt(10)
	v_pk_fma_f32 v[184:185], v[72:73], v[40:41], v[184:185]
	v_pk_fma_f32 v[188:189], v[72:73], v[136:137], v[188:189]
	v_pk_fma_f32 v[186:187], v[88:89], v[40:41], v[186:187]
	v_pk_fma_f32 v[190:191], v[88:89], v[136:137], v[190:191]
	v_pk_fma_f32 v[184:185], v[74:75], v[42:43], v[184:185]
	v_pk_fma_f32 v[188:189], v[74:75], v[138:139], v[188:189]
	v_pk_fma_f32 v[186:187], v[90:91], v[42:43], v[186:187]
	v_pk_fma_f32 v[190:191], v[90:91], v[138:139], v[190:191]
	s_waitcnt lgkmcnt(8)
	v_pk_fma_f32 v[184:185], v[76:77], v[44:45], v[184:185]
	v_pk_fma_f32 v[188:189], v[76:77], v[140:141], v[188:189]
	v_pk_fma_f32 v[186:187], v[92:93], v[44:45], v[186:187]
	v_pk_fma_f32 v[190:191], v[92:93], v[140:141], v[190:191]
	v_pk_fma_f32 v[184:185], v[78:79], v[46:47], v[184:185]
	v_pk_fma_f32 v[188:189], v[78:79], v[142:143], v[188:189]
	v_pk_fma_f32 v[186:187], v[94:95], v[46:47], v[186:187]
	v_pk_fma_f32 v[190:191], v[94:95], v[142:143], v[190:191]
	s_waitcnt lgkmcnt(6)
	v_pk_fma_f32 v[184:185], v[96:97], v[48:49], v[184:185]
	v_pk_fma_f32 v[188:189], v[96:97], v[144:145], v[188:189]
	v_pk_fma_f32 v[186:187], v[112:113], v[48:49], v[186:187]
	v_pk_fma_f32 v[190:191], v[112:113], v[144:145], v[190:191]
	v_pk_fma_f32 v[184:185], v[98:99], v[50:51], v[184:185]
	v_pk_fma_f32 v[188:189], v[98:99], v[146:147], v[188:189]
	v_pk_fma_f32 v[186:187], v[114:115], v[50:51], v[186:187]
	v_pk_fma_f32 v[190:191], v[114:115], v[146:147], v[190:191]
	s_waitcnt lgkmcnt(4)
	v_pk_fma_f32 v[184:185], v[100:101], v[52:53], v[184:185]
	v_pk_fma_f32 v[188:189], v[100:101], v[148:149], v[188:189]
	v_pk_fma_f32 v[186:187], v[116:117], v[52:53], v[186:187]
	v_pk_fma_f32 v[190:191], v[116:117], v[148:149], v[190:191]
	v_pk_fma_f32 v[184:185], v[102:103], v[54:55], v[184:185]
	v_pk_fma_f32 v[188:189], v[102:103], v[150:151], v[188:189]
	v_pk_fma_f32 v[186:187], v[118:119], v[54:55], v[186:187]
	v_pk_fma_f32 v[190:191], v[118:119], v[150:151], v[190:191]
	s_waitcnt lgkmcnt(2)
	v_pk_fma_f32 v[184:185], v[104:105], v[56:57], v[184:185]
	v_pk_fma_f32 v[188:189], v[104:105], v[152:153], v[188:189]
	v_pk_fma_f32 v[186:187], v[120:121], v[56:57], v[186:187]
	v_pk_fma_f32 v[190:191], v[120:121], v[152:153], v[190:191]
	v_pk_fma_f32 v[184:185], v[106:107], v[58:59], v[184:185]
	v_pk_fma_f32 v[188:189], v[106:107], v[154:155], v[188:189]
	v_pk_fma_f32 v[186:187], v[122:123], v[58:59], v[186:187]
	v_pk_fma_f32 v[190:191], v[122:123], v[154:155], v[190:191]
	s_waitcnt lgkmcnt(0)
; DI bf16_t f2bf(float x) { unsigned u = __float_as_uint(x); u += 0x7fffu + ((u >> 16) & 1u); return (bf16_t)(u >> 16); }
; DI float bf2f(bf16_t b) { return __uint_as_float(((unsigned)b) << 16); }
; template <bool PASS2>
; DI void rwkv_item(const Params& p, int l, int item, int lane, const bf16_t* rkv, const bf16_t* lo2, float* rwst) {
;     ...
;   auto derive = [&](const Raw& x, float rpp, float kpp) __attribute__((always_inline)) {
;     Der d;
;     const float rp = bf2f(x.rp), kp = bf2f(x.kp), a = bf2f(x.a);
;     d.rr = rp + (rpp - rp) * mu_r;
;     const float k = kp + (kpp - kp) * mu_k;
;     d.wdec = __expf(-bf2f(x.ew));
;     float kkv = k * kkw;
;     const float nrm = wave_sum(kkv * kkv);
;     kkv *= rsqrtf(fmaxf(nrm, 1e-24f));
;     d.kf = k * (1.f + (a - 1.f) * kaw);
;     d.av = -kkv; d.bv = kkv * a;
;     d.v = bf2f(x.v); d.gg = bf2f(x.g);
;     return d;
;   };
;     ...
; #pragma unroll
;     for (int j = 0; j < 64; j += 2) {
;       const float a0 = rl(av, j), a1 = rl(av, j + 1);
;       sa0 += S[j] * a0; sa1 += S[j + 1] * a1;
;       if (!PASS2) { pa0 += P[j] * a0; pa1 += P[j + 1] * a1; }
;     }
;     const float sa = sa0 + sa1, pa = pa0 + pa1;
;     float y0 = 0.f, y1 = 0.f;
; #pragma unroll
;     for (int j = 0; j < 64; j += 2) {
;       const float w0 = rl(wdec, j), b0 = rl(bv, j), k0 = rl(kf, j);
;       const float w1 = rl(wdec, j + 1), b1 = rl(bv, j + 1), k1 = rl(kf, j + 1);
;       S[j] = S[j] * w0 + sa * b0 + v * k0;
;       S[j + 1] = S[j + 1] * w1 + sa * b1 + v * k1;
;       if (!PASS2) {
;         P[j] = P[j] * w0 + pa * b0;
;         P[j + 1] = P[j + 1] * w1 + pa * b1;
;       } else {
;         y0 += S[j] * rl(rr, j); y1 += S[j + 1] * rl(rr, j + 1);
;       }
;     }
;     if (PASS2) {
;       const float y = y0 + y1;
;       float s1 = y, s2 = y * y, s3 = rr * kf * rkw;
; #pragma unroll
;       for (int off = 32; off >= 1; off >>= 1) {
;         const float t1 = __shfl_xor(s1, off), t2 = __shfl_xor(s2, off), t3 = __shfl_xor(s3, off);
;         s1 += t1; s2 += t2; s3 += t3;
;       }
;       const float mean = s1 * (1.f / 64.f);
;       const float var = fmaxf(s2 * (1.f / 64.f) - mean * mean, 0.f);
;       const float yn = (y - mean) * rsqrtf(var + 64e-5f) * gnw + gnb;
;       const float bs = s3;
;       p.yc[(tok0 + t) * 512 + ch] = f2bf((yn + bs * v) * gg);
;     }
;     rpA = bf2f(rawB.rp); kpA = bf2f(rawB.kp); rawB = rawC; cur = nxt;
	v_pk_fma_f32 v[184:185], v[108:109], v[60:61], v[184:185]
	v_pk_fma_f32 v[188:189], v[108:109], v[156:157], v[188:189]
	v_pk_fma_f32 v[186:187], v[124:125], v[60:61], v[186:187]
	v_pk_fma_f32 v[190:191], v[124:125], v[156:157], v[190:191]
	v_pk_fma_f32 v[184:185], v[110:111], v[62:63], v[184:185]
	v_pk_fma_f32 v[188:189], v[110:111], v[158:159], v[188:189]
	v_pk_fma_f32 v[186:187], v[126:127], v[62:63], v[186:187]
	v_pk_fma_f32 v[190:191], v[126:127], v[158:159], v[190:191]
	v_add_f32_e32 v18, v184, v185
	v_add_f32_e32 v200, v186, v187
	s_nop 1
	v_permlane32_swap_b32 v18, v200
	s_nop 0
	v_add_f32_e32 v18, v18, v200
	v_add_f32_e32 v201, v188, v189
	v_add_f32_e32 v202, v190, v191
	s_nop 1
	v_permlane32_swap_b32 v201, v202
	s_nop 0
	v_add_f32_e32 v201, v201, v202
	v_mul_f32_e32 v203, v201, v201
	v_mov_b32_e32 v204, v201
	s_nop 1
	v_permlane32_swap_b32 v204, v203
	s_nop 0
	v_add_f32_e32 v204, v204, v203
	s_nop 1
	v_add_f32_dpp v204, v204, v204 quad_perm:[1,0,3,2] row_mask:0xf bank_mask:0xf
	s_nop 1
	v_add_f32_dpp v204, v204, v204 quad_perm:[2,3,0,1] row_mask:0xf bank_mask:0xf
	s_nop 1
	v_add_f32_dpp v204, v204, v204 row_half_mirror row_mask:0xf bank_mask:0xf
	s_nop 1
	v_add_f32_dpp v204, v204, v204 row_mirror row_mask:0xf bank_mask:0xf
	s_nop 1
	v_add_f32_dpp v204, v204, v204 row_bcast:15 row_mask:0xa bank_mask:0xf
	s_nop 1
	v_readlane_b32 s34, v204, 31
	v_readlane_b32 s35, v204, 63
	s_nop 1
	v_mul_f32_e32 v205, s34, v207
	v_mul_f32_e32 v206, s35, v207
	v_fma_f32 v206, -v205, v205, v206
	v_max_f32_e32 v206, 0, v206
	v_add_f32_e32 v206, 0x3a27c5ac, v206
	v_rsq_f32_e32 v206, v206
	v_sub_f32_e32 v205, v201, v205
	v_mul_f32_e32 v205, v205, v206
	v_fma_f32 v205, v205, v14, v15
	v_fma_f32 v205, s30, v20, v205
	v_mul_f32_e32 v205, v205, v22
	v_bfe_u32 v206, v205, 16, 1
	v_add3_u32 v205, v205, v206, s36
	global_store_short_d16_hi v5, v205, s[14:15]
	v_add_u32_e32 v5, 0x400, v5
	s_nop 1
	v_permlane32_swap_b32 v18, v19
	s_nop 1
	v_mfma_f32_32x32x2_f32 v[64:79], v16, v18, v[64:79]
	v_mfma_f32_32x32x2_f32 v[80:95], v16, v19, v[80:95]
	v_mfma_f32_32x32x2_f32 v[96:111], v17, v18, v[96:111]
	v_mfma_f32_32x32x2_f32 v[112:127], v17, v19, v[112:127]
	global_load_ushort v178, v3, s[4:5]
	global_load_ushort v179, v3, s[4:5] offset:1024
	global_load_ushort v180, v4, s[6:7]
	global_load_ushort v181, v4, s[8:9]
	global_load_ushort v182, v4, s[10:11]
	global_load_ushort v183, v4, s[12:13]
	v_add_u32_e32 v3, 0xc00, v3
	v_add_u32_e32 v4, 0x400, v4
	s_waitcnt vmcnt(21)
	v_lshlrev_b32_e32 v27, 16, v161
	v_sub_f32_e32 v29, v7, v27
	v_fma_f32 v29, v29, v10, v27
	v_mov_b32_e32 v7, v27
	v_lshlrev_b32_e32 v26, 16, v160
	v_sub_f32_e32 v28, v6, v26
	v_fma_f32 v28, v28, v9, v26
	v_mov_b32_e32 v6, v26
	v_lshlrev_b32_e32 v30, 16, v163
	v_mul_f32_e32 v30, 0xbfb8aa3b, v30
	v_exp_f32_e32 v30, v30
	v_lshlrev_b32_e32 v31, 16, v164
	v_mul_f32_e32 v192, v29, v11
	v_add_f32_e32 v193, -1.0, v31
	v_fma_f32 v193, v193, v12, 1.0
	v_mul_f32_e32 v193, v29, v193
	v_mul_f32_e32 v194, v192, v192
	v_mul_f32_e32 v195, v28, v193
	v_mul_f32_e32 v195, v195, v13
	v_lshlrev_b32_e32 v22, 16, v165
	v_lshlrev_b32_e32 v20, 16, v162
	s_nop 1
	v_permlane32_swap_b32 v194, v195
	s_nop 0
	v_add_f32_e32 v194, v194, v195
	s_nop 1
	v_add_f32_dpp v194, v194, v194 quad_perm:[1,0,3,2] row_mask:0xf bank_mask:0xf
	s_nop 1
	v_add_f32_dpp v194, v194, v194 quad_perm:[2,3,0,1] row_mask:0xf bank_mask:0xf
	s_nop 1
	v_add_f32_dpp v194, v194, v194 row_half_mirror row_mask:0xf bank_mask:0xf
	s_nop 1
	v_add_f32_dpp v194, v194, v194 row_mirror row_mask:0xf bank_mask:0xf
	s_nop 1
	v_add_f32_dpp v194, v194, v194 row_bcast:15 row_mask:0xa bank_mask:0xf
	s_nop 1
	v_readlane_b32 s28, v194, 31
	v_readlane_b32 s30, v194, 63
	s_nop 1
	v_mov_b32_e32 v196, s28
	v_max_f32_e32 v196, 0x179abe15, v196
	v_rsq_f32_e32 v196, v196
	v_mov_b32_e32 v19, v20
	v_mul_f32_e32 v192, v192, v196
	v_mul_f32_e64 v24, -v192, v8
	v_mul_f32_e32 v197, v192, v31
	v_mul_f32_e32 v8, v8, v30
	v_rcp_f32_e32 v198, v8
	v_mul_f32_e32 v25, v8, v28
	v_mul_f32_e32 v16, v197, v198
	v_mul_f32_e32 v17, v193, v198
	s_nop 1
	v_permlane32_swap_b32 v16, v17
	ds_write_b32 v1, v24
	ds_write_b32 v1, v25 offset:256
	ds_read_b128 v[32:35], v2 offset:0
	ds_read_b128 v[128:131], v2 offset:512
	ds_read_b128 v[36:39], v2 offset:32
	ds_read_b128 v[132:135], v2 offset:544
	ds_read_b128 v[40:43], v2 offset:64
	ds_read_b128 v[136:139], v2 offset:576
	ds_read_b128 v[44:47], v2 offset:96
	ds_read_b128 v[140:143], v2 offset:608
	ds_read_b128 v[48:51], v2 offset:128
	ds_read_b128 v[144:147], v2 offset:640
	ds_read_b128 v[52:55], v2 offset:160
	ds_read_b128 v[148:151], v2 offset:672
	ds_read_b128 v[56:59], v2 offset:192
	ds_read_b128 v[152:155], v2 offset:704
	ds_read_b128 v[60:63], v2 offset:224
	ds_read_b128 v[156:159], v2 offset:736
	s_waitcnt lgkmcnt(14)
	v_pk_mul_f32 v[184:185], v[64:65], v[32:33]
	v_pk_mul_f32 v[188:189], v[64:65], v[128:129]
	v_pk_mul_f32 v[186:187], v[80:81], v[32:33]
	v_pk_mul_f32 v[190:191], v[80:81], v[128:129]
	v_pk_fma_f32 v[184:185], v[66:67], v[34:35], v[184:185]
	v_pk_fma_f32 v[188:189], v[66:67], v[130:131], v[188:189]
	v_pk_fma_f32 v[186:187], v[82:83], v[34:35], v[186:187]
	v_pk_fma_f32 v[190:191], v[82:83], v[130:131], v[190:191]
	s_waitcnt lgkmcnt(12)
; DI bf16_t f2bf(float x) { unsigned u = __float_as_uint(x); u += 0x7fffu + ((u >> 16) & 1u); return (bf16_t)(u >> 16); }
; DI float bf2f(bf16_t b) { return __uint_as_float(((unsigned)b) << 16); }
; DI float rl(float x, int l) { return __int_as_float(__builtin_amdgcn_readlane(__float_as_int(x), l)); }
; template <bool PASS2>
; DI void rwkv_item(const Params& p, int l, int item, int lane, const bf16_t* rkv, const bf16_t* lo2, float* rwst) {
;     ...
; #pragma unroll
;     for (int j = 0; j < 64; j += 2) {
;       const float a0 = rl(av, j), a1 = rl(av, j + 1);
;       sa0 += S[j] * a0; sa1 += S[j + 1] * a1;
;       if (!PASS2) { pa0 += P[j] * a0; pa1 += P[j + 1] * a1; }
;     }
;     const float sa = sa0 + sa1, pa = pa0 + pa1;
;     float y0 = 0.f, y1 = 0.f;
; #pragma unroll
;     for (int j = 0; j < 64; j += 2) {
;       const float w0 = rl(wdec, j), b0 = rl(bv, j), k0 = rl(kf, j);
;       const float w1 = rl(wdec, j + 1), b1 = rl(bv, j + 1), k1 = rl(kf, j + 1);
;       S[j] = S[j] * w0 + sa * b0 + v * k0;
;       S[j + 1] = S[j + 1] * w1 + sa * b1 + v * k1;
;       if (!PASS2) {
;         P[j] = P[j] * w0 + pa * b0;
;         P[j + 1] = P[j + 1] * w1 + pa * b1;
;       } else {
;         y0 += S[j] * rl(rr, j); y1 += S[j + 1] * rl(rr, j + 1);
;       }
;     }
;     if (PASS2) {
;       const float y = y0 + y1;
;       float s1 = y, s2 = y * y, s3 = rr * kf * rkw;
; #pragma unroll
;       for (int off = 32; off >= 1; off >>= 1) {
;         const float t1 = __shfl_xor(s1, off), t2 = __shfl_xor(s2, off), t3 = __shfl_xor(s3, off);
;         s1 += t1; s2 += t2; s3 += t3;
;       }
;       const float mean = s1 * (1.f / 64.f);
;       const float var = fmaxf(s2 * (1.f / 64.f) - mean * mean, 0.f);
;       const float yn = (y - mean) * rsqrtf(var + 64e-5f) * gnw + gnb;
;       const float bs = s3;
;       p.yc[(tok0 + t) * 512 + ch] = f2bf((yn + bs * v) * gg);
;     }
;     rpA = bf2f(rawB.rp); kpA = bf2f(rawB.kp); rawB = rawC; cur = nxt;
	v_pk_fma_f32 v[184:185], v[68:69], v[36:37], v[184:185]
	v_pk_fma_f32 v[188:189], v[68:69], v[132:133], v[188:189]
	v_pk_fma_f32 v[186:187], v[84:85], v[36:37], v[186:187]
	v_pk_fma_f32 v[190:191], v[84:85], v[132:133], v[190:191]
	v_pk_fma_f32 v[184:185], v[70:71], v[38:39], v[184:185]
	v_pk_fma_f32 v[188:189], v[70:71], v[134:135], v[188:189]
	v_pk_fma_f32 v[186:187], v[86:87], v[38:39], v[186:187]
	v_pk_fma_f32 v[190:191], v[86:87], v[134:135], v[190:191]
	s_waitcnt lgkmcnt(10)
	v_pk_fma_f32 v[184:185], v[72:73], v[40:41], v[184:185]
	v_pk_fma_f32 v[188:189], v[72:73], v[136:137], v[188:189]
	v_pk_fma_f32 v[186:187], v[88:89], v[40:41], v[186:187]
	v_pk_fma_f32 v[190:191], v[88:89], v[136:137], v[190:191]
	v_pk_fma_f32 v[184:185], v[74:75], v[42:43], v[184:185]
	v_pk_fma_f32 v[188:189], v[74:75], v[138:139], v[188:189]
	v_pk_fma_f32 v[186:187], v[90:91], v[42:43], v[186:187]
	v_pk_fma_f32 v[190:191], v[90:91], v[138:139], v[190:191]
	s_waitcnt lgkmcnt(8)
	v_pk_fma_f32 v[184:185], v[76:77], v[44:45], v[184:185]
	v_pk_fma_f32 v[188:189], v[76:77], v[140:141], v[188:189]
	v_pk_fma_f32 v[186:187], v[92:93], v[44:45], v[186:187]
	v_pk_fma_f32 v[190:191], v[92:93], v[140:141], v[190:191]
	v_pk_fma_f32 v[184:185], v[78:79], v[46:47], v[184:185]
	v_pk_fma_f32 v[188:189], v[78:79], v[142:143], v[188:189]
	v_pk_fma_f32 v[186:187], v[94:95], v[46:47], v[186:187]
	v_pk_fma_f32 v[190:191], v[94:95], v[142:143], v[190:191]
	s_waitcnt lgkmcnt(6)
	v_pk_fma_f32 v[184:185], v[96:97], v[48:49], v[184:185]
	v_pk_fma_f32 v[188:189], v[96:97], v[144:145], v[188:189]
	v_pk_fma_f32 v[186:187], v[112:113], v[48:49], v[186:187]
	v_pk_fma_f32 v[190:191], v[112:113], v[144:145], v[190:191]
	v_pk_fma_f32 v[184:185], v[98:99], v[50:51], v[184:185]
	v_pk_fma_f32 v[188:189], v[98:99], v[146:147], v[188:189]
	v_pk_fma_f32 v[186:187], v[114:115], v[50:51], v[186:187]
	v_pk_fma_f32 v[190:191], v[114:115], v[146:147], v[190:191]
	s_waitcnt lgkmcnt(4)
	v_pk_fma_f32 v[184:185], v[100:101], v[52:53], v[184:185]
	v_pk_fma_f32 v[188:189], v[100:101], v[148:149], v[188:189]
	v_pk_fma_f32 v[186:187], v[116:117], v[52:53], v[186:187]
	v_pk_fma_f32 v[190:191], v[116:117], v[148:149], v[190:191]
	v_pk_fma_f32 v[184:185], v[102:103], v[54:55], v[184:185]
	v_pk_fma_f32 v[188:189], v[102:103], v[150:151], v[188:189]
	v_pk_fma_f32 v[186:187], v[118:119], v[54:55], v[186:187]
	v_pk_fma_f32 v[190:191], v[118:119], v[150:151], v[190:191]
	s_waitcnt lgkmcnt(2)
	v_pk_fma_f32 v[184:185], v[104:105], v[56:57], v[184:185]
	v_pk_fma_f32 v[188:189], v[104:105], v[152:153], v[188:189]
	v_pk_fma_f32 v[186:187], v[120:121], v[56:57], v[186:187]
	v_pk_fma_f32 v[190:191], v[120:121], v[152:153], v[190:191]
	v_pk_fma_f32 v[184:185], v[106:107], v[58:59], v[184:185]
	v_pk_fma_f32 v[188:189], v[106:107], v[154:155], v[188:189]
	v_pk_fma_f32 v[186:187], v[122:123], v[58:59], v[186:187]
	v_pk_fma_f32 v[190:191], v[122:123], v[154:155], v[190:191]
	s_waitcnt lgkmcnt(0)
	v_pk_fma_f32 v[184:185], v[108:109], v[60:61], v[184:185]
	v_pk_fma_f32 v[188:189], v[108:109], v[156:157], v[188:189]
	v_pk_fma_f32 v[186:187], v[124:125], v[60:61], v[186:187]
	v_pk_fma_f32 v[190:191], v[124:125], v[156:157], v[190:191]
	v_pk_fma_f32 v[184:185], v[110:111], v[62:63], v[184:185]
	v_pk_fma_f32 v[188:189], v[110:111], v[158:159], v[188:189]
	v_pk_fma_f32 v[186:187], v[126:127], v[62:63], v[186:187]
	v_pk_fma_f32 v[190:191], v[126:127], v[158:159], v[190:191]
	v_add_f32_e32 v18, v184, v185
	v_add_f32_e32 v200, v186, v187
	s_nop 1
	v_permlane32_swap_b32 v18, v200
	s_nop 0
	v_add_f32_e32 v18, v18, v200
	v_add_f32_e32 v201, v188, v189
	v_add_f32_e32 v202, v190, v191
	s_nop 1
	v_permlane32_swap_b32 v201, v202
	s_nop 0
	v_add_f32_e32 v201, v201, v202
	v_mul_f32_e32 v203, v201, v201
	v_mov_b32_e32 v204, v201
	s_nop 1
	v_permlane32_swap_b32 v204, v203
	s_nop 0
	v_add_f32_e32 v204, v204, v203
	s_nop 1
	v_add_f32_dpp v204, v204, v204 quad_perm:[1,0,3,2] row_mask:0xf bank_mask:0xf
	s_nop 1
	v_add_f32_dpp v204, v204, v204 quad_perm:[2,3,0,1] row_mask:0xf bank_mask:0xf
	s_nop 1
	v_add_f32_dpp v204, v204, v204 row_half_mirror row_mask:0xf bank_mask:0xf
	s_nop 1
	v_add_f32_dpp v204, v204, v204 row_mirror row_mask:0xf bank_mask:0xf
	s_nop 1
	v_add_f32_dpp v204, v204, v204 row_bcast:15 row_mask:0xa bank_mask:0xf
	s_nop 1
	v_readlane_b32 s34, v204, 31
	v_readlane_b32 s35, v204, 63
	s_nop 1
	v_mul_f32_e32 v205, s34, v207
	v_mul_f32_e32 v206, s35, v207
	v_fma_f32 v206, -v205, v205, v206
	v_max_f32_e32 v206, 0, v206
	v_add_f32_e32 v206, 0x3a27c5ac, v206
	v_rsq_f32_e32 v206, v206
	v_sub_f32_e32 v205, v201, v205
	v_mul_f32_e32 v205, v205, v206
	v_fma_f32 v205, v205, v14, v15
	v_fma_f32 v205, s31, v21, v205
	v_mul_f32_e32 v205, v205, v23
	v_bfe_u32 v206, v205, 16, 1
	v_add3_u32 v205, v205, v206, s36
	global_store_short_d16_hi v5, v205, s[14:15]
	v_add_u32_e32 v5, 0x400, v5
	s_add_u32 s18, s18, 4
	s_cmp_lt_u32 s18, 128
	s_cbranch_scc1 .Lrwp2b_loop
	s_waitcnt vmcnt(0)
	s_add_u32 s16, s16, s17
	s_cmpk_lt_i32 s16, 0x800
	s_cbranch_scc1 .Lrwp2b_item
